# closing s_barrier of each MFMA segment issued 4 MFMAs early, tail at prio 2, all GEMM loops
# speedup vs baseline: 1.0041x; 1.0041x over previous
.LBB0_308:
	ds_read_b128 v[142:145], v191
	ds_read_b128 v[138:141], v191 offset:1024
	ds_read_b128 v[134:137], v191 offset:2048
	ds_read_b128 v[130:133], v191 offset:3072
	s_add_u32 s46, s44, 0xfff80080
	s_addc_u32 s47, s45, -1
	s_cmp_eq_u32 s37, 28
	s_cselect_b32 s49, s0, s47
	s_cselect_b32 s48, s1, s46
	s_cselect_b32 s47, s7, s31
	s_cselect_b32 s46, s14, s15
	v_lshl_add_u64 v[166:167], s[44:45], 0, v[162:163]
	s_add_i32 m0, s9, 0xc000
	ds_read_b128 v[170:173], v192
	ds_read_b128 v[174:177], v192 offset:1024
	s_waitcnt lgkmcnt(0)
	ds_read_b128 v[178:181], v192 offset:2048
	ds_read_b128 v[182:185], v192 offset:3072
	ds_read_b128 v[204:207], v192 offset:4096
	ds_read_b128 v[208:211], v192 offset:5120
	ds_read_b128 v[212:215], v192 offset:6144
	ds_read_b128 v[216:219], v192 offset:7168
	global_load_lds_dwordx4 v[166:167], off
	v_lshl_add_u64 v[166:167], s[44:45], 0, v[164:165]
	s_add_i32 m0, s9, 0xe000
	s_nop 0
	global_load_lds_dwordx4 v[166:167], off
	s_waitcnt lgkmcnt(8)
	s_barrier
	s_waitcnt lgkmcnt(0)
	s_setprio 1
	s_waitcnt lgkmcnt(0)
	v_mfma_i32_16x16x64_i8 v[126:129], v[142:145], v[170:173], v[126:129]
	s_nop 0
	v_mfma_i32_16x16x64_i8 v[126:129], v[138:141], v[174:177], v[126:129]
	v_mfma_i32_16x16x64_i8 v[122:125], v[134:137], v[170:173], v[122:125]
	s_nop 0
	v_mfma_i32_16x16x64_i8 v[122:125], v[130:133], v[174:177], v[122:125]
	v_mfma_i32_16x16x64_i8 v[110:113], v[142:145], v[178:181], v[110:113]
	s_nop 0
	v_mfma_i32_16x16x64_i8 v[110:113], v[138:141], v[182:185], v[110:113]
	v_mfma_i32_16x16x64_i8 v[106:109], v[134:137], v[178:181], v[106:109]
	s_nop 0
	v_mfma_i32_16x16x64_i8 v[106:109], v[130:133], v[182:185], v[106:109]
	v_mfma_i32_16x16x64_i8 v[94:97], v[142:145], v[204:207], v[94:97]
	s_nop 0
	v_mfma_i32_16x16x64_i8 v[94:97], v[138:141], v[208:211], v[94:97]
	v_mfma_i32_16x16x64_i8 v[90:93], v[134:137], v[204:207], v[90:93]
	s_nop 0
	v_mfma_i32_16x16x64_i8 v[90:93], v[130:133], v[208:211], v[90:93]
	s_barrier
	s_setprio 2
	v_mfma_i32_16x16x64_i8 v[78:81], v[142:145], v[212:215], v[78:81]
	s_nop 0
	v_mfma_i32_16x16x64_i8 v[78:81], v[138:141], v[216:219], v[78:81]
	v_mfma_i32_16x16x64_i8 v[74:77], v[134:137], v[212:215], v[74:77]
	s_nop 0
	v_mfma_i32_16x16x64_i8 v[74:77], v[130:133], v[216:219], v[74:77]
	s_setprio 0
	s_add_i32 s50, s55, s8
	v_lshl_add_u64 v[166:167], s[46:47], 0, v[148:149]
	s_mov_b32 m0, s50
	ds_read_b128 v[220:223], v193
	ds_read_b128 v[224:227], v193 offset:1024
	ds_read_b128 v[234:237], v193 offset:2048
	ds_read_b128 v[238:241], v193 offset:3072
	global_load_lds_dwordx4 v[166:167], off
	v_lshl_add_u64 v[168:169], s[46:47], 0, v[152:153]
	s_add_i32 m0, s50, 0x2000
	s_nop 0
	global_load_lds_dwordx4 v[168:169], off
	s_barrier
	s_waitcnt lgkmcnt(0)
	s_setprio 1
	s_waitcnt lgkmcnt(0)
	v_mfma_i32_16x16x64_i8 v[118:121], v[220:223], v[170:173], v[118:121]
	s_nop 0
	v_mfma_i32_16x16x64_i8 v[118:121], v[224:227], v[174:177], v[118:121]
	v_mfma_i32_16x16x64_i8 v[114:117], v[234:237], v[170:173], v[114:117]
	s_nop 0
	v_mfma_i32_16x16x64_i8 v[114:117], v[238:241], v[174:177], v[114:117]
	v_mfma_i32_16x16x64_i8 v[102:105], v[220:223], v[178:181], v[102:105]
	s_nop 0
	v_mfma_i32_16x16x64_i8 v[102:105], v[224:227], v[182:185], v[102:105]
	v_mfma_i32_16x16x64_i8 v[98:101], v[234:237], v[178:181], v[98:101]
	s_nop 0
	v_mfma_i32_16x16x64_i8 v[98:101], v[238:241], v[182:185], v[98:101]
	v_mfma_i32_16x16x64_i8 v[86:89], v[220:223], v[204:207], v[86:89]
	s_nop 0
	v_mfma_i32_16x16x64_i8 v[86:89], v[224:227], v[208:211], v[86:89]
	v_mfma_i32_16x16x64_i8 v[82:85], v[234:237], v[204:207], v[82:85]
	s_nop 0
	v_mfma_i32_16x16x64_i8 v[82:85], v[238:241], v[208:211], v[82:85]
	s_barrier
	s_setprio 2
	v_mfma_i32_16x16x64_i8 v[70:73], v[220:223], v[212:215], v[70:73]
	s_nop 0
	v_mfma_i32_16x16x64_i8 v[70:73], v[224:227], v[216:219], v[70:73]
	v_mfma_i32_16x16x64_i8 v[66:69], v[234:237], v[212:215], v[66:69]
	s_nop 0
	v_mfma_i32_16x16x64_i8 v[66:69], v[238:241], v[216:219], v[66:69]
	s_setprio 0
	s_mov_b32 m0, s9
	v_lshl_add_u64 v[170:171], s[48:49], 0, v[146:147]
	ds_read_b128 v[174:177], v192 offset:16384
	ds_read_b128 v[178:181], v192 offset:17408
	ds_read_b128 v[182:185], v192 offset:18432
	ds_read_b128 v[204:207], v192 offset:19456
	ds_read_b128 v[208:211], v192 offset:20480
	ds_read_b128 v[212:215], v192 offset:21504
	ds_read_b128 v[216:219], v192 offset:22528
	ds_read_b128 v[242:245], v192 offset:23552
	global_load_lds_dwordx4 v[170:171], off
	v_lshl_add_u64 v[172:173], s[48:49], 0, v[150:151]
	s_mov_b32 m0, s13
	s_nop 0
	global_load_lds_dwordx4 v[172:173], off
	s_barrier
	s_waitcnt lgkmcnt(0)
	s_setprio 1
	s_waitcnt lgkmcnt(0)
	v_mfma_i32_16x16x64_i8 v[62:65], v[142:145], v[174:177], v[62:65]
	s_nop 0
	v_mfma_i32_16x16x64_i8 v[62:65], v[138:141], v[178:181], v[62:65]
	v_mfma_i32_16x16x64_i8 v[58:61], v[134:137], v[174:177], v[58:61]
	s_nop 0
	v_mfma_i32_16x16x64_i8 v[58:61], v[130:133], v[178:181], v[58:61]
	v_mfma_i32_16x16x64_i8 v[46:49], v[142:145], v[182:185], v[46:49]
	s_nop 0
	v_mfma_i32_16x16x64_i8 v[46:49], v[138:141], v[204:207], v[46:49]
	v_mfma_i32_16x16x64_i8 v[42:45], v[134:137], v[182:185], v[42:45]
	s_nop 0
	v_mfma_i32_16x16x64_i8 v[42:45], v[130:133], v[204:207], v[42:45]
	v_mfma_i32_16x16x64_i8 v[30:33], v[142:145], v[208:211], v[30:33]
	s_nop 0
	v_mfma_i32_16x16x64_i8 v[30:33], v[138:141], v[212:215], v[30:33]
	v_mfma_i32_16x16x64_i8 v[26:29], v[134:137], v[208:211], v[26:29]
	s_nop 0
	v_mfma_i32_16x16x64_i8 v[26:29], v[130:133], v[212:215], v[26:29]
	s_barrier
	s_setprio 2
	v_mfma_i32_16x16x64_i8 v[14:17], v[142:145], v[216:219], v[14:17]
	s_nop 0
	v_mfma_i32_16x16x64_i8 v[14:17], v[138:141], v[242:245], v[14:17]
	v_mfma_i32_16x16x64_i8 v[10:13], v[134:137], v[216:219], v[10:13]
	s_nop 0
	v_mfma_i32_16x16x64_i8 v[10:13], v[130:133], v[242:245], v[10:13]
	s_setprio 0
	s_add_u32 s50, s46, 0x80000
	s_addc_u32 s51, s47, 0
	s_add_i32 s59, s56, s8
	v_lshl_add_u64 v[130:131], s[50:51], 0, v[148:149]
	s_mov_b32 m0, s59
	s_nop 0
	global_load_lds_dwordx4 v[130:131], off
	v_lshl_add_u64 v[130:131], s[50:51], 0, v[152:153]
	s_add_i32 m0, s59, 0x2000
	s_nop 0
	global_load_lds_dwordx4 v[130:131], off
	s_waitcnt vmcnt(6)
	s_barrier
	s_setprio 1
	v_mfma_i32_16x16x64_i8 v[54:57], v[220:223], v[174:177], v[54:57]
	s_nop 0
	v_mfma_i32_16x16x64_i8 v[54:57], v[224:227], v[178:181], v[54:57]
	v_mfma_i32_16x16x64_i8 v[50:53], v[234:237], v[174:177], v[50:53]
	s_nop 0
	v_mfma_i32_16x16x64_i8 v[50:53], v[238:241], v[178:181], v[50:53]
	v_mfma_i32_16x16x64_i8 v[38:41], v[220:223], v[182:185], v[38:41]
	s_nop 0
	v_mfma_i32_16x16x64_i8 v[38:41], v[224:227], v[204:207], v[38:41]
	v_mfma_i32_16x16x64_i8 v[34:37], v[234:237], v[182:185], v[34:37]
	s_nop 0
	v_mfma_i32_16x16x64_i8 v[34:37], v[238:241], v[204:207], v[34:37]
	v_mfma_i32_16x16x64_i8 v[22:25], v[220:223], v[208:211], v[22:25]
	s_nop 0
	v_mfma_i32_16x16x64_i8 v[22:25], v[224:227], v[212:215], v[22:25]
	v_mfma_i32_16x16x64_i8 v[18:21], v[234:237], v[208:211], v[18:21]
	s_nop 0
	v_mfma_i32_16x16x64_i8 v[18:21], v[238:241], v[212:215], v[18:21]
	s_barrier
	s_setprio 2
	v_mfma_i32_16x16x64_i8 v[6:9], v[220:223], v[216:219], v[6:9]
	s_nop 0
	v_mfma_i32_16x16x64_i8 v[6:9], v[224:227], v[242:245], v[6:9]
	v_mfma_i32_16x16x64_i8 v[2:5], v[234:237], v[216:219], v[2:5]
	s_nop 0
	v_mfma_i32_16x16x64_i8 v[2:5], v[238:241], v[242:245], v[2:5]
	s_setprio 0
	s_add_i32 s50, 0, 0x18000
	v_add_u32_e32 v142, s50, v188
	ds_read_b128 v[130:133], v142
	ds_read_b128 v[134:137], v142 offset:1024
	ds_read_b128 v[138:141], v142 offset:2048
	ds_read_b128 v[142:145], v142 offset:3072
	s_add_u32 s48, s48, 0x80000
	s_addc_u32 s49, s49, 0
	s_mov_b32 m0, s29
	v_lshl_add_u64 v[186:187], s[48:49], 0, v[146:147]
	ds_read_b128 v[174:177], v192 offset:32768
	ds_read_b128 v[178:181], v192 offset:33792
	ds_read_b128 v[182:185], v192 offset:34816
	ds_read_b128 v[204:207], v192 offset:35840
	ds_read_b128 v[208:211], v192 offset:36864
	ds_read_b128 v[212:215], v192 offset:37888
	ds_read_b128 v[216:219], v192 offset:38912
	ds_read_b128 v[220:223], v192 offset:39936
	global_load_lds_dwordx4 v[186:187], off
	v_lshl_add_u64 v[186:187], s[48:49], 0, v[150:151]
	s_mov_b32 m0, s33
	s_nop 0
	global_load_lds_dwordx4 v[186:187], off
	s_waitcnt lgkmcnt(8)
	s_barrier
	s_waitcnt lgkmcnt(0)
	s_setprio 1
	s_waitcnt lgkmcnt(0)
	v_mfma_i32_16x16x64_i8 v[126:129], v[130:133], v[174:177], v[126:129]
	s_nop 0
	v_mfma_i32_16x16x64_i8 v[126:129], v[134:137], v[178:181], v[126:129]
	v_mfma_i32_16x16x64_i8 v[122:125], v[138:141], v[174:177], v[122:125]
	s_nop 0
	v_mfma_i32_16x16x64_i8 v[122:125], v[142:145], v[178:181], v[122:125]
	v_mfma_i32_16x16x64_i8 v[110:113], v[130:133], v[182:185], v[110:113]
	s_nop 0
	v_mfma_i32_16x16x64_i8 v[110:113], v[134:137], v[204:207], v[110:113]
	v_mfma_i32_16x16x64_i8 v[106:109], v[138:141], v[182:185], v[106:109]
	s_nop 0
	v_mfma_i32_16x16x64_i8 v[106:109], v[142:145], v[204:207], v[106:109]
	v_mfma_i32_16x16x64_i8 v[94:97], v[130:133], v[208:211], v[94:97]
	s_nop 0
	v_mfma_i32_16x16x64_i8 v[94:97], v[134:137], v[212:215], v[94:97]
	v_mfma_i32_16x16x64_i8 v[90:93], v[138:141], v[208:211], v[90:93]
	s_nop 0
	v_mfma_i32_16x16x64_i8 v[90:93], v[142:145], v[212:215], v[90:93]
	s_barrier
	s_setprio 2
	v_mfma_i32_16x16x64_i8 v[78:81], v[130:133], v[216:219], v[78:81]
	s_nop 0
	v_mfma_i32_16x16x64_i8 v[78:81], v[134:137], v[220:223], v[78:81]
	v_mfma_i32_16x16x64_i8 v[74:77], v[138:141], v[216:219], v[74:77]
	s_nop 0
	v_mfma_i32_16x16x64_i8 v[74:77], v[142:145], v[220:223], v[74:77]
	s_setprio 0
	s_add_i32 s48, 0, 0x1c000
	s_add_i32 s49, s50, s8
	v_add_u32_e32 v156, s48, v188
	v_lshl_add_u64 v[166:167], v[166:167], 0, s[22:23]
	s_mov_b32 m0, s49
	ds_read_b128 v[224:227], v156
	ds_read_b128 v[234:237], v156 offset:1024
	ds_read_b128 v[238:241], v156 offset:2048
	ds_read_b128 v[242:245], v156 offset:3072
	global_load_lds_dwordx4 v[166:167], off
	v_lshl_add_u64 v[166:167], v[168:169], 0, s[22:23]
	s_add_i32 m0, s49, 0x2000
	s_nop 0
	global_load_lds_dwordx4 v[166:167], off
	s_barrier
	s_waitcnt lgkmcnt(0)
	s_setprio 1
	s_waitcnt lgkmcnt(0)
	v_mfma_i32_16x16x64_i8 v[118:121], v[224:227], v[174:177], v[118:121]
	s_nop 0
	v_mfma_i32_16x16x64_i8 v[118:121], v[234:237], v[178:181], v[118:121]
	v_mfma_i32_16x16x64_i8 v[114:117], v[238:241], v[174:177], v[114:117]
	s_nop 0
	v_mfma_i32_16x16x64_i8 v[114:117], v[242:245], v[178:181], v[114:117]
	v_mfma_i32_16x16x64_i8 v[102:105], v[224:227], v[182:185], v[102:105]
	s_nop 0
	v_mfma_i32_16x16x64_i8 v[102:105], v[234:237], v[204:207], v[102:105]
	v_mfma_i32_16x16x64_i8 v[98:101], v[238:241], v[182:185], v[98:101]
	s_nop 0
	v_mfma_i32_16x16x64_i8 v[98:101], v[242:245], v[204:207], v[98:101]
	v_mfma_i32_16x16x64_i8 v[86:89], v[224:227], v[208:211], v[86:89]
	s_nop 0
	v_mfma_i32_16x16x64_i8 v[86:89], v[234:237], v[212:215], v[86:89]
	v_mfma_i32_16x16x64_i8 v[82:85], v[238:241], v[208:211], v[82:85]
	s_nop 0
	v_mfma_i32_16x16x64_i8 v[82:85], v[242:245], v[212:215], v[82:85]
	s_barrier
	s_setprio 2
	v_mfma_i32_16x16x64_i8 v[70:73], v[224:227], v[216:219], v[70:73]
	s_nop 0
	v_mfma_i32_16x16x64_i8 v[70:73], v[234:237], v[220:223], v[70:73]
	v_mfma_i32_16x16x64_i8 v[66:69], v[238:241], v[216:219], v[66:69]
	s_nop 0
	v_mfma_i32_16x16x64_i8 v[66:69], v[242:245], v[220:223], v[66:69]
	s_setprio 0
	s_mov_b32 m0, s53
	v_lshl_add_u64 v[170:171], v[170:171], 0, s[22:23]
	ds_read_b128 v[166:169], v192 offset:49152
	ds_read_b128 v[174:177], v192 offset:50176
	ds_read_b128 v[178:181], v192 offset:51200
	ds_read_b128 v[182:185], v192 offset:52224
	ds_read_b128 v[204:207], v192 offset:53248
	ds_read_b128 v[208:211], v192 offset:54272
	ds_read_b128 v[212:215], v192 offset:55296
	ds_read_b128 v[216:219], v192 offset:56320
	global_load_lds_dwordx4 v[170:171], off
	v_lshl_add_u64 v[170:171], v[172:173], 0, s[22:23]
	s_mov_b32 m0, s54
	s_nop 0
	global_load_lds_dwordx4 v[170:171], off
	s_barrier
	s_waitcnt lgkmcnt(0)
	s_setprio 1
	s_waitcnt lgkmcnt(0)
	v_mfma_i32_16x16x64_i8 v[62:65], v[130:133], v[166:169], v[62:65]
	s_nop 0
	v_mfma_i32_16x16x64_i8 v[62:65], v[134:137], v[174:177], v[62:65]
	v_mfma_i32_16x16x64_i8 v[58:61], v[138:141], v[166:169], v[58:61]
	s_nop 0
	v_mfma_i32_16x16x64_i8 v[58:61], v[142:145], v[174:177], v[58:61]
	v_mfma_i32_16x16x64_i8 v[46:49], v[130:133], v[178:181], v[46:49]
	s_nop 0
	v_mfma_i32_16x16x64_i8 v[46:49], v[134:137], v[182:185], v[46:49]
	v_mfma_i32_16x16x64_i8 v[42:45], v[138:141], v[178:181], v[42:45]
	s_nop 0
	v_mfma_i32_16x16x64_i8 v[42:45], v[142:145], v[182:185], v[42:45]
	v_mfma_i32_16x16x64_i8 v[30:33], v[130:133], v[204:207], v[30:33]
	s_nop 0
	v_mfma_i32_16x16x64_i8 v[30:33], v[134:137], v[208:211], v[30:33]
	v_mfma_i32_16x16x64_i8 v[26:29], v[138:141], v[204:207], v[26:29]
	s_nop 0
	v_mfma_i32_16x16x64_i8 v[26:29], v[142:145], v[208:211], v[26:29]
	s_barrier
	s_setprio 2
	v_mfma_i32_16x16x64_i8 v[14:17], v[130:133], v[212:215], v[14:17]
	s_nop 0
	v_mfma_i32_16x16x64_i8 v[14:17], v[134:137], v[216:219], v[14:17]
	v_mfma_i32_16x16x64_i8 v[10:13], v[138:141], v[212:215], v[10:13]
	s_nop 0
	v_mfma_i32_16x16x64_i8 v[10:13], v[142:145], v[216:219], v[10:13]
	s_setprio 0
	s_add_u32 s46, s46, 0x80080
	s_addc_u32 s47, s47, 0
	s_add_i32 s48, s48, s8
	v_lshl_add_u64 v[130:131], s[46:47], 0, v[148:149]
	s_mov_b32 m0, s48
	s_nop 0
	global_load_lds_dwordx4 v[130:131], off
	v_lshl_add_u64 v[130:131], s[46:47], 0, v[152:153]
	s_add_i32 m0, s48, 0x2000
	s_nop 0
	global_load_lds_dwordx4 v[130:131], off
	s_waitcnt vmcnt(6)
	s_barrier
	s_setprio 1
	v_mfma_i32_16x16x64_i8 v[54:57], v[224:227], v[166:169], v[54:57]
	s_nop 0
	v_mfma_i32_16x16x64_i8 v[54:57], v[234:237], v[174:177], v[54:57]
	v_mfma_i32_16x16x64_i8 v[50:53], v[238:241], v[166:169], v[50:53]
	s_nop 0
	v_mfma_i32_16x16x64_i8 v[50:53], v[242:245], v[174:177], v[50:53]
	v_mfma_i32_16x16x64_i8 v[38:41], v[224:227], v[178:181], v[38:41]
	s_nop 0
	v_mfma_i32_16x16x64_i8 v[38:41], v[234:237], v[182:185], v[38:41]
	v_mfma_i32_16x16x64_i8 v[34:37], v[238:241], v[178:181], v[34:37]
	s_nop 0
	v_mfma_i32_16x16x64_i8 v[34:37], v[242:245], v[182:185], v[34:37]
	v_mfma_i32_16x16x64_i8 v[22:25], v[224:227], v[204:207], v[22:25]
	s_nop 0
	v_mfma_i32_16x16x64_i8 v[22:25], v[234:237], v[208:211], v[22:25]
	v_mfma_i32_16x16x64_i8 v[18:21], v[238:241], v[204:207], v[18:21]
	s_nop 0
	v_mfma_i32_16x16x64_i8 v[18:21], v[242:245], v[208:211], v[18:21]
	s_barrier
	s_setprio 2
	v_mfma_i32_16x16x64_i8 v[6:9], v[224:227], v[212:215], v[6:9]
	s_nop 0
	v_mfma_i32_16x16x64_i8 v[6:9], v[234:237], v[216:219], v[6:9]
	v_mfma_i32_16x16x64_i8 v[2:5], v[238:241], v[212:215], v[2:5]
	s_nop 0
	v_mfma_i32_16x16x64_i8 v[2:5], v[242:245], v[216:219], v[2:5]
	s_setprio 0
	s_add_i32 s37, s37, 2
	s_add_u32 s44, s44, 0x100
	s_addc_u32 s45, s45, 0
	s_add_u32 s15, s15, 0x100
	s_addc_u32 s31, s31, 0
	s_cmp_gt_u32 s37, 29
	s_cbranch_scc0 .LBB0_308
	s_nop 15
	s_nop 15
	s_and_b64 vcc, exec, s[24:25]
	s_cbranch_vccz .LBB0_311
	s_barrier

.LBB0_412:
	ds_read_b128 v[130:133], v191
	ds_read_b128 v[134:137], v191 offset:1024
	ds_read_b128 v[138:141], v191 offset:2048
	ds_read_b128 v[142:145], v191 offset:3072
	ds_read_b128 v[146:149], v192
	ds_read_b128 v[150:153], v192 offset:1024
	ds_read_b128 v[174:177], v192 offset:2048
	s_waitcnt lgkmcnt(0)
	ds_read_b128 v[178:181], v192 offset:3072
	s_add_u32 s42, s40, 0xfff00080
	s_addc_u32 s43, s41, -1
	s_cmp_eq_u32 s29, 60
	s_cselect_b32 s45, s0, s43
	s_cselect_b32 s44, s1, s42
	s_cselect_b32 s43, s7, s27
	s_cselect_b32 s42, s14, s15
	v_lshl_add_u64 v[186:187], s[40:41], 0, v[170:171]
	s_add_i32 m0, s9, 0xc000
	ds_read_b128 v[182:185], v193
	ds_read_b128 v[204:207], v193 offset:1024
	ds_read_b128 v[208:211], v193 offset:2048
	ds_read_b128 v[212:215], v193 offset:3072
	ds_read_b128 v[216:219], v193 offset:4096
	ds_read_b128 v[220:223], v193 offset:5120
	ds_read_b128 v[224:227], v193 offset:6144
	ds_read_b128 v[234:237], v193 offset:7168
	global_load_lds_dwordx4 v[186:187], off
	v_lshl_add_u64 v[186:187], s[40:41], 0, v[172:173]
	s_add_i32 m0, s9, 0xe000
	s_nop 0
	global_load_lds_dwordx4 v[186:187], off
	s_waitcnt vmcnt(8)
	s_waitcnt lgkmcnt(0)
	s_barrier
	s_setprio 1
	s_waitcnt lgkmcnt(0)
	v_mfma_f32_16x16x32_bf16 v[126:129], v[130:133], v[182:185], v[126:129]
	v_mfma_f32_16x16x32_bf16 v[122:125], v[138:141], v[182:185], v[122:125]
	v_mfma_f32_16x16x32_bf16 v[118:121], v[130:133], v[208:211], v[118:121]
	v_mfma_f32_16x16x32_bf16 v[110:113], v[138:141], v[208:211], v[110:113]
	v_mfma_f32_16x16x32_bf16 v[102:105], v[130:133], v[216:219], v[102:105]
	v_mfma_f32_16x16x32_bf16 v[94:97], v[138:141], v[216:219], v[94:97]
	v_mfma_f32_16x16x32_bf16 v[86:89], v[130:133], v[224:227], v[86:89]
	v_mfma_f32_16x16x32_bf16 v[78:81], v[138:141], v[224:227], v[78:81]
	v_mfma_f32_16x16x32_bf16 v[126:129], v[134:137], v[204:207], v[126:129]
	v_mfma_f32_16x16x32_bf16 v[122:125], v[142:145], v[204:207], v[122:125]
	v_mfma_f32_16x16x32_bf16 v[118:121], v[134:137], v[212:215], v[118:121]
	v_mfma_f32_16x16x32_bf16 v[110:113], v[142:145], v[212:215], v[110:113]
	v_mfma_f32_16x16x32_bf16 v[102:105], v[134:137], v[220:223], v[102:105]
	v_mfma_f32_16x16x32_bf16 v[94:97], v[142:145], v[220:223], v[94:97]
	v_mfma_f32_16x16x32_bf16 v[86:89], v[134:137], v[234:237], v[86:89]
	v_mfma_f32_16x16x32_bf16 v[78:81], v[142:145], v[234:237], v[78:81]
	s_setprio 0
	s_setprio 1
	v_mfma_f32_16x16x32_bf16 v[114:117], v[146:149], v[182:185], v[114:117]
	v_mfma_f32_16x16x32_bf16 v[106:109], v[174:177], v[182:185], v[106:109]
	v_mfma_f32_16x16x32_bf16 v[98:101], v[146:149], v[208:211], v[98:101]
	v_mfma_f32_16x16x32_bf16 v[90:93], v[174:177], v[208:211], v[90:93]
	v_mfma_f32_16x16x32_bf16 v[82:85], v[146:149], v[216:219], v[82:85]
	v_mfma_f32_16x16x32_bf16 v[74:77], v[174:177], v[216:219], v[74:77]
	v_mfma_f32_16x16x32_bf16 v[70:73], v[146:149], v[224:227], v[70:73]
	v_mfma_f32_16x16x32_bf16 v[66:69], v[174:177], v[224:227], v[66:69]
	v_mfma_f32_16x16x32_bf16 v[114:117], v[150:153], v[204:207], v[114:117]
	v_mfma_f32_16x16x32_bf16 v[106:109], v[178:181], v[204:207], v[106:109]
	v_mfma_f32_16x16x32_bf16 v[98:101], v[150:153], v[212:215], v[98:101]
	v_mfma_f32_16x16x32_bf16 v[90:93], v[178:181], v[212:215], v[90:93]
	s_barrier
	s_setprio 2
	v_mfma_f32_16x16x32_bf16 v[82:85], v[150:153], v[220:223], v[82:85]
	v_mfma_f32_16x16x32_bf16 v[74:77], v[178:181], v[220:223], v[74:77]
	v_mfma_f32_16x16x32_bf16 v[70:73], v[150:153], v[234:237], v[70:73]
	v_mfma_f32_16x16x32_bf16 v[66:69], v[178:181], v[234:237], v[66:69]
	s_setprio 0
	s_add_i32 s46, s52, s8
	v_lshl_add_u64 v[186:187], s[42:43], 0, v[158:159]
	s_mov_b32 m0, s46
	ds_read_b128 v[182:185], v193 offset:16384
	ds_read_b128 v[204:207], v193 offset:17408
	ds_read_b128 v[208:211], v193 offset:18432
	ds_read_b128 v[212:215], v193 offset:19456
	ds_read_b128 v[216:219], v193 offset:20480
	ds_read_b128 v[220:223], v193 offset:21504
	ds_read_b128 v[224:227], v193 offset:22528
	ds_read_b128 v[234:237], v193 offset:23552
	global_load_lds_dwordx4 v[186:187], off
	s_add_i32 m0, s46, 0x2000
	s_add_u32 s46, s42, 0x100000
	v_lshl_add_u64 v[194:195], s[42:43], 0, v[162:163]
	s_addc_u32 s47, s43, 0
	s_add_i32 s56, s53, s8
	global_load_lds_dwordx4 v[194:195], off
	v_lshl_add_u64 v[200:201], s[46:47], 0, v[158:159]
	s_mov_b32 m0, s56
	v_lshl_add_u64 v[238:239], s[44:45], 0, v[160:161]
	global_load_lds_dwordx4 v[200:201], off
	v_lshl_add_u64 v[200:201], s[46:47], 0, v[162:163]
	s_add_i32 m0, s56, 0x2000
	s_nop 0
	global_load_lds_dwordx4 v[200:201], off
	v_lshl_add_u64 v[200:201], s[44:45], 0, v[156:157]
	s_mov_b32 m0, s9
	s_nop 0
	global_load_lds_dwordx4 v[200:201], off
	s_mov_b32 m0, s13
	s_nop 0
	global_load_lds_dwordx4 v[238:239], off
	s_waitcnt vmcnt(8)
	s_waitcnt lgkmcnt(0)
	s_barrier
	s_setprio 1
	s_waitcnt lgkmcnt(0)
	v_mfma_f32_16x16x32_bf16 v[62:65], v[130:133], v[182:185], v[62:65]
	v_mfma_f32_16x16x32_bf16 v[58:61], v[138:141], v[182:185], v[58:61]
	v_mfma_f32_16x16x32_bf16 v[54:57], v[130:133], v[208:211], v[54:57]
	v_mfma_f32_16x16x32_bf16 v[46:49], v[138:141], v[208:211], v[46:49]
	v_mfma_f32_16x16x32_bf16 v[38:41], v[130:133], v[216:219], v[38:41]
	v_mfma_f32_16x16x32_bf16 v[30:33], v[138:141], v[216:219], v[30:33]
	v_mfma_f32_16x16x32_bf16 v[22:25], v[130:133], v[224:227], v[22:25]
	v_mfma_f32_16x16x32_bf16 v[14:17], v[138:141], v[224:227], v[14:17]
	v_mfma_f32_16x16x32_bf16 v[62:65], v[134:137], v[204:207], v[62:65]
	v_mfma_f32_16x16x32_bf16 v[58:61], v[142:145], v[204:207], v[58:61]
	v_mfma_f32_16x16x32_bf16 v[54:57], v[134:137], v[212:215], v[54:57]
	v_mfma_f32_16x16x32_bf16 v[46:49], v[142:145], v[212:215], v[46:49]
	v_mfma_f32_16x16x32_bf16 v[38:41], v[134:137], v[220:223], v[38:41]
	v_mfma_f32_16x16x32_bf16 v[30:33], v[142:145], v[220:223], v[30:33]
	v_mfma_f32_16x16x32_bf16 v[22:25], v[134:137], v[234:237], v[22:25]
	v_mfma_f32_16x16x32_bf16 v[14:17], v[142:145], v[234:237], v[14:17]
	s_setprio 0
	s_setprio 1
	v_mfma_f32_16x16x32_bf16 v[50:53], v[146:149], v[182:185], v[50:53]
	v_mfma_f32_16x16x32_bf16 v[42:45], v[174:177], v[182:185], v[42:45]
	v_mfma_f32_16x16x32_bf16 v[34:37], v[146:149], v[208:211], v[34:37]
	v_mfma_f32_16x16x32_bf16 v[26:29], v[174:177], v[208:211], v[26:29]
	v_mfma_f32_16x16x32_bf16 v[18:21], v[146:149], v[216:219], v[18:21]
	v_mfma_f32_16x16x32_bf16 v[10:13], v[174:177], v[216:219], v[10:13]
	v_mfma_f32_16x16x32_bf16 v[6:9], v[146:149], v[224:227], v[6:9]
	v_mfma_f32_16x16x32_bf16 v[2:5], v[174:177], v[224:227], v[2:5]
	v_mfma_f32_16x16x32_bf16 v[50:53], v[150:153], v[204:207], v[50:53]
	v_mfma_f32_16x16x32_bf16 v[42:45], v[178:181], v[204:207], v[42:45]
	v_mfma_f32_16x16x32_bf16 v[34:37], v[150:153], v[212:215], v[34:37]
	v_mfma_f32_16x16x32_bf16 v[26:29], v[178:181], v[212:215], v[26:29]
	s_barrier
	s_setprio 2
	v_mfma_f32_16x16x32_bf16 v[18:21], v[150:153], v[220:223], v[18:21]
	v_mfma_f32_16x16x32_bf16 v[10:13], v[178:181], v[220:223], v[10:13]
	v_mfma_f32_16x16x32_bf16 v[6:9], v[150:153], v[234:237], v[6:9]
	v_mfma_f32_16x16x32_bf16 v[2:5], v[178:181], v[234:237], v[2:5]
	s_setprio 0
	s_add_i32 s46, 0, 0x18000
	s_add_i32 s47, 0, 0x1c000
	v_add_u32_e32 v142, s46, v188
	v_add_u32_e32 v164, s47, v188
	ds_read_b128 v[130:133], v142
	ds_read_b128 v[134:137], v142 offset:1024
	ds_read_b128 v[138:141], v142 offset:2048
	ds_read_b128 v[142:145], v142 offset:3072
	ds_read_b128 v[146:149], v164
	ds_read_b128 v[150:153], v164 offset:1024
	ds_read_b128 v[174:177], v164 offset:2048
	ds_read_b128 v[178:181], v164 offset:3072
	s_add_u32 s44, s44, 0x100000
	s_addc_u32 s45, s45, 0
	s_mov_b32 m0, s33
	v_lshl_add_u64 v[240:241], s[44:45], 0, v[156:157]
	ds_read_b128 v[182:185], v193 offset:32768
	ds_read_b128 v[204:207], v193 offset:33792
	ds_read_b128 v[208:211], v193 offset:34816
	ds_read_b128 v[212:215], v193 offset:35840
	ds_read_b128 v[216:219], v193 offset:36864
	ds_read_b128 v[220:223], v193 offset:37888
	ds_read_b128 v[224:227], v193 offset:38912
	ds_read_b128 v[234:237], v193 offset:39936
	global_load_lds_dwordx4 v[240:241], off
	v_lshl_add_u64 v[240:241], s[44:45], 0, v[160:161]
	s_mov_b32 m0, s39
	s_nop 0
	global_load_lds_dwordx4 v[240:241], off
	s_waitcnt vmcnt(8)
	s_waitcnt lgkmcnt(0)
	s_barrier
	s_setprio 1
	s_waitcnt lgkmcnt(0)
	v_mfma_f32_16x16x32_bf16 v[126:129], v[130:133], v[182:185], v[126:129]
	v_mfma_f32_16x16x32_bf16 v[122:125], v[138:141], v[182:185], v[122:125]
	v_mfma_f32_16x16x32_bf16 v[118:121], v[130:133], v[208:211], v[118:121]
	v_mfma_f32_16x16x32_bf16 v[110:113], v[138:141], v[208:211], v[110:113]
	v_mfma_f32_16x16x32_bf16 v[102:105], v[130:133], v[216:219], v[102:105]
	v_mfma_f32_16x16x32_bf16 v[94:97], v[138:141], v[216:219], v[94:97]
	v_mfma_f32_16x16x32_bf16 v[86:89], v[130:133], v[224:227], v[86:89]
	v_mfma_f32_16x16x32_bf16 v[78:81], v[138:141], v[224:227], v[78:81]
	v_mfma_f32_16x16x32_bf16 v[126:129], v[134:137], v[204:207], v[126:129]
	v_mfma_f32_16x16x32_bf16 v[122:125], v[142:145], v[204:207], v[122:125]
	v_mfma_f32_16x16x32_bf16 v[118:121], v[134:137], v[212:215], v[118:121]
	v_mfma_f32_16x16x32_bf16 v[110:113], v[142:145], v[212:215], v[110:113]
	v_mfma_f32_16x16x32_bf16 v[102:105], v[134:137], v[220:223], v[102:105]
	v_mfma_f32_16x16x32_bf16 v[94:97], v[142:145], v[220:223], v[94:97]
	v_mfma_f32_16x16x32_bf16 v[86:89], v[134:137], v[234:237], v[86:89]
	v_mfma_f32_16x16x32_bf16 v[78:81], v[142:145], v[234:237], v[78:81]
	s_setprio 0
	s_setprio 1
	v_mfma_f32_16x16x32_bf16 v[114:117], v[146:149], v[182:185], v[114:117]
	v_mfma_f32_16x16x32_bf16 v[106:109], v[174:177], v[182:185], v[106:109]
	v_mfma_f32_16x16x32_bf16 v[98:101], v[146:149], v[208:211], v[98:101]
	v_mfma_f32_16x16x32_bf16 v[90:93], v[174:177], v[208:211], v[90:93]
	v_mfma_f32_16x16x32_bf16 v[82:85], v[146:149], v[216:219], v[82:85]
	v_mfma_f32_16x16x32_bf16 v[74:77], v[174:177], v[216:219], v[74:77]
	v_mfma_f32_16x16x32_bf16 v[70:73], v[146:149], v[224:227], v[70:73]
	v_mfma_f32_16x16x32_bf16 v[66:69], v[174:177], v[224:227], v[66:69]
	v_mfma_f32_16x16x32_bf16 v[114:117], v[150:153], v[204:207], v[114:117]
	v_mfma_f32_16x16x32_bf16 v[106:109], v[178:181], v[204:207], v[106:109]
	v_mfma_f32_16x16x32_bf16 v[98:101], v[150:153], v[212:215], v[98:101]
	v_mfma_f32_16x16x32_bf16 v[90:93], v[178:181], v[212:215], v[90:93]
	s_barrier
	s_setprio 2
	v_mfma_f32_16x16x32_bf16 v[82:85], v[150:153], v[220:223], v[82:85]
	v_mfma_f32_16x16x32_bf16 v[74:77], v[178:181], v[220:223], v[74:77]
	v_mfma_f32_16x16x32_bf16 v[70:73], v[150:153], v[234:237], v[70:73]
	v_mfma_f32_16x16x32_bf16 v[66:69], v[178:181], v[234:237], v[66:69]
	s_setprio 0
	s_add_i32 s44, s46, s8
	v_lshl_add_u64 v[186:187], v[186:187], 0, s[20:21]
	s_mov_b32 m0, s44
	ds_read_b128 v[182:185], v193 offset:49152
	ds_read_b128 v[204:207], v193 offset:50176
	ds_read_b128 v[208:211], v193 offset:51200
	ds_read_b128 v[212:215], v193 offset:52224
	ds_read_b128 v[216:219], v193 offset:53248
	ds_read_b128 v[220:223], v193 offset:54272
	ds_read_b128 v[224:227], v193 offset:55296
	ds_read_b128 v[234:237], v193 offset:56320
	global_load_lds_dwordx4 v[186:187], off
	s_add_i32 m0, s44, 0x2000
	s_add_u32 s42, s42, 0x100080
	v_lshl_add_u64 v[186:187], v[194:195], 0, s[20:21]
	s_addc_u32 s43, s43, 0
	s_add_i32 s44, s47, s8
	global_load_lds_dwordx4 v[186:187], off
	v_lshl_add_u64 v[186:187], s[42:43], 0, v[158:159]
	s_mov_b32 m0, s44
	s_nop 0
	global_load_lds_dwordx4 v[186:187], off
	v_lshl_add_u64 v[186:187], s[42:43], 0, v[162:163]
	s_add_i32 m0, s44, 0x2000
	s_nop 0
	global_load_lds_dwordx4 v[186:187], off
	v_lshl_add_u64 v[186:187], v[200:201], 0, s[20:21]
	s_mov_b32 m0, s50
	s_nop 0
	global_load_lds_dwordx4 v[186:187], off
	v_lshl_add_u64 v[186:187], v[238:239], 0, s[20:21]
	s_mov_b32 m0, s51
	s_nop 0
	global_load_lds_dwordx4 v[186:187], off
	s_waitcnt vmcnt(8)
	s_waitcnt lgkmcnt(0)
	s_barrier
	s_setprio 1
	s_waitcnt lgkmcnt(0)
	v_mfma_f32_16x16x32_bf16 v[62:65], v[130:133], v[182:185], v[62:65]
	v_mfma_f32_16x16x32_bf16 v[58:61], v[138:141], v[182:185], v[58:61]
	v_mfma_f32_16x16x32_bf16 v[54:57], v[130:133], v[208:211], v[54:57]
	v_mfma_f32_16x16x32_bf16 v[46:49], v[138:141], v[208:211], v[46:49]
	v_mfma_f32_16x16x32_bf16 v[38:41], v[130:133], v[216:219], v[38:41]
	v_mfma_f32_16x16x32_bf16 v[30:33], v[138:141], v[216:219], v[30:33]
	v_mfma_f32_16x16x32_bf16 v[22:25], v[130:133], v[224:227], v[22:25]
	v_mfma_f32_16x16x32_bf16 v[14:17], v[138:141], v[224:227], v[14:17]
	v_mfma_f32_16x16x32_bf16 v[62:65], v[134:137], v[204:207], v[62:65]
	v_mfma_f32_16x16x32_bf16 v[58:61], v[142:145], v[204:207], v[58:61]
	v_mfma_f32_16x16x32_bf16 v[54:57], v[134:137], v[212:215], v[54:57]
	v_mfma_f32_16x16x32_bf16 v[46:49], v[142:145], v[212:215], v[46:49]
	v_mfma_f32_16x16x32_bf16 v[38:41], v[134:137], v[220:223], v[38:41]
	v_mfma_f32_16x16x32_bf16 v[30:33], v[142:145], v[220:223], v[30:33]
	v_mfma_f32_16x16x32_bf16 v[22:25], v[134:137], v[234:237], v[22:25]
	v_mfma_f32_16x16x32_bf16 v[14:17], v[142:145], v[234:237], v[14:17]
	s_setprio 0
	s_setprio 1
	v_mfma_f32_16x16x32_bf16 v[50:53], v[146:149], v[182:185], v[50:53]
	v_mfma_f32_16x16x32_bf16 v[42:45], v[174:177], v[182:185], v[42:45]
	v_mfma_f32_16x16x32_bf16 v[34:37], v[146:149], v[208:211], v[34:37]
	v_mfma_f32_16x16x32_bf16 v[26:29], v[174:177], v[208:211], v[26:29]
	v_mfma_f32_16x16x32_bf16 v[18:21], v[146:149], v[216:219], v[18:21]
	v_mfma_f32_16x16x32_bf16 v[10:13], v[174:177], v[216:219], v[10:13]
	v_mfma_f32_16x16x32_bf16 v[6:9], v[146:149], v[224:227], v[6:9]
	v_mfma_f32_16x16x32_bf16 v[2:5], v[174:177], v[224:227], v[2:5]
	v_mfma_f32_16x16x32_bf16 v[50:53], v[150:153], v[204:207], v[50:53]
	v_mfma_f32_16x16x32_bf16 v[42:45], v[178:181], v[204:207], v[42:45]
	v_mfma_f32_16x16x32_bf16 v[34:37], v[150:153], v[212:215], v[34:37]
	v_mfma_f32_16x16x32_bf16 v[26:29], v[178:181], v[212:215], v[26:29]
	s_barrier
	s_setprio 2
	v_mfma_f32_16x16x32_bf16 v[18:21], v[150:153], v[220:223], v[18:21]
	v_mfma_f32_16x16x32_bf16 v[10:13], v[178:181], v[220:223], v[10:13]
	v_mfma_f32_16x16x32_bf16 v[6:9], v[150:153], v[234:237], v[6:9]
	v_mfma_f32_16x16x32_bf16 v[2:5], v[178:181], v[234:237], v[2:5]
	s_setprio 0
	s_add_i32 s29, s29, 2
	s_add_u32 s40, s40, 0x100
	s_addc_u32 s41, s41, 0
	s_add_u32 s15, s15, 0x100
	s_addc_u32 s27, s27, 0
	s_cmp_gt_u32 s29, 61
	s_cbranch_scc0 .LBB0_412
	s_and_b64 vcc, exec, s[22:23]
	s_cbranch_vccz .LBB0_415
	s_barrier

.LBB0_514:
	ds_read_b128 v[156:159], v146
	ds_read_b128 v[160:163], v146 offset:1024
	ds_read_b128 v[164:167], v146 offset:2048
	ds_read_b128 v[168:171], v146 offset:3072
	ds_read_b128 v[172:175], v147
	s_waitcnt lgkmcnt(0)
	ds_read_b128 v[176:179], v147 offset:1024
	ds_read_b128 v[180:183], v147 offset:2048
	ds_read_b128 v[184:187], v147 offset:3072
	s_add_u32 s28, s26, 0xfff00080
	s_addc_u32 s29, s27, -1
	s_cmp_eq_u32 s50, 4
	s_cselect_b32 s31, s19, s29
	s_cselect_b32 s30, s18, s28
	s_cselect_b32 s29, s21, s49
	s_cselect_b32 s28, s20, s23
	s_mov_b32 m0, s36
	v_lshl_add_u64 v[142:143], s[26:27], 0, v[138:139]
	ds_read_b128 v[190:193], v148
	ds_read_b128 v[204:207], v148 offset:1024
	ds_read_b128 v[208:211], v148 offset:2048
	ds_read_b128 v[212:215], v148 offset:3072
	ds_read_b128 v[216:219], v148 offset:4096
	ds_read_b128 v[220:223], v148 offset:5120
	ds_read_b128 v[224:227], v148 offset:6144
	ds_read_b128 v[234:237], v148 offset:7168
	global_load_lds_dwordx4 v[142:143], off
	v_lshl_add_u64 v[142:143], s[26:27], 0, v[140:141]
	s_mov_b32 m0, s37
	s_nop 0
	global_load_lds_dwordx4 v[142:143], off
	s_waitcnt vmcnt(8)
	s_waitcnt lgkmcnt(0)
	s_barrier
	s_setprio 1
	s_waitcnt lgkmcnt(0)
	v_mfma_f32_16x16x32_bf16 v[126:129], v[156:159], v[190:193], v[126:129]
	v_mfma_f32_16x16x32_bf16 v[122:125], v[164:167], v[190:193], v[122:125]
	v_mfma_f32_16x16x32_bf16 v[118:121], v[156:159], v[208:211], v[118:121]
	v_mfma_f32_16x16x32_bf16 v[110:113], v[164:167], v[208:211], v[110:113]
	v_mfma_f32_16x16x32_bf16 v[102:105], v[156:159], v[216:219], v[102:105]
	v_mfma_f32_16x16x32_bf16 v[94:97], v[164:167], v[216:219], v[94:97]
	v_mfma_f32_16x16x32_bf16 v[82:85], v[156:159], v[224:227], v[82:85]
	v_mfma_f32_16x16x32_bf16 v[74:77], v[164:167], v[224:227], v[74:77]
	v_mfma_f32_16x16x32_bf16 v[126:129], v[160:163], v[204:207], v[126:129]
	v_mfma_f32_16x16x32_bf16 v[122:125], v[168:171], v[204:207], v[122:125]
	v_mfma_f32_16x16x32_bf16 v[118:121], v[160:163], v[212:215], v[118:121]
	v_mfma_f32_16x16x32_bf16 v[110:113], v[168:171], v[212:215], v[110:113]
	v_mfma_f32_16x16x32_bf16 v[102:105], v[160:163], v[220:223], v[102:105]
	v_mfma_f32_16x16x32_bf16 v[94:97], v[168:171], v[220:223], v[94:97]
	v_mfma_f32_16x16x32_bf16 v[82:85], v[160:163], v[234:237], v[82:85]
	v_mfma_f32_16x16x32_bf16 v[74:77], v[168:171], v[234:237], v[74:77]
	s_setprio 0
	s_setprio 1
	v_mfma_f32_16x16x32_bf16 v[114:117], v[172:175], v[190:193], v[114:117]
	v_mfma_f32_16x16x32_bf16 v[106:109], v[180:183], v[190:193], v[106:109]
	v_mfma_f32_16x16x32_bf16 v[98:101], v[172:175], v[208:211], v[98:101]
	v_mfma_f32_16x16x32_bf16 v[90:93], v[180:183], v[208:211], v[90:93]
	v_mfma_f32_16x16x32_bf16 v[86:89], v[172:175], v[216:219], v[86:89]
	v_mfma_f32_16x16x32_bf16 v[78:81], v[180:183], v[216:219], v[78:81]
	v_mfma_f32_16x16x32_bf16 v[70:73], v[172:175], v[224:227], v[70:73]
	v_mfma_f32_16x16x32_bf16 v[66:69], v[180:183], v[224:227], v[66:69]
	v_mfma_f32_16x16x32_bf16 v[114:117], v[176:179], v[204:207], v[114:117]
	v_mfma_f32_16x16x32_bf16 v[106:109], v[184:187], v[204:207], v[106:109]
	v_mfma_f32_16x16x32_bf16 v[98:101], v[176:179], v[212:215], v[98:101]
	v_mfma_f32_16x16x32_bf16 v[90:93], v[184:187], v[212:215], v[90:93]
	s_barrier
	s_setprio 2
	v_mfma_f32_16x16x32_bf16 v[86:89], v[176:179], v[220:223], v[86:89]
	v_mfma_f32_16x16x32_bf16 v[78:81], v[184:187], v[220:223], v[78:81]
	v_mfma_f32_16x16x32_bf16 v[70:73], v[176:179], v[234:237], v[70:73]
	v_mfma_f32_16x16x32_bf16 v[66:69], v[184:187], v[234:237], v[66:69]
	s_setprio 0
	s_mov_b32 m0, s38
	v_lshl_add_u64 v[142:143], s[28:29], 0, v[134:135]
	s_add_u32 s52, s28, 0x20000
	ds_read_b128 v[190:193], v148 offset:16384
	ds_read_b128 v[204:207], v148 offset:17408
	ds_read_b128 v[208:211], v148 offset:18432
	ds_read_b128 v[212:215], v148 offset:19456
	ds_read_b128 v[216:219], v148 offset:20480
	ds_read_b128 v[220:223], v148 offset:21504
	ds_read_b128 v[224:227], v148 offset:22528
	ds_read_b128 v[234:237], v148 offset:23552
	global_load_lds_dwordx4 v[142:143], off
	v_lshl_add_u64 v[152:153], s[28:29], 0, v[130:131]
	s_mov_b32 m0, s39
	s_addc_u32 s53, s29, 0
	global_load_lds_dwordx4 v[152:153], off
	v_lshl_add_u64 v[194:195], s[52:53], 0, v[134:135]
	s_mov_b32 m0, s40
	v_lshl_add_u64 v[200:201], s[30:31], 0, v[132:133]
	global_load_lds_dwordx4 v[194:195], off
	v_lshl_add_u64 v[194:195], s[52:53], 0, v[130:131]
	s_mov_b32 m0, s41
	s_nop 0
	global_load_lds_dwordx4 v[194:195], off
	v_lshl_add_u64 v[194:195], s[30:31], 0, v[136:137]
	s_mov_b32 m0, s9
	s_nop 0
	global_load_lds_dwordx4 v[194:195], off
	s_mov_b32 m0, s13
	s_nop 0
	global_load_lds_dwordx4 v[200:201], off
	s_waitcnt vmcnt(8)
	s_waitcnt lgkmcnt(0)
	s_barrier
	s_setprio 1
	s_waitcnt lgkmcnt(0)
	v_mfma_f32_16x16x32_bf16 v[62:65], v[156:159], v[190:193], v[62:65]
	v_mfma_f32_16x16x32_bf16 v[58:61], v[164:167], v[190:193], v[58:61]
	v_mfma_f32_16x16x32_bf16 v[54:57], v[156:159], v[208:211], v[54:57]
	v_mfma_f32_16x16x32_bf16 v[46:49], v[164:167], v[208:211], v[46:49]
	v_mfma_f32_16x16x32_bf16 v[38:41], v[156:159], v[216:219], v[38:41]
	v_mfma_f32_16x16x32_bf16 v[30:33], v[164:167], v[216:219], v[30:33]
	v_mfma_f32_16x16x32_bf16 v[22:25], v[156:159], v[224:227], v[22:25]
	v_mfma_f32_16x16x32_bf16 v[14:17], v[164:167], v[224:227], v[14:17]
	v_mfma_f32_16x16x32_bf16 v[62:65], v[160:163], v[204:207], v[62:65]
	v_mfma_f32_16x16x32_bf16 v[58:61], v[168:171], v[204:207], v[58:61]
	v_mfma_f32_16x16x32_bf16 v[54:57], v[160:163], v[212:215], v[54:57]
	v_mfma_f32_16x16x32_bf16 v[46:49], v[168:171], v[212:215], v[46:49]
	v_mfma_f32_16x16x32_bf16 v[38:41], v[160:163], v[220:223], v[38:41]
	v_mfma_f32_16x16x32_bf16 v[30:33], v[168:171], v[220:223], v[30:33]
	v_mfma_f32_16x16x32_bf16 v[22:25], v[160:163], v[234:237], v[22:25]
	v_mfma_f32_16x16x32_bf16 v[14:17], v[168:171], v[234:237], v[14:17]
	s_setprio 0
	s_setprio 1
	v_mfma_f32_16x16x32_bf16 v[50:53], v[172:175], v[190:193], v[50:53]
	v_mfma_f32_16x16x32_bf16 v[42:45], v[180:183], v[190:193], v[42:45]
	v_mfma_f32_16x16x32_bf16 v[34:37], v[172:175], v[208:211], v[34:37]
	v_mfma_f32_16x16x32_bf16 v[26:29], v[180:183], v[208:211], v[26:29]
	v_mfma_f32_16x16x32_bf16 v[18:21], v[172:175], v[216:219], v[18:21]
	v_mfma_f32_16x16x32_bf16 v[10:13], v[180:183], v[216:219], v[10:13]
	v_mfma_f32_16x16x32_bf16 v[6:9], v[172:175], v[224:227], v[6:9]
	v_mfma_f32_16x16x32_bf16 v[2:5], v[180:183], v[224:227], v[2:5]
	v_mfma_f32_16x16x32_bf16 v[50:53], v[176:179], v[204:207], v[50:53]
	v_mfma_f32_16x16x32_bf16 v[42:45], v[184:187], v[204:207], v[42:45]
	v_mfma_f32_16x16x32_bf16 v[34:37], v[176:179], v[212:215], v[34:37]
	v_mfma_f32_16x16x32_bf16 v[26:29], v[184:187], v[212:215], v[26:29]
	s_barrier
	s_setprio 2
	v_mfma_f32_16x16x32_bf16 v[18:21], v[176:179], v[220:223], v[18:21]
	v_mfma_f32_16x16x32_bf16 v[10:13], v[184:187], v[220:223], v[10:13]
	v_mfma_f32_16x16x32_bf16 v[6:9], v[176:179], v[234:237], v[6:9]
	v_mfma_f32_16x16x32_bf16 v[2:5], v[184:187], v[234:237], v[2:5]
	s_setprio 0
	ds_read_b128 v[156:159], v149
	ds_read_b128 v[160:163], v149 offset:1024
	ds_read_b128 v[164:167], v149 offset:2048
	ds_read_b128 v[168:171], v149 offset:3072
	ds_read_b128 v[172:175], v150
	ds_read_b128 v[176:179], v150 offset:1024
	ds_read_b128 v[180:183], v150 offset:2048
	ds_read_b128 v[184:187], v150 offset:3072
	s_add_u32 s30, s30, 0x100000
	s_addc_u32 s31, s31, 0
	s_mov_b32 m0, s14
	v_lshl_add_u64 v[238:239], s[30:31], 0, v[136:137]
	ds_read_b128 v[190:193], v148 offset:32768
	ds_read_b128 v[204:207], v148 offset:33792
	ds_read_b128 v[208:211], v148 offset:34816
	ds_read_b128 v[212:215], v148 offset:35840
	ds_read_b128 v[216:219], v148 offset:36864
	ds_read_b128 v[220:223], v148 offset:37888
	ds_read_b128 v[224:227], v148 offset:38912
	ds_read_b128 v[234:237], v148 offset:39936
	global_load_lds_dwordx4 v[238:239], off
	v_lshl_add_u64 v[238:239], s[30:31], 0, v[132:133]
	s_mov_b32 m0, s15
	s_nop 0
	global_load_lds_dwordx4 v[238:239], off
	s_waitcnt vmcnt(8)
	s_waitcnt lgkmcnt(0)
	s_barrier
	s_setprio 1
	s_waitcnt lgkmcnt(0)
	v_mfma_f32_16x16x32_bf16 v[126:129], v[156:159], v[190:193], v[126:129]
	v_mfma_f32_16x16x32_bf16 v[122:125], v[164:167], v[190:193], v[122:125]
	v_mfma_f32_16x16x32_bf16 v[118:121], v[156:159], v[208:211], v[118:121]
	v_mfma_f32_16x16x32_bf16 v[110:113], v[164:167], v[208:211], v[110:113]
	v_mfma_f32_16x16x32_bf16 v[102:105], v[156:159], v[216:219], v[102:105]
	v_mfma_f32_16x16x32_bf16 v[94:97], v[164:167], v[216:219], v[94:97]
	v_mfma_f32_16x16x32_bf16 v[82:85], v[156:159], v[224:227], v[82:85]
	v_mfma_f32_16x16x32_bf16 v[74:77], v[164:167], v[224:227], v[74:77]
	v_mfma_f32_16x16x32_bf16 v[126:129], v[160:163], v[204:207], v[126:129]
	v_mfma_f32_16x16x32_bf16 v[122:125], v[168:171], v[204:207], v[122:125]
	v_mfma_f32_16x16x32_bf16 v[118:121], v[160:163], v[212:215], v[118:121]
	v_mfma_f32_16x16x32_bf16 v[110:113], v[168:171], v[212:215], v[110:113]
	v_mfma_f32_16x16x32_bf16 v[102:105], v[160:163], v[220:223], v[102:105]
	v_mfma_f32_16x16x32_bf16 v[94:97], v[168:171], v[220:223], v[94:97]
	v_mfma_f32_16x16x32_bf16 v[82:85], v[160:163], v[234:237], v[82:85]
	v_mfma_f32_16x16x32_bf16 v[74:77], v[168:171], v[234:237], v[74:77]
	s_setprio 0
	s_setprio 1
	v_mfma_f32_16x16x32_bf16 v[114:117], v[172:175], v[190:193], v[114:117]
	v_mfma_f32_16x16x32_bf16 v[106:109], v[180:183], v[190:193], v[106:109]
	v_mfma_f32_16x16x32_bf16 v[98:101], v[172:175], v[208:211], v[98:101]
	v_mfma_f32_16x16x32_bf16 v[90:93], v[180:183], v[208:211], v[90:93]
	v_mfma_f32_16x16x32_bf16 v[86:89], v[172:175], v[216:219], v[86:89]
	v_mfma_f32_16x16x32_bf16 v[78:81], v[180:183], v[216:219], v[78:81]
	v_mfma_f32_16x16x32_bf16 v[70:73], v[172:175], v[224:227], v[70:73]
	v_mfma_f32_16x16x32_bf16 v[66:69], v[180:183], v[224:227], v[66:69]
	v_mfma_f32_16x16x32_bf16 v[114:117], v[176:179], v[204:207], v[114:117]
	v_mfma_f32_16x16x32_bf16 v[106:109], v[184:187], v[204:207], v[106:109]
	v_mfma_f32_16x16x32_bf16 v[98:101], v[176:179], v[212:215], v[98:101]
	v_mfma_f32_16x16x32_bf16 v[90:93], v[184:187], v[212:215], v[90:93]
	s_barrier
	s_setprio 2
	v_mfma_f32_16x16x32_bf16 v[86:89], v[176:179], v[220:223], v[86:89]
	v_mfma_f32_16x16x32_bf16 v[78:81], v[184:187], v[220:223], v[78:81]
	v_mfma_f32_16x16x32_bf16 v[70:73], v[176:179], v[234:237], v[70:73]
	v_mfma_f32_16x16x32_bf16 v[66:69], v[184:187], v[234:237], v[66:69]
	s_setprio 0
	s_mov_b32 m0, s42
	v_lshl_add_u64 v[142:143], v[142:143], 0, s[4:5]
	s_add_u32 s28, s28, 0x20080
	ds_read_b128 v[190:193], v148 offset:49152
	ds_read_b128 v[204:207], v148 offset:50176
	ds_read_b128 v[208:211], v148 offset:51200
	ds_read_b128 v[212:215], v148 offset:52224
	ds_read_b128 v[216:219], v148 offset:53248
	ds_read_b128 v[220:223], v148 offset:54272
	ds_read_b128 v[224:227], v148 offset:55296
	ds_read_b128 v[234:237], v148 offset:56320
	global_load_lds_dwordx4 v[142:143], off
	v_lshl_add_u64 v[142:143], v[152:153], 0, s[4:5]
	s_mov_b32 m0, s43
	s_addc_u32 s29, s29, 0
	global_load_lds_dwordx4 v[142:143], off
	v_lshl_add_u64 v[142:143], s[28:29], 0, v[134:135]
	s_mov_b32 m0, s44
	s_nop 0
	global_load_lds_dwordx4 v[142:143], off
	v_lshl_add_u64 v[142:143], s[28:29], 0, v[130:131]
	s_mov_b32 m0, s45
	s_nop 0
	global_load_lds_dwordx4 v[142:143], off
	v_lshl_add_u64 v[142:143], v[194:195], 0, s[4:5]
	s_mov_b32 m0, s34
	s_nop 0
	global_load_lds_dwordx4 v[142:143], off
	v_lshl_add_u64 v[142:143], v[200:201], 0, s[4:5]
	s_mov_b32 m0, s35
	s_nop 0
	global_load_lds_dwordx4 v[142:143], off
	s_waitcnt vmcnt(8)
	s_waitcnt lgkmcnt(0)
	s_barrier
	s_setprio 1
	s_waitcnt lgkmcnt(0)
	v_mfma_f32_16x16x32_bf16 v[62:65], v[156:159], v[190:193], v[62:65]
	v_mfma_f32_16x16x32_bf16 v[58:61], v[164:167], v[190:193], v[58:61]
	v_mfma_f32_16x16x32_bf16 v[54:57], v[156:159], v[208:211], v[54:57]
	v_mfma_f32_16x16x32_bf16 v[46:49], v[164:167], v[208:211], v[46:49]
	v_mfma_f32_16x16x32_bf16 v[38:41], v[156:159], v[216:219], v[38:41]
	v_mfma_f32_16x16x32_bf16 v[30:33], v[164:167], v[216:219], v[30:33]
	v_mfma_f32_16x16x32_bf16 v[22:25], v[156:159], v[224:227], v[22:25]
	v_mfma_f32_16x16x32_bf16 v[14:17], v[164:167], v[224:227], v[14:17]
	v_mfma_f32_16x16x32_bf16 v[62:65], v[160:163], v[204:207], v[62:65]
	v_mfma_f32_16x16x32_bf16 v[58:61], v[168:171], v[204:207], v[58:61]
	v_mfma_f32_16x16x32_bf16 v[54:57], v[160:163], v[212:215], v[54:57]
	v_mfma_f32_16x16x32_bf16 v[46:49], v[168:171], v[212:215], v[46:49]
	v_mfma_f32_16x16x32_bf16 v[38:41], v[160:163], v[220:223], v[38:41]
	v_mfma_f32_16x16x32_bf16 v[30:33], v[168:171], v[220:223], v[30:33]
	v_mfma_f32_16x16x32_bf16 v[22:25], v[160:163], v[234:237], v[22:25]
	v_mfma_f32_16x16x32_bf16 v[14:17], v[168:171], v[234:237], v[14:17]
	s_setprio 0
	s_setprio 1
	v_mfma_f32_16x16x32_bf16 v[50:53], v[172:175], v[190:193], v[50:53]
	v_mfma_f32_16x16x32_bf16 v[42:45], v[180:183], v[190:193], v[42:45]
	v_mfma_f32_16x16x32_bf16 v[34:37], v[172:175], v[208:211], v[34:37]
	v_mfma_f32_16x16x32_bf16 v[26:29], v[180:183], v[208:211], v[26:29]
	v_mfma_f32_16x16x32_bf16 v[18:21], v[172:175], v[216:219], v[18:21]
	v_mfma_f32_16x16x32_bf16 v[10:13], v[180:183], v[216:219], v[10:13]
	v_mfma_f32_16x16x32_bf16 v[6:9], v[172:175], v[224:227], v[6:9]
	v_mfma_f32_16x16x32_bf16 v[2:5], v[180:183], v[224:227], v[2:5]
	v_mfma_f32_16x16x32_bf16 v[50:53], v[176:179], v[204:207], v[50:53]
	v_mfma_f32_16x16x32_bf16 v[42:45], v[184:187], v[204:207], v[42:45]
	v_mfma_f32_16x16x32_bf16 v[34:37], v[176:179], v[212:215], v[34:37]
	v_mfma_f32_16x16x32_bf16 v[26:29], v[184:187], v[212:215], v[26:29]
	s_barrier
	s_setprio 2
	v_mfma_f32_16x16x32_bf16 v[18:21], v[176:179], v[220:223], v[18:21]
	v_mfma_f32_16x16x32_bf16 v[10:13], v[184:187], v[220:223], v[10:13]
	v_mfma_f32_16x16x32_bf16 v[6:9], v[176:179], v[234:237], v[6:9]
	v_mfma_f32_16x16x32_bf16 v[2:5], v[184:187], v[234:237], v[2:5]
	s_setprio 0
	s_add_i32 s50, s50, 2
	s_add_u32 s26, s26, 0x100
	s_addc_u32 s27, s27, 0
	s_add_u32 s23, s23, 0x100
	s_addc_u32 s49, s49, 0
	s_cmp_gt_u32 s50, 5
	s_cbranch_scc0 .LBB0_514
	s_and_b64 vcc, exec, s[6:7]
	s_cbranch_vccz .LBB0_517
	s_barrier

.LBB0_734:
	ds_read_b128 v[158:161], v227
	ds_read_b128 v[154:157], v227 offset:1024
	ds_read_b128 v[150:153], v227 offset:2048
	ds_read_b128 v[146:149], v227 offset:3072
	ds_read_b128 v[62:65], v233
	ds_read_b128 v[58:61], v233 offset:1024
	ds_read_b128 v[54:57], v233 offset:2048
	ds_read_b128 v[50:53], v233 offset:3072
	s_add_u32 s14, s30, s34
	s_addc_u32 s15, s31, s35
	s_add_u32 s14, s14, 0x100
	s_addc_u32 s15, s15, 0
	s_add_u32 s25, s77, s34
	s_addc_u32 s29, s78, s35
	s_cmpk_eq_i32 s34, 0xf00
	s_cselect_b32 s41, s31, s15
	s_cselect_b32 s40, s30, s14
	s_cselect_b32 s39, s1, s29
	s_cselect_b32 s38, s0, s25
	s_add_i32 s66, s23, 0xc000
	v_lshl_add_u64 v[240:241], v[162:163], 0, s[34:35]
	s_mov_b32 m0, s66
	s_add_i32 s67, s23, 0xe000
	ds_read_b128 v[166:169], v226
	ds_read_b128 v[170:173], v226 offset:1024
	ds_read_b128 v[174:177], v226 offset:2048
	ds_read_b128 v[178:181], v226 offset:3072
	ds_read_b128 v[182:185], v226 offset:4096
	ds_read_b128 v[186:189], v226 offset:5120
	ds_read_b128 v[190:193], v226 offset:6144
	ds_read_b128 v[236:239], v226 offset:7168
	global_load_lds_dwordx4 v[240:241], off
	v_lshl_add_u64 v[240:241], v[164:165], 0, s[34:35]
	s_mov_b32 m0, s67
	s_nop 0
	global_load_lds_dwordx4 v[240:241], off
	s_waitcnt vmcnt(8)
	s_waitcnt lgkmcnt(0)
	s_barrier
	s_setprio 1
	s_waitcnt lgkmcnt(0)
	v_mfma_i32_16x16x64_i8 v[142:145], v[158:161], v[166:169], v[142:145]
	s_nop 0
	v_mfma_i32_16x16x64_i8 v[142:145], v[154:157], v[170:173], v[142:145]
	v_mfma_i32_16x16x64_i8 v[138:141], v[150:153], v[166:169], v[138:141]
	s_nop 0
	v_mfma_i32_16x16x64_i8 v[138:141], v[146:149], v[170:173], v[138:141]
	v_mfma_i32_16x16x64_i8 v[126:129], v[158:161], v[174:177], v[126:129]
	s_nop 0
	v_mfma_i32_16x16x64_i8 v[126:129], v[154:157], v[178:181], v[126:129]
	v_mfma_i32_16x16x64_i8 v[122:125], v[150:153], v[174:177], v[122:125]
	s_nop 0
	v_mfma_i32_16x16x64_i8 v[122:125], v[146:149], v[178:181], v[122:125]
	v_mfma_i32_16x16x64_i8 v[110:113], v[158:161], v[182:185], v[110:113]
	s_nop 0
	v_mfma_i32_16x16x64_i8 v[110:113], v[154:157], v[186:189], v[110:113]
	v_mfma_i32_16x16x64_i8 v[106:109], v[150:153], v[182:185], v[106:109]
	s_nop 0
	v_mfma_i32_16x16x64_i8 v[106:109], v[146:149], v[186:189], v[106:109]
	v_mfma_i32_16x16x64_i8 v[94:97], v[158:161], v[190:193], v[94:97]
	s_nop 0
	v_mfma_i32_16x16x64_i8 v[94:97], v[154:157], v[236:239], v[94:97]
	v_mfma_i32_16x16x64_i8 v[90:93], v[150:153], v[190:193], v[90:93]
	s_nop 0
	v_mfma_i32_16x16x64_i8 v[90:93], v[146:149], v[236:239], v[90:93]
	s_setprio 0
	s_setprio 1
	v_mfma_i32_16x16x64_i8 v[134:137], v[62:65], v[166:169], v[134:137]
	s_nop 0
	v_mfma_i32_16x16x64_i8 v[134:137], v[58:61], v[170:173], v[134:137]
	v_mfma_i32_16x16x64_i8 v[130:133], v[54:57], v[166:169], v[130:133]
	s_nop 0
	v_mfma_i32_16x16x64_i8 v[130:133], v[50:53], v[170:173], v[130:133]
	v_mfma_i32_16x16x64_i8 v[118:121], v[62:65], v[174:177], v[118:121]
	s_nop 0
	v_mfma_i32_16x16x64_i8 v[118:121], v[58:61], v[178:181], v[118:121]
	v_mfma_i32_16x16x64_i8 v[114:117], v[54:57], v[174:177], v[114:117]
	s_nop 0
	v_mfma_i32_16x16x64_i8 v[114:117], v[50:53], v[178:181], v[114:117]
	v_mfma_i32_16x16x64_i8 v[102:105], v[62:65], v[182:185], v[102:105]
	s_nop 0
	v_mfma_i32_16x16x64_i8 v[102:105], v[58:61], v[186:189], v[102:105]
	v_mfma_i32_16x16x64_i8 v[98:101], v[54:57], v[182:185], v[98:101]
	s_nop 0
	v_mfma_i32_16x16x64_i8 v[98:101], v[50:53], v[186:189], v[98:101]
	s_barrier
	s_setprio 2
	v_mfma_i32_16x16x64_i8 v[86:89], v[62:65], v[190:193], v[86:89]
	s_nop 0
	v_mfma_i32_16x16x64_i8 v[86:89], v[58:61], v[236:239], v[86:89]
	v_mfma_i32_16x16x64_i8 v[82:85], v[54:57], v[190:193], v[82:85]
	s_nop 0
	v_mfma_i32_16x16x64_i8 v[82:85], v[50:53], v[236:239], v[82:85]
	s_setprio 0
	s_add_i32 s68, s60, s21
	s_add_i32 s69, s68, 0x2000
	v_lshl_add_u64 v[166:167], s[38:39], 0, v[202:203]
	s_mov_b32 m0, s68
	s_add_u32 s14, s38, 0x80000
	ds_read_b128 v[174:177], v226 offset:16384
	ds_read_b128 v[178:181], v226 offset:17408
	ds_read_b128 v[182:185], v226 offset:18432
	ds_read_b128 v[186:189], v226 offset:19456
	ds_read_b128 v[190:193], v226 offset:20480
	ds_read_b128 v[236:239], v226 offset:21504
	ds_read_b128 v[240:243], v226 offset:22528
	ds_read_b128 v[244:247], v226 offset:23552
	global_load_lds_dwordx4 v[166:167], off
	v_lshl_add_u64 v[168:169], s[38:39], 0, v[206:207]
	s_mov_b32 m0, s69
	s_addc_u32 s15, s39, 0
	s_add_i32 s70, s61, s21
	global_load_lds_dwordx4 v[168:169], off
	v_lshl_add_u64 v[170:171], s[14:15], 0, v[202:203]
	s_mov_b32 m0, s70
	s_add_i32 s71, s70, 0x2000
	global_load_lds_dwordx4 v[170:171], off
	v_lshl_add_u64 v[170:171], s[14:15], 0, v[206:207]
	s_mov_b32 m0, s71
	v_lshl_add_u64 v[172:173], s[40:41], 0, v[204:205]
	global_load_lds_dwordx4 v[170:171], off
	v_lshl_add_u64 v[170:171], s[40:41], 0, v[194:195]
	s_mov_b32 m0, s23
	s_nop 0
	global_load_lds_dwordx4 v[170:171], off
	s_mov_b32 m0, s42
	s_nop 0
	global_load_lds_dwordx4 v[172:173], off
	s_waitcnt vmcnt(8)
	s_waitcnt lgkmcnt(0)
	s_barrier
	s_setprio 1
	s_waitcnt lgkmcnt(0)
	v_mfma_i32_16x16x64_i8 v[78:81], v[158:161], v[174:177], v[78:81]
	s_nop 0
	v_mfma_i32_16x16x64_i8 v[78:81], v[154:157], v[178:181], v[78:81]
	v_mfma_i32_16x16x64_i8 v[74:77], v[150:153], v[174:177], v[74:77]
	s_nop 0
	v_mfma_i32_16x16x64_i8 v[74:77], v[146:149], v[178:181], v[74:77]
	v_mfma_i32_16x16x64_i8 v[46:49], v[158:161], v[182:185], v[46:49]
	s_nop 0
	v_mfma_i32_16x16x64_i8 v[46:49], v[154:157], v[186:189], v[46:49]
	v_mfma_i32_16x16x64_i8 v[42:45], v[150:153], v[182:185], v[42:45]
	s_nop 0
	v_mfma_i32_16x16x64_i8 v[42:45], v[146:149], v[186:189], v[42:45]
	v_mfma_i32_16x16x64_i8 v[30:33], v[158:161], v[190:193], v[30:33]
	s_nop 0
	v_mfma_i32_16x16x64_i8 v[30:33], v[154:157], v[236:239], v[30:33]
	v_mfma_i32_16x16x64_i8 v[26:29], v[150:153], v[190:193], v[26:29]
	s_nop 0
	v_mfma_i32_16x16x64_i8 v[26:29], v[146:149], v[236:239], v[26:29]
	v_mfma_i32_16x16x64_i8 v[14:17], v[158:161], v[240:243], v[14:17]
	s_nop 0
	v_mfma_i32_16x16x64_i8 v[14:17], v[154:157], v[244:247], v[14:17]
	v_mfma_i32_16x16x64_i8 v[10:13], v[150:153], v[240:243], v[10:13]
	s_nop 0
	v_mfma_i32_16x16x64_i8 v[10:13], v[146:149], v[244:247], v[10:13]
	s_setprio 0
	s_setprio 1
	v_mfma_i32_16x16x64_i8 v[70:73], v[62:65], v[174:177], v[70:73]
	s_nop 0
	v_mfma_i32_16x16x64_i8 v[70:73], v[58:61], v[178:181], v[70:73]
	v_mfma_i32_16x16x64_i8 v[66:69], v[54:57], v[174:177], v[66:69]
	s_nop 0
	v_mfma_i32_16x16x64_i8 v[66:69], v[50:53], v[178:181], v[66:69]
	v_mfma_i32_16x16x64_i8 v[38:41], v[62:65], v[182:185], v[38:41]
	s_nop 0
	v_mfma_i32_16x16x64_i8 v[38:41], v[58:61], v[186:189], v[38:41]
	v_mfma_i32_16x16x64_i8 v[34:37], v[54:57], v[182:185], v[34:37]
	s_nop 0
	v_mfma_i32_16x16x64_i8 v[34:37], v[50:53], v[186:189], v[34:37]
	v_mfma_i32_16x16x64_i8 v[22:25], v[62:65], v[190:193], v[22:25]
	s_nop 0
	v_mfma_i32_16x16x64_i8 v[22:25], v[58:61], v[236:239], v[22:25]
	v_mfma_i32_16x16x64_i8 v[18:21], v[54:57], v[190:193], v[18:21]
	s_nop 0
	v_mfma_i32_16x16x64_i8 v[18:21], v[50:53], v[236:239], v[18:21]
	s_barrier
	s_setprio 2
	v_mfma_i32_16x16x64_i8 v[6:9], v[62:65], v[240:243], v[6:9]
	s_nop 0
	v_mfma_i32_16x16x64_i8 v[6:9], v[58:61], v[244:247], v[6:9]
	v_mfma_i32_16x16x64_i8 v[2:5], v[54:57], v[240:243], v[2:5]
	s_nop 0
	v_mfma_i32_16x16x64_i8 v[2:5], v[50:53], v[244:247], v[2:5]
	s_setprio 0
	s_add_i32 s72, 0, 0x18000
	v_add_u32_e32 v235, s72, v225
	s_add_i32 s74, 0, 0x1c000
	v_add_u32_e32 v236, s74, v225
	ds_read_b128 v[50:53], v235
	ds_read_b128 v[54:57], v235 offset:1024
	ds_read_b128 v[58:61], v235 offset:2048
	ds_read_b128 v[62:65], v235 offset:3072
	ds_read_b128 v[146:149], v236
	ds_read_b128 v[150:153], v236 offset:1024
	ds_read_b128 v[154:157], v236 offset:2048
	ds_read_b128 v[158:161], v236 offset:3072
	s_add_u32 s14, s40, 0x80000
	s_addc_u32 s15, s41, 0
	s_mov_b32 m0, s43
	v_lshl_add_u64 v[250:251], s[14:15], 0, v[194:195]
	ds_read_b128 v[174:177], v226 offset:32768
	ds_read_b128 v[178:181], v226 offset:33792
	ds_read_b128 v[182:185], v226 offset:34816
	ds_read_b128 v[186:189], v226 offset:35840
	ds_read_b128 v[190:193], v226 offset:36864
	ds_read_b128 v[238:241], v226 offset:37888
	ds_read_b128 v[242:245], v226 offset:38912
	ds_read_b128 v[246:249], v226 offset:39936
	global_load_lds_dwordx4 v[250:251], off
	v_lshl_add_u64 v[250:251], s[14:15], 0, v[204:205]
	s_mov_b32 m0, s44
	s_nop 0
	global_load_lds_dwordx4 v[250:251], off
	s_waitcnt vmcnt(8)
	s_waitcnt lgkmcnt(0)
	s_barrier
	s_setprio 1
	s_waitcnt lgkmcnt(0)
	v_mfma_i32_16x16x64_i8 v[142:145], v[50:53], v[174:177], v[142:145]
	s_nop 0
	v_mfma_i32_16x16x64_i8 v[142:145], v[54:57], v[178:181], v[142:145]
	v_mfma_i32_16x16x64_i8 v[138:141], v[58:61], v[174:177], v[138:141]
	s_nop 0
	v_mfma_i32_16x16x64_i8 v[138:141], v[62:65], v[178:181], v[138:141]
	v_mfma_i32_16x16x64_i8 v[126:129], v[50:53], v[182:185], v[126:129]
	s_nop 0
	v_mfma_i32_16x16x64_i8 v[126:129], v[54:57], v[186:189], v[126:129]
	v_mfma_i32_16x16x64_i8 v[122:125], v[58:61], v[182:185], v[122:125]
	s_nop 0
	v_mfma_i32_16x16x64_i8 v[122:125], v[62:65], v[186:189], v[122:125]
	v_mfma_i32_16x16x64_i8 v[110:113], v[50:53], v[190:193], v[110:113]
	s_nop 0
	v_mfma_i32_16x16x64_i8 v[110:113], v[54:57], v[238:241], v[110:113]
	v_mfma_i32_16x16x64_i8 v[106:109], v[58:61], v[190:193], v[106:109]
	s_nop 0
	v_mfma_i32_16x16x64_i8 v[106:109], v[62:65], v[238:241], v[106:109]
	v_mfma_i32_16x16x64_i8 v[94:97], v[50:53], v[242:245], v[94:97]
	s_nop 0
	v_mfma_i32_16x16x64_i8 v[94:97], v[54:57], v[246:249], v[94:97]
	v_mfma_i32_16x16x64_i8 v[90:93], v[58:61], v[242:245], v[90:93]
	s_nop 0
	v_mfma_i32_16x16x64_i8 v[90:93], v[62:65], v[246:249], v[90:93]
	s_setprio 0
	s_setprio 1
	v_mfma_i32_16x16x64_i8 v[134:137], v[146:149], v[174:177], v[134:137]
	s_nop 0
	v_mfma_i32_16x16x64_i8 v[134:137], v[150:153], v[178:181], v[134:137]
	v_mfma_i32_16x16x64_i8 v[130:133], v[154:157], v[174:177], v[130:133]
	s_nop 0
	v_mfma_i32_16x16x64_i8 v[130:133], v[158:161], v[178:181], v[130:133]
	v_mfma_i32_16x16x64_i8 v[118:121], v[146:149], v[182:185], v[118:121]
	s_nop 0
	v_mfma_i32_16x16x64_i8 v[118:121], v[150:153], v[186:189], v[118:121]
	v_mfma_i32_16x16x64_i8 v[114:117], v[154:157], v[182:185], v[114:117]
	s_nop 0
	v_mfma_i32_16x16x64_i8 v[114:117], v[158:161], v[186:189], v[114:117]
	v_mfma_i32_16x16x64_i8 v[102:105], v[146:149], v[190:193], v[102:105]
	s_nop 0
	v_mfma_i32_16x16x64_i8 v[102:105], v[150:153], v[238:241], v[102:105]
	v_mfma_i32_16x16x64_i8 v[98:101], v[154:157], v[190:193], v[98:101]
	s_nop 0
	v_mfma_i32_16x16x64_i8 v[98:101], v[158:161], v[238:241], v[98:101]
	s_barrier
	s_setprio 2
	v_mfma_i32_16x16x64_i8 v[86:89], v[146:149], v[242:245], v[86:89]
	s_nop 0
	v_mfma_i32_16x16x64_i8 v[86:89], v[150:153], v[246:249], v[86:89]
	v_mfma_i32_16x16x64_i8 v[82:85], v[154:157], v[242:245], v[82:85]
	s_nop 0
	v_mfma_i32_16x16x64_i8 v[82:85], v[158:161], v[246:249], v[82:85]
	s_setprio 0
	s_add_i32 s72, s72, s21
	s_add_i32 s73, s72, 0x2000
	v_lshl_add_u64 v[166:167], v[166:167], 0, s[6:7]
	s_mov_b32 m0, s72
	s_add_u32 s14, s38, 0x80080
	ds_read_b128 v[174:177], v226 offset:49152
	ds_read_b128 v[178:181], v226 offset:50176
	ds_read_b128 v[182:185], v226 offset:51200
	ds_read_b128 v[186:189], v226 offset:52224
	ds_read_b128 v[190:193], v226 offset:53248
	ds_read_b128 v[238:241], v226 offset:54272
	ds_read_b128 v[242:245], v226 offset:55296
	ds_read_b128 v[246:249], v226 offset:56320
	global_load_lds_dwordx4 v[166:167], off
	v_lshl_add_u64 v[166:167], v[168:169], 0, s[6:7]
	s_mov_b32 m0, s73
	s_addc_u32 s15, s39, 0
	s_add_i32 s74, s74, s21
	global_load_lds_dwordx4 v[166:167], off
	v_lshl_add_u64 v[166:167], s[14:15], 0, v[202:203]
	s_mov_b32 m0, s74
	s_add_i32 s75, s74, 0x2000
	global_load_lds_dwordx4 v[166:167], off
	v_lshl_add_u64 v[166:167], s[14:15], 0, v[206:207]
	s_mov_b32 m0, s75
	s_nop 0
	global_load_lds_dwordx4 v[166:167], off
	v_lshl_add_u64 v[166:167], v[170:171], 0, s[6:7]
	s_mov_b32 m0, s51
	s_nop 0
	global_load_lds_dwordx4 v[166:167], off
	v_lshl_add_u64 v[166:167], v[172:173], 0, s[6:7]
	s_mov_b32 m0, s53
	s_nop 0
	global_load_lds_dwordx4 v[166:167], off
	s_waitcnt vmcnt(8)
	s_waitcnt lgkmcnt(0)
	s_barrier
	s_setprio 1
	s_waitcnt lgkmcnt(0)
	v_mfma_i32_16x16x64_i8 v[78:81], v[50:53], v[174:177], v[78:81]
	s_nop 0
	v_mfma_i32_16x16x64_i8 v[78:81], v[54:57], v[178:181], v[78:81]
	v_mfma_i32_16x16x64_i8 v[74:77], v[58:61], v[174:177], v[74:77]
	s_nop 0
	v_mfma_i32_16x16x64_i8 v[74:77], v[62:65], v[178:181], v[74:77]
	v_mfma_i32_16x16x64_i8 v[46:49], v[50:53], v[182:185], v[46:49]
	s_nop 0
	v_mfma_i32_16x16x64_i8 v[46:49], v[54:57], v[186:189], v[46:49]
	v_mfma_i32_16x16x64_i8 v[42:45], v[58:61], v[182:185], v[42:45]
	s_nop 0
	v_mfma_i32_16x16x64_i8 v[42:45], v[62:65], v[186:189], v[42:45]
	v_mfma_i32_16x16x64_i8 v[30:33], v[50:53], v[190:193], v[30:33]
	s_nop 0
	v_mfma_i32_16x16x64_i8 v[30:33], v[54:57], v[238:241], v[30:33]
	v_mfma_i32_16x16x64_i8 v[26:29], v[58:61], v[190:193], v[26:29]
	s_nop 0
	v_mfma_i32_16x16x64_i8 v[26:29], v[62:65], v[238:241], v[26:29]
	v_mfma_i32_16x16x64_i8 v[14:17], v[50:53], v[242:245], v[14:17]
	s_nop 0
	v_mfma_i32_16x16x64_i8 v[14:17], v[54:57], v[246:249], v[14:17]
	v_mfma_i32_16x16x64_i8 v[10:13], v[58:61], v[242:245], v[10:13]
	s_nop 0
	v_mfma_i32_16x16x64_i8 v[10:13], v[62:65], v[246:249], v[10:13]
	s_setprio 0
	s_setprio 1
	v_mfma_i32_16x16x64_i8 v[70:73], v[146:149], v[174:177], v[70:73]
	s_nop 0
	v_mfma_i32_16x16x64_i8 v[70:73], v[150:153], v[178:181], v[70:73]
	v_mfma_i32_16x16x64_i8 v[66:69], v[154:157], v[174:177], v[66:69]
	s_nop 0
	v_mfma_i32_16x16x64_i8 v[66:69], v[158:161], v[178:181], v[66:69]
	v_mfma_i32_16x16x64_i8 v[38:41], v[146:149], v[182:185], v[38:41]
	s_nop 0
	v_mfma_i32_16x16x64_i8 v[38:41], v[150:153], v[186:189], v[38:41]
	v_mfma_i32_16x16x64_i8 v[34:37], v[154:157], v[182:185], v[34:37]
	s_nop 0
	v_mfma_i32_16x16x64_i8 v[34:37], v[158:161], v[186:189], v[34:37]
	v_mfma_i32_16x16x64_i8 v[22:25], v[146:149], v[190:193], v[22:25]
	s_nop 0
	v_mfma_i32_16x16x64_i8 v[22:25], v[150:153], v[238:241], v[22:25]
	v_mfma_i32_16x16x64_i8 v[18:21], v[154:157], v[190:193], v[18:21]
	s_nop 0
	v_mfma_i32_16x16x64_i8 v[18:21], v[158:161], v[238:241], v[18:21]
	s_barrier
	s_setprio 2
	v_mfma_i32_16x16x64_i8 v[6:9], v[146:149], v[242:245], v[6:9]
	s_nop 0
	v_mfma_i32_16x16x64_i8 v[6:9], v[150:153], v[246:249], v[6:9]
	v_mfma_i32_16x16x64_i8 v[2:5], v[154:157], v[242:245], v[2:5]
	s_nop 0
	v_mfma_i32_16x16x64_i8 v[2:5], v[158:161], v[246:249], v[2:5]
	s_setprio 0
	s_add_i32 s3, s3, 2
	s_add_u32 s34, s34, 0x100
	s_addc_u32 s35, s35, 0
	s_cmp_gt_u32 s3, 29
	s_cbranch_scc0 .LBB0_734
	s_nop 15
	s_nop 15
	s_and_b64 vcc, exec, s[8:9]
	s_cbranch_vccz .LBB0_737
	s_barrier

.LBB0_740:
	ds_read_b128 v[158:161], v227
	ds_read_b128 v[154:157], v227 offset:1024
	ds_read_b128 v[150:153], v227 offset:2048
	ds_read_b128 v[146:149], v227 offset:3072
	ds_read_b128 v[62:65], v233
	ds_read_b128 v[58:61], v233 offset:1024
	ds_read_b128 v[54:57], v233 offset:2048
	ds_read_b128 v[50:53], v233 offset:3072
	s_add_u32 s36, s38, 0xfff80080
	s_addc_u32 s37, s39, -1
	s_cmp_eq_u32 s33, 28
	s_cselect_b32 s41, s1, s37
	s_cselect_b32 s40, s0, s36
	s_cselect_b32 s37, s15, s29
	s_cselect_b32 s36, s14, s25
	s_mov_b32 m0, s66
	v_lshl_add_u64 v[238:239], s[38:39], 0, v[208:209]
	ds_read_b128 v[162:165], v226
	ds_read_b128 v[166:169], v226 offset:1024
	ds_read_b128 v[170:173], v226 offset:2048
	ds_read_b128 v[174:177], v226 offset:3072
	ds_read_b128 v[178:181], v226 offset:4096
	ds_read_b128 v[182:185], v226 offset:5120
	ds_read_b128 v[186:189], v226 offset:6144
	ds_read_b128 v[190:193], v226 offset:7168
	global_load_lds_dwordx4 v[238:239], off
	v_lshl_add_u64 v[238:239], s[38:39], 0, v[212:213]
	s_mov_b32 m0, s67
	s_nop 0
	global_load_lds_dwordx4 v[238:239], off
	s_waitcnt vmcnt(8)
	s_waitcnt lgkmcnt(0)
	s_barrier
	s_setprio 1
	s_waitcnt lgkmcnt(0)
	v_mfma_i32_16x16x64_i8 v[142:145], v[158:161], v[162:165], v[142:145]
	s_nop 0
	v_mfma_i32_16x16x64_i8 v[142:145], v[154:157], v[166:169], v[142:145]
	v_mfma_i32_16x16x64_i8 v[138:141], v[150:153], v[162:165], v[138:141]
	s_nop 0
	v_mfma_i32_16x16x64_i8 v[138:141], v[146:149], v[166:169], v[138:141]
	v_mfma_i32_16x16x64_i8 v[126:129], v[158:161], v[170:173], v[126:129]
	s_nop 0
	v_mfma_i32_16x16x64_i8 v[126:129], v[154:157], v[174:177], v[126:129]
	v_mfma_i32_16x16x64_i8 v[122:125], v[150:153], v[170:173], v[122:125]
	s_nop 0
	v_mfma_i32_16x16x64_i8 v[122:125], v[146:149], v[174:177], v[122:125]
	v_mfma_i32_16x16x64_i8 v[110:113], v[158:161], v[178:181], v[110:113]
	s_nop 0
	v_mfma_i32_16x16x64_i8 v[110:113], v[154:157], v[182:185], v[110:113]
	v_mfma_i32_16x16x64_i8 v[106:109], v[150:153], v[178:181], v[106:109]
	s_nop 0
	v_mfma_i32_16x16x64_i8 v[106:109], v[146:149], v[182:185], v[106:109]
	v_mfma_i32_16x16x64_i8 v[94:97], v[158:161], v[186:189], v[94:97]
	s_nop 0
	v_mfma_i32_16x16x64_i8 v[94:97], v[154:157], v[190:193], v[94:97]
	v_mfma_i32_16x16x64_i8 v[90:93], v[150:153], v[186:189], v[90:93]
	s_nop 0
	v_mfma_i32_16x16x64_i8 v[90:93], v[146:149], v[190:193], v[90:93]
	s_setprio 0
	s_setprio 1
	v_mfma_i32_16x16x64_i8 v[134:137], v[62:65], v[162:165], v[134:137]
	s_nop 0
	v_mfma_i32_16x16x64_i8 v[134:137], v[58:61], v[166:169], v[134:137]
	v_mfma_i32_16x16x64_i8 v[130:133], v[54:57], v[162:165], v[130:133]
	s_nop 0
	v_mfma_i32_16x16x64_i8 v[130:133], v[50:53], v[166:169], v[130:133]
	v_mfma_i32_16x16x64_i8 v[118:121], v[62:65], v[170:173], v[118:121]
	s_nop 0
	v_mfma_i32_16x16x64_i8 v[118:121], v[58:61], v[174:177], v[118:121]
	v_mfma_i32_16x16x64_i8 v[114:117], v[54:57], v[170:173], v[114:117]
	s_nop 0
	v_mfma_i32_16x16x64_i8 v[114:117], v[50:53], v[174:177], v[114:117]
	v_mfma_i32_16x16x64_i8 v[102:105], v[62:65], v[178:181], v[102:105]
	s_nop 0
	v_mfma_i32_16x16x64_i8 v[102:105], v[58:61], v[182:185], v[102:105]
	v_mfma_i32_16x16x64_i8 v[98:101], v[54:57], v[178:181], v[98:101]
	s_nop 0
	v_mfma_i32_16x16x64_i8 v[98:101], v[50:53], v[182:185], v[98:101]
	s_barrier
	s_setprio 2
	v_mfma_i32_16x16x64_i8 v[86:89], v[62:65], v[186:189], v[86:89]
	s_nop 0
	v_mfma_i32_16x16x64_i8 v[86:89], v[58:61], v[190:193], v[86:89]
	v_mfma_i32_16x16x64_i8 v[82:85], v[54:57], v[186:189], v[82:85]
	s_nop 0
	v_mfma_i32_16x16x64_i8 v[82:85], v[50:53], v[190:193], v[82:85]
	s_setprio 0
	s_mov_b32 m0, s68
	v_lshl_add_u64 v[162:163], s[36:37], 0, v[202:203]
	s_add_u32 s80, s36, 0x80000
	ds_read_b128 v[170:173], v226 offset:16384
	ds_read_b128 v[174:177], v226 offset:17408
	ds_read_b128 v[178:181], v226 offset:18432
	ds_read_b128 v[182:185], v226 offset:19456
	ds_read_b128 v[186:189], v226 offset:20480
	ds_read_b128 v[190:193], v226 offset:21504
	ds_read_b128 v[238:241], v226 offset:22528
	ds_read_b128 v[242:245], v226 offset:23552
	global_load_lds_dwordx4 v[162:163], off
	v_lshl_add_u64 v[164:165], s[36:37], 0, v[206:207]
	s_mov_b32 m0, s69
	s_addc_u32 s81, s37, 0
	global_load_lds_dwordx4 v[164:165], off
	v_lshl_add_u64 v[166:167], s[80:81], 0, v[202:203]
	s_mov_b32 m0, s70
	v_lshl_add_u64 v[168:169], s[40:41], 0, v[204:205]
	global_load_lds_dwordx4 v[166:167], off
	v_lshl_add_u64 v[166:167], s[80:81], 0, v[206:207]
	s_mov_b32 m0, s71
	s_nop 0
	global_load_lds_dwordx4 v[166:167], off
	v_lshl_add_u64 v[166:167], s[40:41], 0, v[194:195]
	s_mov_b32 m0, s23
	s_nop 0
	global_load_lds_dwordx4 v[166:167], off
	s_mov_b32 m0, s42
	s_nop 0
	global_load_lds_dwordx4 v[168:169], off
	s_waitcnt vmcnt(8)
	s_waitcnt lgkmcnt(0)
	s_barrier
	s_setprio 1
	s_waitcnt lgkmcnt(0)
	v_mfma_i32_16x16x64_i8 v[78:81], v[158:161], v[170:173], v[78:81]
	s_nop 0
	v_mfma_i32_16x16x64_i8 v[78:81], v[154:157], v[174:177], v[78:81]
	v_mfma_i32_16x16x64_i8 v[74:77], v[150:153], v[170:173], v[74:77]
	s_nop 0
	v_mfma_i32_16x16x64_i8 v[74:77], v[146:149], v[174:177], v[74:77]
	v_mfma_i32_16x16x64_i8 v[46:49], v[158:161], v[178:181], v[46:49]
	s_nop 0
	v_mfma_i32_16x16x64_i8 v[46:49], v[154:157], v[182:185], v[46:49]
	v_mfma_i32_16x16x64_i8 v[42:45], v[150:153], v[178:181], v[42:45]
	s_nop 0
	v_mfma_i32_16x16x64_i8 v[42:45], v[146:149], v[182:185], v[42:45]
	v_mfma_i32_16x16x64_i8 v[30:33], v[158:161], v[186:189], v[30:33]
	s_nop 0
	v_mfma_i32_16x16x64_i8 v[30:33], v[154:157], v[190:193], v[30:33]
	v_mfma_i32_16x16x64_i8 v[26:29], v[150:153], v[186:189], v[26:29]
	s_nop 0
	v_mfma_i32_16x16x64_i8 v[26:29], v[146:149], v[190:193], v[26:29]
	v_mfma_i32_16x16x64_i8 v[14:17], v[158:161], v[238:241], v[14:17]
	s_nop 0
	v_mfma_i32_16x16x64_i8 v[14:17], v[154:157], v[242:245], v[14:17]
	v_mfma_i32_16x16x64_i8 v[10:13], v[150:153], v[238:241], v[10:13]
	s_nop 0
	v_mfma_i32_16x16x64_i8 v[10:13], v[146:149], v[242:245], v[10:13]
	s_setprio 0
	s_setprio 1
	v_mfma_i32_16x16x64_i8 v[70:73], v[62:65], v[170:173], v[70:73]
	s_nop 0
	v_mfma_i32_16x16x64_i8 v[70:73], v[58:61], v[174:177], v[70:73]
	v_mfma_i32_16x16x64_i8 v[66:69], v[54:57], v[170:173], v[66:69]
	s_nop 0
	v_mfma_i32_16x16x64_i8 v[66:69], v[50:53], v[174:177], v[66:69]
	v_mfma_i32_16x16x64_i8 v[38:41], v[62:65], v[178:181], v[38:41]
	s_nop 0
	v_mfma_i32_16x16x64_i8 v[38:41], v[58:61], v[182:185], v[38:41]
	v_mfma_i32_16x16x64_i8 v[34:37], v[54:57], v[178:181], v[34:37]
	s_nop 0
	v_mfma_i32_16x16x64_i8 v[34:37], v[50:53], v[182:185], v[34:37]
	v_mfma_i32_16x16x64_i8 v[22:25], v[62:65], v[186:189], v[22:25]
	s_nop 0
	v_mfma_i32_16x16x64_i8 v[22:25], v[58:61], v[190:193], v[22:25]
	v_mfma_i32_16x16x64_i8 v[18:21], v[54:57], v[186:189], v[18:21]
	s_nop 0
	v_mfma_i32_16x16x64_i8 v[18:21], v[50:53], v[190:193], v[18:21]
	s_barrier
	s_setprio 2
	v_mfma_i32_16x16x64_i8 v[6:9], v[62:65], v[238:241], v[6:9]
	s_nop 0
	v_mfma_i32_16x16x64_i8 v[6:9], v[58:61], v[242:245], v[6:9]
	v_mfma_i32_16x16x64_i8 v[2:5], v[54:57], v[238:241], v[2:5]
	s_nop 0
	v_mfma_i32_16x16x64_i8 v[2:5], v[50:53], v[242:245], v[2:5]
	s_setprio 0
	ds_read_b128 v[50:53], v235
	ds_read_b128 v[54:57], v235 offset:1024
	ds_read_b128 v[58:61], v235 offset:2048
	ds_read_b128 v[62:65], v235 offset:3072
	ds_read_b128 v[146:149], v236
	ds_read_b128 v[150:153], v236 offset:1024
	ds_read_b128 v[154:157], v236 offset:2048
	ds_read_b128 v[158:161], v236 offset:3072
	s_add_u32 s40, s40, 0x80000
	s_addc_u32 s41, s41, 0
	s_mov_b32 m0, s43
	v_lshl_add_u64 v[246:247], s[40:41], 0, v[194:195]
	ds_read_b128 v[170:173], v226 offset:32768
	ds_read_b128 v[174:177], v226 offset:33792
	ds_read_b128 v[178:181], v226 offset:34816
	ds_read_b128 v[182:185], v226 offset:35840
	ds_read_b128 v[186:189], v226 offset:36864
	ds_read_b128 v[190:193], v226 offset:37888
	ds_read_b128 v[238:241], v226 offset:38912
	ds_read_b128 v[242:245], v226 offset:39936
	global_load_lds_dwordx4 v[246:247], off
	v_lshl_add_u64 v[246:247], s[40:41], 0, v[204:205]
	s_mov_b32 m0, s44
	s_nop 0
	global_load_lds_dwordx4 v[246:247], off
	s_waitcnt vmcnt(8)
	s_waitcnt lgkmcnt(0)
	s_barrier
	s_setprio 1
	s_waitcnt lgkmcnt(0)
	v_mfma_i32_16x16x64_i8 v[142:145], v[50:53], v[170:173], v[142:145]
	s_nop 0
	v_mfma_i32_16x16x64_i8 v[142:145], v[54:57], v[174:177], v[142:145]
	v_mfma_i32_16x16x64_i8 v[138:141], v[58:61], v[170:173], v[138:141]
	s_nop 0
	v_mfma_i32_16x16x64_i8 v[138:141], v[62:65], v[174:177], v[138:141]
	v_mfma_i32_16x16x64_i8 v[126:129], v[50:53], v[178:181], v[126:129]
	s_nop 0
	v_mfma_i32_16x16x64_i8 v[126:129], v[54:57], v[182:185], v[126:129]
	v_mfma_i32_16x16x64_i8 v[122:125], v[58:61], v[178:181], v[122:125]
	s_nop 0
	v_mfma_i32_16x16x64_i8 v[122:125], v[62:65], v[182:185], v[122:125]
	v_mfma_i32_16x16x64_i8 v[110:113], v[50:53], v[186:189], v[110:113]
	s_nop 0
	v_mfma_i32_16x16x64_i8 v[110:113], v[54:57], v[190:193], v[110:113]
	v_mfma_i32_16x16x64_i8 v[106:109], v[58:61], v[186:189], v[106:109]
	s_nop 0
	v_mfma_i32_16x16x64_i8 v[106:109], v[62:65], v[190:193], v[106:109]
	v_mfma_i32_16x16x64_i8 v[94:97], v[50:53], v[238:241], v[94:97]
	s_nop 0
	v_mfma_i32_16x16x64_i8 v[94:97], v[54:57], v[242:245], v[94:97]
	v_mfma_i32_16x16x64_i8 v[90:93], v[58:61], v[238:241], v[90:93]
	s_nop 0
	v_mfma_i32_16x16x64_i8 v[90:93], v[62:65], v[242:245], v[90:93]
	s_setprio 0
	s_setprio 1
	v_mfma_i32_16x16x64_i8 v[134:137], v[146:149], v[170:173], v[134:137]
	s_nop 0
	v_mfma_i32_16x16x64_i8 v[134:137], v[150:153], v[174:177], v[134:137]
	v_mfma_i32_16x16x64_i8 v[130:133], v[154:157], v[170:173], v[130:133]
	s_nop 0
	v_mfma_i32_16x16x64_i8 v[130:133], v[158:161], v[174:177], v[130:133]
	v_mfma_i32_16x16x64_i8 v[118:121], v[146:149], v[178:181], v[118:121]
	s_nop 0
	v_mfma_i32_16x16x64_i8 v[118:121], v[150:153], v[182:185], v[118:121]
	v_mfma_i32_16x16x64_i8 v[114:117], v[154:157], v[178:181], v[114:117]
	s_nop 0
	v_mfma_i32_16x16x64_i8 v[114:117], v[158:161], v[182:185], v[114:117]
	v_mfma_i32_16x16x64_i8 v[102:105], v[146:149], v[186:189], v[102:105]
	s_nop 0
	v_mfma_i32_16x16x64_i8 v[102:105], v[150:153], v[190:193], v[102:105]
	v_mfma_i32_16x16x64_i8 v[98:101], v[154:157], v[186:189], v[98:101]
	s_nop 0
	v_mfma_i32_16x16x64_i8 v[98:101], v[158:161], v[190:193], v[98:101]
	s_barrier
	s_setprio 2
	v_mfma_i32_16x16x64_i8 v[86:89], v[146:149], v[238:241], v[86:89]
	s_nop 0
	v_mfma_i32_16x16x64_i8 v[86:89], v[150:153], v[242:245], v[86:89]
	v_mfma_i32_16x16x64_i8 v[82:85], v[154:157], v[238:241], v[82:85]
	s_nop 0
	v_mfma_i32_16x16x64_i8 v[82:85], v[158:161], v[242:245], v[82:85]
	s_setprio 0
	s_mov_b32 m0, s72
	v_lshl_add_u64 v[162:163], v[162:163], 0, s[6:7]
	s_add_u32 s36, s36, 0x80080
	ds_read_b128 v[170:173], v226 offset:49152
	ds_read_b128 v[174:177], v226 offset:50176
	ds_read_b128 v[178:181], v226 offset:51200
	ds_read_b128 v[182:185], v226 offset:52224
	ds_read_b128 v[186:189], v226 offset:53248
	ds_read_b128 v[190:193], v226 offset:54272
	ds_read_b128 v[238:241], v226 offset:55296
	ds_read_b128 v[242:245], v226 offset:56320
	global_load_lds_dwordx4 v[162:163], off
	v_lshl_add_u64 v[162:163], v[164:165], 0, s[6:7]
	s_mov_b32 m0, s73
	s_addc_u32 s37, s37, 0
	global_load_lds_dwordx4 v[162:163], off
	v_lshl_add_u64 v[162:163], s[36:37], 0, v[202:203]
	s_mov_b32 m0, s74
	s_nop 0
	global_load_lds_dwordx4 v[162:163], off
	v_lshl_add_u64 v[162:163], s[36:37], 0, v[206:207]
	s_mov_b32 m0, s75
	s_nop 0
	global_load_lds_dwordx4 v[162:163], off
	v_lshl_add_u64 v[162:163], v[166:167], 0, s[6:7]
	s_mov_b32 m0, s51
	s_nop 0
	global_load_lds_dwordx4 v[162:163], off
	v_lshl_add_u64 v[162:163], v[168:169], 0, s[6:7]
	s_mov_b32 m0, s53
	s_nop 0
	global_load_lds_dwordx4 v[162:163], off
	s_waitcnt vmcnt(8)
	s_waitcnt lgkmcnt(0)
	s_barrier
	s_setprio 1
	s_waitcnt lgkmcnt(0)
	v_mfma_i32_16x16x64_i8 v[78:81], v[50:53], v[170:173], v[78:81]
	s_nop 0
	v_mfma_i32_16x16x64_i8 v[78:81], v[54:57], v[174:177], v[78:81]
	v_mfma_i32_16x16x64_i8 v[74:77], v[58:61], v[170:173], v[74:77]
	s_nop 0
	v_mfma_i32_16x16x64_i8 v[74:77], v[62:65], v[174:177], v[74:77]
	v_mfma_i32_16x16x64_i8 v[46:49], v[50:53], v[178:181], v[46:49]
	s_nop 0
	v_mfma_i32_16x16x64_i8 v[46:49], v[54:57], v[182:185], v[46:49]
	v_mfma_i32_16x16x64_i8 v[42:45], v[58:61], v[178:181], v[42:45]
	s_nop 0
	v_mfma_i32_16x16x64_i8 v[42:45], v[62:65], v[182:185], v[42:45]
	v_mfma_i32_16x16x64_i8 v[30:33], v[50:53], v[186:189], v[30:33]
	s_nop 0
	v_mfma_i32_16x16x64_i8 v[30:33], v[54:57], v[190:193], v[30:33]
	v_mfma_i32_16x16x64_i8 v[26:29], v[58:61], v[186:189], v[26:29]
	s_nop 0
	v_mfma_i32_16x16x64_i8 v[26:29], v[62:65], v[190:193], v[26:29]
	v_mfma_i32_16x16x64_i8 v[14:17], v[50:53], v[238:241], v[14:17]
	s_nop 0
	v_mfma_i32_16x16x64_i8 v[14:17], v[54:57], v[242:245], v[14:17]
	v_mfma_i32_16x16x64_i8 v[10:13], v[58:61], v[238:241], v[10:13]
	s_nop 0
	v_mfma_i32_16x16x64_i8 v[10:13], v[62:65], v[242:245], v[10:13]
	s_setprio 0
	s_setprio 1
	v_mfma_i32_16x16x64_i8 v[70:73], v[146:149], v[170:173], v[70:73]
	s_nop 0
	v_mfma_i32_16x16x64_i8 v[70:73], v[150:153], v[174:177], v[70:73]
	v_mfma_i32_16x16x64_i8 v[66:69], v[154:157], v[170:173], v[66:69]
	s_nop 0
	v_mfma_i32_16x16x64_i8 v[66:69], v[158:161], v[174:177], v[66:69]
	v_mfma_i32_16x16x64_i8 v[38:41], v[146:149], v[178:181], v[38:41]
	s_nop 0
	v_mfma_i32_16x16x64_i8 v[38:41], v[150:153], v[182:185], v[38:41]
	v_mfma_i32_16x16x64_i8 v[34:37], v[154:157], v[178:181], v[34:37]
	s_nop 0
	v_mfma_i32_16x16x64_i8 v[34:37], v[158:161], v[182:185], v[34:37]
	v_mfma_i32_16x16x64_i8 v[22:25], v[146:149], v[186:189], v[22:25]
	s_nop 0
	v_mfma_i32_16x16x64_i8 v[22:25], v[150:153], v[190:193], v[22:25]
	v_mfma_i32_16x16x64_i8 v[18:21], v[154:157], v[186:189], v[18:21]
	s_nop 0
	v_mfma_i32_16x16x64_i8 v[18:21], v[158:161], v[190:193], v[18:21]
	s_barrier
	s_setprio 2
	v_mfma_i32_16x16x64_i8 v[6:9], v[146:149], v[238:241], v[6:9]
	s_nop 0
	v_mfma_i32_16x16x64_i8 v[6:9], v[150:153], v[242:245], v[6:9]
	v_mfma_i32_16x16x64_i8 v[2:5], v[154:157], v[238:241], v[2:5]
	s_nop 0
	v_mfma_i32_16x16x64_i8 v[2:5], v[158:161], v[242:245], v[2:5]
	s_setprio 0
	s_add_i32 s33, s33, 2
	s_add_u32 s38, s38, 0x100
	s_addc_u32 s39, s39, 0
	s_add_u32 s25, s25, 0x100
	s_addc_u32 s29, s29, 0
	s_cmp_gt_u32 s33, 29
	s_cbranch_scc0 .LBB0_740
	s_nop 15
	s_nop 15
	s_and_b64 vcc, exec, s[8:9]
	s_cbranch_vccz .LBB0_743
	s_barrier

.LBB0_746:
	ds_read_b128 v[158:161], v227
	ds_read_b128 v[154:157], v227 offset:1024
	ds_read_b128 v[150:153], v227 offset:2048
	ds_read_b128 v[146:149], v227 offset:3072
	ds_read_b128 v[142:145], v233
	ds_read_b128 v[138:141], v233 offset:1024
	ds_read_b128 v[134:137], v233 offset:2048
	ds_read_b128 v[130:133], v233 offset:3072
	s_add_u32 s38, s29, s36
	s_addc_u32 s39, s33, s37
	s_add_u32 s38, s38, 0x3d000100
	s_addc_u32 s39, s39, 0
	s_add_u32 s81, s25, s36
	s_addc_u32 s82, s79, s37
	s_cmpk_eq_i32 s36, 0x700
	s_cselect_b32 s41, s1, s39
	s_cselect_b32 s40, s0, s38
	s_cselect_b32 s39, s15, s82
	s_cselect_b32 s38, s14, s81
	s_mov_b32 m0, s66
	v_lshl_add_u64 v[242:243], v[162:163], 0, s[36:37]
	ds_read_b128 v[166:169], v226
	ds_read_b128 v[170:173], v226 offset:1024
	ds_read_b128 v[174:177], v226 offset:2048
	ds_read_b128 v[178:181], v226 offset:3072
	ds_read_b128 v[182:185], v226 offset:4096
	ds_read_b128 v[186:189], v226 offset:5120
	ds_read_b128 v[190:193], v226 offset:6144
	ds_read_b128 v[238:241], v226 offset:7168
	global_load_lds_dwordx4 v[242:243], off
	v_lshl_add_u64 v[242:243], v[164:165], 0, s[36:37]
	s_mov_b32 m0, s67
	s_nop 0
	global_load_lds_dwordx4 v[242:243], off
	s_waitcnt vmcnt(8)
	s_waitcnt lgkmcnt(0)
	s_barrier
	s_setprio 1
	s_waitcnt lgkmcnt(0)
	v_mfma_i32_16x16x64_i8 v[30:33], v[158:161], v[166:169], v[30:33]
	s_nop 0
	v_mfma_i32_16x16x64_i8 v[30:33], v[154:157], v[170:173], v[30:33]
	v_mfma_i32_16x16x64_i8 v[26:29], v[150:153], v[166:169], v[26:29]
	s_nop 0
	v_mfma_i32_16x16x64_i8 v[26:29], v[146:149], v[170:173], v[26:29]
	v_mfma_i32_16x16x64_i8 v[46:49], v[158:161], v[174:177], v[46:49]
	s_nop 0
	v_mfma_i32_16x16x64_i8 v[46:49], v[154:157], v[178:181], v[46:49]
	v_mfma_i32_16x16x64_i8 v[42:45], v[150:153], v[174:177], v[42:45]
	s_nop 0
	v_mfma_i32_16x16x64_i8 v[42:45], v[146:149], v[178:181], v[42:45]
	v_mfma_i32_16x16x64_i8 v[74:77], v[158:161], v[182:185], v[74:77]
	s_nop 0
	v_mfma_i32_16x16x64_i8 v[74:77], v[154:157], v[186:189], v[74:77]
	v_mfma_i32_16x16x64_i8 v[70:73], v[150:153], v[182:185], v[70:73]
	s_nop 0
	v_mfma_i32_16x16x64_i8 v[70:73], v[146:149], v[186:189], v[70:73]
	v_mfma_i32_16x16x64_i8 v[94:97], v[158:161], v[190:193], v[94:97]
	s_nop 0
	v_mfma_i32_16x16x64_i8 v[94:97], v[154:157], v[238:241], v[94:97]
	v_mfma_i32_16x16x64_i8 v[90:93], v[150:153], v[190:193], v[90:93]
	s_nop 0
	v_mfma_i32_16x16x64_i8 v[90:93], v[146:149], v[238:241], v[90:93]
	s_setprio 0
	s_setprio 1
	v_mfma_i32_16x16x64_i8 v[38:41], v[142:145], v[166:169], v[38:41]
	s_nop 0
	v_mfma_i32_16x16x64_i8 v[38:41], v[138:141], v[170:173], v[38:41]
	v_mfma_i32_16x16x64_i8 v[34:37], v[134:137], v[166:169], v[34:37]
	s_nop 0
	v_mfma_i32_16x16x64_i8 v[34:37], v[130:133], v[170:173], v[34:37]
	v_mfma_i32_16x16x64_i8 v[58:61], v[142:145], v[174:177], v[58:61]
	s_nop 0
	v_mfma_i32_16x16x64_i8 v[58:61], v[138:141], v[178:181], v[58:61]
	v_mfma_i32_16x16x64_i8 v[54:57], v[134:137], v[174:177], v[54:57]
	s_nop 0
	v_mfma_i32_16x16x64_i8 v[54:57], v[130:133], v[178:181], v[54:57]
	v_mfma_i32_16x16x64_i8 v[86:89], v[142:145], v[182:185], v[86:89]
	s_nop 0
	v_mfma_i32_16x16x64_i8 v[86:89], v[138:141], v[186:189], v[86:89]
	v_mfma_i32_16x16x64_i8 v[82:85], v[134:137], v[182:185], v[82:85]
	s_nop 0
	v_mfma_i32_16x16x64_i8 v[82:85], v[130:133], v[186:189], v[82:85]
	s_barrier
	s_setprio 2
	v_mfma_i32_16x16x64_i8 v[102:105], v[142:145], v[190:193], v[102:105]
	s_nop 0
	v_mfma_i32_16x16x64_i8 v[102:105], v[138:141], v[238:241], v[102:105]
	v_mfma_i32_16x16x64_i8 v[98:101], v[134:137], v[190:193], v[98:101]
	s_nop 0
	v_mfma_i32_16x16x64_i8 v[98:101], v[130:133], v[238:241], v[98:101]
	s_setprio 0
	s_mov_b32 m0, s68
	v_lshl_add_u64 v[166:167], s[38:39], 0, v[202:203]
	s_add_u32 s82, s38, 0x80000
	ds_read_b128 v[174:177], v226 offset:16384
	ds_read_b128 v[178:181], v226 offset:17408
	ds_read_b128 v[182:185], v226 offset:18432
	ds_read_b128 v[186:189], v226 offset:19456
	ds_read_b128 v[190:193], v226 offset:20480
	ds_read_b128 v[238:241], v226 offset:21504
	ds_read_b128 v[242:245], v226 offset:22528
	ds_read_b128 v[246:249], v226 offset:23552
	global_load_lds_dwordx4 v[166:167], off
	v_lshl_add_u64 v[168:169], s[38:39], 0, v[206:207]
	s_mov_b32 m0, s69
	s_addc_u32 s83, s39, 0
	global_load_lds_dwordx4 v[168:169], off
	v_lshl_add_u64 v[170:171], s[82:83], 0, v[202:203]
	s_mov_b32 m0, s70
	v_lshl_add_u64 v[172:173], s[40:41], 0, v[204:205]
	global_load_lds_dwordx4 v[170:171], off
	v_lshl_add_u64 v[170:171], s[82:83], 0, v[206:207]
	s_mov_b32 m0, s71
	s_nop 0
	global_load_lds_dwordx4 v[170:171], off
	v_lshl_add_u64 v[170:171], s[40:41], 0, v[194:195]
	s_mov_b32 m0, s23
	s_nop 0
	global_load_lds_dwordx4 v[170:171], off
	s_mov_b32 m0, s42
	s_nop 0
	global_load_lds_dwordx4 v[172:173], off
	s_waitcnt vmcnt(8)
	s_waitcnt lgkmcnt(0)
	s_barrier
	s_setprio 1
	s_waitcnt lgkmcnt(0)
	v_mfma_i32_16x16x64_i8 v[110:113], v[158:161], v[174:177], v[110:113]
	s_nop 0
	v_mfma_i32_16x16x64_i8 v[110:113], v[154:157], v[178:181], v[110:113]
	v_mfma_i32_16x16x64_i8 v[106:109], v[150:153], v[174:177], v[106:109]
	s_nop 0
	v_mfma_i32_16x16x64_i8 v[106:109], v[146:149], v[178:181], v[106:109]
	v_mfma_i32_16x16x64_i8 v[126:129], v[158:161], v[182:185], v[126:129]
	s_nop 0
	v_mfma_i32_16x16x64_i8 v[126:129], v[154:157], v[186:189], v[126:129]
	v_mfma_i32_16x16x64_i8 v[118:121], v[150:153], v[182:185], v[118:121]
	s_nop 0
	v_mfma_i32_16x16x64_i8 v[118:121], v[146:149], v[186:189], v[118:121]
	v_mfma_i32_16x16x64_i8 v[62:65], v[158:161], v[190:193], v[62:65]
	s_nop 0
	v_mfma_i32_16x16x64_i8 v[62:65], v[154:157], v[238:241], v[62:65]
	v_mfma_i32_16x16x64_i8 v[50:53], v[150:153], v[190:193], v[50:53]
	s_nop 0
	v_mfma_i32_16x16x64_i8 v[50:53], v[146:149], v[238:241], v[50:53]
	v_mfma_i32_16x16x64_i8 v[14:17], v[158:161], v[242:245], v[14:17]
	s_nop 0
	v_mfma_i32_16x16x64_i8 v[14:17], v[154:157], v[246:249], v[14:17]
	v_mfma_i32_16x16x64_i8 v[10:13], v[150:153], v[242:245], v[10:13]
	s_nop 0
	v_mfma_i32_16x16x64_i8 v[10:13], v[146:149], v[246:249], v[10:13]
	s_setprio 0
	s_setprio 1
	v_mfma_i32_16x16x64_i8 v[122:125], v[142:145], v[174:177], v[122:125]
	s_nop 0
	v_mfma_i32_16x16x64_i8 v[122:125], v[138:141], v[178:181], v[122:125]
	v_mfma_i32_16x16x64_i8 v[114:117], v[134:137], v[174:177], v[114:117]
	s_nop 0
	v_mfma_i32_16x16x64_i8 v[114:117], v[130:133], v[178:181], v[114:117]
	v_mfma_i32_16x16x64_i8 v[78:81], v[142:145], v[182:185], v[78:81]
	s_nop 0
	v_mfma_i32_16x16x64_i8 v[78:81], v[138:141], v[186:189], v[78:81]
	v_mfma_i32_16x16x64_i8 v[66:69], v[134:137], v[182:185], v[66:69]
	s_nop 0
	v_mfma_i32_16x16x64_i8 v[66:69], v[130:133], v[186:189], v[66:69]
	v_mfma_i32_16x16x64_i8 v[22:25], v[142:145], v[190:193], v[22:25]
	s_nop 0
	v_mfma_i32_16x16x64_i8 v[22:25], v[138:141], v[238:241], v[22:25]
	v_mfma_i32_16x16x64_i8 v[18:21], v[134:137], v[190:193], v[18:21]
	s_nop 0
	v_mfma_i32_16x16x64_i8 v[18:21], v[130:133], v[238:241], v[18:21]
	s_barrier
	s_setprio 2
	v_mfma_i32_16x16x64_i8 v[6:9], v[142:145], v[242:245], v[6:9]
	s_nop 0
	v_mfma_i32_16x16x64_i8 v[6:9], v[138:141], v[246:249], v[6:9]
	v_mfma_i32_16x16x64_i8 v[2:5], v[134:137], v[242:245], v[2:5]
	s_nop 0
	v_mfma_i32_16x16x64_i8 v[2:5], v[130:133], v[246:249], v[2:5]
	s_setprio 0
	ds_read_b128 v[130:133], v235
	ds_read_b128 v[134:137], v235 offset:1024
	ds_read_b128 v[138:141], v235 offset:2048
	ds_read_b128 v[142:145], v235 offset:3072
	ds_read_b128 v[146:149], v236
	ds_read_b128 v[150:153], v236 offset:1024
	ds_read_b128 v[154:157], v236 offset:2048
	ds_read_b128 v[158:161], v236 offset:3072
	s_add_u32 s40, s40, 0x80000
	s_addc_u32 s41, s41, 0
	s_mov_b32 m0, s43
	v_lshl_add_u64 v[250:251], s[40:41], 0, v[194:195]
	ds_read_b128 v[174:177], v226 offset:32768
	ds_read_b128 v[178:181], v226 offset:33792
	ds_read_b128 v[182:185], v226 offset:34816
	ds_read_b128 v[186:189], v226 offset:35840
	ds_read_b128 v[190:193], v226 offset:36864
	ds_read_b128 v[238:241], v226 offset:37888
	ds_read_b128 v[242:245], v226 offset:38912
	ds_read_b128 v[246:249], v226 offset:39936
	global_load_lds_dwordx4 v[250:251], off
	v_lshl_add_u64 v[250:251], s[40:41], 0, v[204:205]
	s_mov_b32 m0, s44
	s_nop 0
	global_load_lds_dwordx4 v[250:251], off
	s_waitcnt vmcnt(8)
	s_waitcnt lgkmcnt(0)
	s_barrier
	s_setprio 1
	s_waitcnt lgkmcnt(0)
	v_mfma_i32_16x16x64_i8 v[30:33], v[130:133], v[174:177], v[30:33]
	s_nop 0
	v_mfma_i32_16x16x64_i8 v[30:33], v[134:137], v[178:181], v[30:33]
	v_mfma_i32_16x16x64_i8 v[26:29], v[138:141], v[174:177], v[26:29]
	s_nop 0
	v_mfma_i32_16x16x64_i8 v[26:29], v[142:145], v[178:181], v[26:29]
	v_mfma_i32_16x16x64_i8 v[46:49], v[130:133], v[182:185], v[46:49]
	s_nop 0
	v_mfma_i32_16x16x64_i8 v[46:49], v[134:137], v[186:189], v[46:49]
	v_mfma_i32_16x16x64_i8 v[42:45], v[138:141], v[182:185], v[42:45]
	s_nop 0
	v_mfma_i32_16x16x64_i8 v[42:45], v[142:145], v[186:189], v[42:45]
	v_mfma_i32_16x16x64_i8 v[74:77], v[130:133], v[190:193], v[74:77]
	s_nop 0
	v_mfma_i32_16x16x64_i8 v[74:77], v[134:137], v[238:241], v[74:77]
	v_mfma_i32_16x16x64_i8 v[70:73], v[138:141], v[190:193], v[70:73]
	s_nop 0
	v_mfma_i32_16x16x64_i8 v[70:73], v[142:145], v[238:241], v[70:73]
	v_mfma_i32_16x16x64_i8 v[94:97], v[130:133], v[242:245], v[94:97]
	s_nop 0
	v_mfma_i32_16x16x64_i8 v[94:97], v[134:137], v[246:249], v[94:97]
	v_mfma_i32_16x16x64_i8 v[90:93], v[138:141], v[242:245], v[90:93]
	s_nop 0
	v_mfma_i32_16x16x64_i8 v[90:93], v[142:145], v[246:249], v[90:93]
	s_setprio 0
	s_setprio 1
	v_mfma_i32_16x16x64_i8 v[38:41], v[146:149], v[174:177], v[38:41]
	s_nop 0
	v_mfma_i32_16x16x64_i8 v[38:41], v[150:153], v[178:181], v[38:41]
	v_mfma_i32_16x16x64_i8 v[34:37], v[154:157], v[174:177], v[34:37]
	s_nop 0
	v_mfma_i32_16x16x64_i8 v[34:37], v[158:161], v[178:181], v[34:37]
	v_mfma_i32_16x16x64_i8 v[58:61], v[146:149], v[182:185], v[58:61]
	s_nop 0
	v_mfma_i32_16x16x64_i8 v[58:61], v[150:153], v[186:189], v[58:61]
	v_mfma_i32_16x16x64_i8 v[54:57], v[154:157], v[182:185], v[54:57]
	s_nop 0
	v_mfma_i32_16x16x64_i8 v[54:57], v[158:161], v[186:189], v[54:57]
	v_mfma_i32_16x16x64_i8 v[86:89], v[146:149], v[190:193], v[86:89]
	s_nop 0
	v_mfma_i32_16x16x64_i8 v[86:89], v[150:153], v[238:241], v[86:89]
	v_mfma_i32_16x16x64_i8 v[82:85], v[154:157], v[190:193], v[82:85]
	s_nop 0
	v_mfma_i32_16x16x64_i8 v[82:85], v[158:161], v[238:241], v[82:85]
	s_barrier
	s_setprio 2
	v_mfma_i32_16x16x64_i8 v[102:105], v[146:149], v[242:245], v[102:105]
	s_nop 0
	v_mfma_i32_16x16x64_i8 v[102:105], v[150:153], v[246:249], v[102:105]
	v_mfma_i32_16x16x64_i8 v[98:101], v[154:157], v[242:245], v[98:101]
	s_nop 0
	v_mfma_i32_16x16x64_i8 v[98:101], v[158:161], v[246:249], v[98:101]
	s_setprio 0
	s_mov_b32 m0, s72
	v_lshl_add_u64 v[166:167], v[166:167], 0, s[6:7]
	s_add_u32 s38, s38, 0x80080
	ds_read_b128 v[174:177], v226 offset:49152
	ds_read_b128 v[178:181], v226 offset:50176
	ds_read_b128 v[182:185], v226 offset:51200
	ds_read_b128 v[186:189], v226 offset:52224
	ds_read_b128 v[190:193], v226 offset:53248
	ds_read_b128 v[238:241], v226 offset:54272
	ds_read_b128 v[242:245], v226 offset:55296
	ds_read_b128 v[246:249], v226 offset:56320
	global_load_lds_dwordx4 v[166:167], off
	v_lshl_add_u64 v[166:167], v[168:169], 0, s[6:7]
	s_mov_b32 m0, s73
	s_addc_u32 s39, s39, 0
	global_load_lds_dwordx4 v[166:167], off
	v_lshl_add_u64 v[166:167], s[38:39], 0, v[202:203]
	s_mov_b32 m0, s74
	s_nop 0
	global_load_lds_dwordx4 v[166:167], off
	v_lshl_add_u64 v[166:167], s[38:39], 0, v[206:207]
	s_mov_b32 m0, s75
	s_nop 0
	global_load_lds_dwordx4 v[166:167], off
	v_lshl_add_u64 v[166:167], v[170:171], 0, s[6:7]
	s_mov_b32 m0, s51
	s_nop 0
	global_load_lds_dwordx4 v[166:167], off
	v_lshl_add_u64 v[166:167], v[172:173], 0, s[6:7]
	s_mov_b32 m0, s53
	s_nop 0
	global_load_lds_dwordx4 v[166:167], off
	s_waitcnt vmcnt(8)
	s_waitcnt lgkmcnt(0)
	s_barrier
	s_setprio 1
	s_waitcnt lgkmcnt(0)
	v_mfma_i32_16x16x64_i8 v[110:113], v[130:133], v[174:177], v[110:113]
	s_nop 0
	v_mfma_i32_16x16x64_i8 v[110:113], v[134:137], v[178:181], v[110:113]
	v_mfma_i32_16x16x64_i8 v[106:109], v[138:141], v[174:177], v[106:109]
	s_nop 0
	v_mfma_i32_16x16x64_i8 v[106:109], v[142:145], v[178:181], v[106:109]
	v_mfma_i32_16x16x64_i8 v[126:129], v[130:133], v[182:185], v[126:129]
	s_nop 0
	v_mfma_i32_16x16x64_i8 v[126:129], v[134:137], v[186:189], v[126:129]
	v_mfma_i32_16x16x64_i8 v[118:121], v[138:141], v[182:185], v[118:121]
	s_nop 0
	v_mfma_i32_16x16x64_i8 v[118:121], v[142:145], v[186:189], v[118:121]
	v_mfma_i32_16x16x64_i8 v[62:65], v[130:133], v[190:193], v[62:65]
	s_nop 0
	v_mfma_i32_16x16x64_i8 v[62:65], v[134:137], v[238:241], v[62:65]
	v_mfma_i32_16x16x64_i8 v[50:53], v[138:141], v[190:193], v[50:53]
	s_nop 0
	v_mfma_i32_16x16x64_i8 v[50:53], v[142:145], v[238:241], v[50:53]
	v_mfma_i32_16x16x64_i8 v[14:17], v[130:133], v[242:245], v[14:17]
	s_nop 0
	v_mfma_i32_16x16x64_i8 v[14:17], v[134:137], v[246:249], v[14:17]
	v_mfma_i32_16x16x64_i8 v[10:13], v[138:141], v[242:245], v[10:13]
	s_nop 0
	v_mfma_i32_16x16x64_i8 v[10:13], v[142:145], v[246:249], v[10:13]
	s_setprio 0
	s_setprio 1
	v_mfma_i32_16x16x64_i8 v[122:125], v[146:149], v[174:177], v[122:125]
	s_nop 0
	v_mfma_i32_16x16x64_i8 v[122:125], v[150:153], v[178:181], v[122:125]
	v_mfma_i32_16x16x64_i8 v[114:117], v[154:157], v[174:177], v[114:117]
	s_nop 0
	v_mfma_i32_16x16x64_i8 v[114:117], v[158:161], v[178:181], v[114:117]
	v_mfma_i32_16x16x64_i8 v[78:81], v[146:149], v[182:185], v[78:81]
	s_nop 0
	v_mfma_i32_16x16x64_i8 v[78:81], v[150:153], v[186:189], v[78:81]
	v_mfma_i32_16x16x64_i8 v[66:69], v[154:157], v[182:185], v[66:69]
	s_nop 0
	v_mfma_i32_16x16x64_i8 v[66:69], v[158:161], v[186:189], v[66:69]
	v_mfma_i32_16x16x64_i8 v[22:25], v[146:149], v[190:193], v[22:25]
	s_nop 0
	v_mfma_i32_16x16x64_i8 v[22:25], v[150:153], v[238:241], v[22:25]
	v_mfma_i32_16x16x64_i8 v[18:21], v[154:157], v[190:193], v[18:21]
	s_nop 0
	v_mfma_i32_16x16x64_i8 v[18:21], v[158:161], v[238:241], v[18:21]
	s_barrier
	s_setprio 2
	v_mfma_i32_16x16x64_i8 v[6:9], v[146:149], v[242:245], v[6:9]
	s_nop 0
	v_mfma_i32_16x16x64_i8 v[6:9], v[150:153], v[246:249], v[6:9]
	v_mfma_i32_16x16x64_i8 v[2:5], v[154:157], v[242:245], v[2:5]
	s_nop 0
	v_mfma_i32_16x16x64_i8 v[2:5], v[158:161], v[246:249], v[2:5]
	s_setprio 0
	s_add_i32 s80, s80, 2
	s_add_u32 s36, s36, 0x100
	s_addc_u32 s37, s37, 0
	s_cmp_gt_u32 s80, 13
	s_cbranch_scc0 .LBB0_746
	s_nop 15
	s_nop 15
	s_and_b64 vcc, exec, s[8:9]
	s_cbranch_vccz .LBB0_749
	s_barrier

.LBB0_752:
	ds_read_b128 v[134:137], v227
	ds_read_b128 v[138:141], v227 offset:1024
	ds_read_b128 v[142:145], v227 offset:2048
	ds_read_b128 v[146:149], v227 offset:3072
	ds_read_b128 v[150:153], v233
	ds_read_b128 v[154:157], v233 offset:1024
	ds_read_b128 v[158:161], v233 offset:2048
	ds_read_b128 v[162:165], v233 offset:3072
	s_add_u32 s30, s29, s2
	s_addc_u32 s31, s33, s3
	s_add_u32 s30, s30, 0x200100
	s_addc_u32 s31, s31, 0
	s_add_u32 s77, s25, s2
	s_addc_u32 s78, s40, s3
	s_cmpk_eq_i32 s2, 0xf00
	s_cselect_b32 s35, s0, s31
	s_cselect_b32 s34, s1, s30
	s_cselect_b32 s31, s14, s78
	s_cselect_b32 s30, s15, s77
	s_mov_b32 m0, s66
	v_lshl_add_u64 v[242:243], v[130:131], 0, s[2:3]
	ds_read_b128 v[166:169], v226
	ds_read_b128 v[170:173], v226 offset:1024
	ds_read_b128 v[174:177], v226 offset:2048
	ds_read_b128 v[178:181], v226 offset:3072
	ds_read_b128 v[182:185], v226 offset:4096
	ds_read_b128 v[186:189], v226 offset:5120
	ds_read_b128 v[190:193], v226 offset:6144
	ds_read_b128 v[238:241], v226 offset:7168
	global_load_lds_dwordx4 v[242:243], off
	v_lshl_add_u64 v[242:243], v[132:133], 0, s[2:3]
	s_mov_b32 m0, s67
	s_nop 0
	global_load_lds_dwordx4 v[242:243], off
	s_waitcnt vmcnt(8)
	s_waitcnt lgkmcnt(0)
	s_barrier
	s_setprio 1
	s_waitcnt lgkmcnt(0)
	v_mfma_f32_16x16x32_bf16 v[26:29], v[134:137], v[166:169], v[26:29]
	v_mfma_f32_16x16x32_bf16 v[30:33], v[142:145], v[166:169], v[30:33]
	v_mfma_f32_16x16x32_bf16 v[42:45], v[134:137], v[174:177], v[42:45]
	v_mfma_f32_16x16x32_bf16 v[46:49], v[142:145], v[174:177], v[46:49]
	v_mfma_f32_16x16x32_bf16 v[70:73], v[134:137], v[182:185], v[70:73]
	v_mfma_f32_16x16x32_bf16 v[74:77], v[142:145], v[182:185], v[74:77]
	v_mfma_f32_16x16x32_bf16 v[90:93], v[134:137], v[190:193], v[90:93]
	v_mfma_f32_16x16x32_bf16 v[94:97], v[142:145], v[190:193], v[94:97]
	v_mfma_f32_16x16x32_bf16 v[26:29], v[138:141], v[170:173], v[26:29]
	v_mfma_f32_16x16x32_bf16 v[30:33], v[146:149], v[170:173], v[30:33]
	v_mfma_f32_16x16x32_bf16 v[42:45], v[138:141], v[178:181], v[42:45]
	v_mfma_f32_16x16x32_bf16 v[46:49], v[146:149], v[178:181], v[46:49]
	v_mfma_f32_16x16x32_bf16 v[70:73], v[138:141], v[186:189], v[70:73]
	v_mfma_f32_16x16x32_bf16 v[74:77], v[146:149], v[186:189], v[74:77]
	v_mfma_f32_16x16x32_bf16 v[90:93], v[138:141], v[238:241], v[90:93]
	v_mfma_f32_16x16x32_bf16 v[94:97], v[146:149], v[238:241], v[94:97]
	s_setprio 0
	s_setprio 1
	v_mfma_f32_16x16x32_bf16 v[34:37], v[150:153], v[166:169], v[34:37]
	v_mfma_f32_16x16x32_bf16 v[38:41], v[158:161], v[166:169], v[38:41]
	v_mfma_f32_16x16x32_bf16 v[54:57], v[150:153], v[174:177], v[54:57]
	v_mfma_f32_16x16x32_bf16 v[58:61], v[158:161], v[174:177], v[58:61]
	v_mfma_f32_16x16x32_bf16 v[82:85], v[150:153], v[182:185], v[82:85]
	v_mfma_f32_16x16x32_bf16 v[86:89], v[158:161], v[182:185], v[86:89]
	v_mfma_f32_16x16x32_bf16 v[98:101], v[150:153], v[190:193], v[98:101]
	v_mfma_f32_16x16x32_bf16 v[102:105], v[158:161], v[190:193], v[102:105]
	v_mfma_f32_16x16x32_bf16 v[34:37], v[154:157], v[170:173], v[34:37]
	v_mfma_f32_16x16x32_bf16 v[38:41], v[162:165], v[170:173], v[38:41]
	v_mfma_f32_16x16x32_bf16 v[54:57], v[154:157], v[178:181], v[54:57]
	v_mfma_f32_16x16x32_bf16 v[58:61], v[162:165], v[178:181], v[58:61]
	s_barrier
	s_setprio 2
	v_mfma_f32_16x16x32_bf16 v[82:85], v[154:157], v[186:189], v[82:85]
	v_mfma_f32_16x16x32_bf16 v[86:89], v[162:165], v[186:189], v[86:89]
	v_mfma_f32_16x16x32_bf16 v[98:101], v[154:157], v[238:241], v[98:101]
	v_mfma_f32_16x16x32_bf16 v[102:105], v[162:165], v[238:241], v[102:105]
	s_setprio 0
	s_mov_b32 m0, s68
	v_lshl_add_u64 v[242:243], s[30:31], 0, v[202:203]
	s_add_u32 s78, s30, 0x80000
	ds_read_b128 v[166:169], v226 offset:16384
	ds_read_b128 v[170:173], v226 offset:17408
	ds_read_b128 v[174:177], v226 offset:18432
	ds_read_b128 v[178:181], v226 offset:19456
	ds_read_b128 v[182:185], v226 offset:20480
	ds_read_b128 v[186:189], v226 offset:21504
	ds_read_b128 v[190:193], v226 offset:22528
	ds_read_b128 v[238:241], v226 offset:23552
	global_load_lds_dwordx4 v[242:243], off
	v_lshl_add_u64 v[244:245], s[30:31], 0, v[206:207]
	s_mov_b32 m0, s69
	s_addc_u32 s79, s31, 0
	global_load_lds_dwordx4 v[244:245], off
	v_lshl_add_u64 v[246:247], s[78:79], 0, v[202:203]
	s_mov_b32 m0, s70
	v_lshl_add_u64 v[248:249], s[34:35], 0, v[204:205]
	global_load_lds_dwordx4 v[246:247], off
	v_lshl_add_u64 v[246:247], s[78:79], 0, v[206:207]
	s_mov_b32 m0, s71
	s_nop 0
	global_load_lds_dwordx4 v[246:247], off
	v_lshl_add_u64 v[246:247], s[34:35], 0, v[194:195]
	s_mov_b32 m0, s23
	s_nop 0
	global_load_lds_dwordx4 v[246:247], off
	s_mov_b32 m0, s42
	s_nop 0
	global_load_lds_dwordx4 v[248:249], off
	s_waitcnt vmcnt(8)
	s_waitcnt lgkmcnt(0)
	s_barrier
	s_setprio 1
	s_waitcnt lgkmcnt(0)
	v_mfma_f32_16x16x32_bf16 v[106:109], v[134:137], v[166:169], v[106:109]
	v_mfma_f32_16x16x32_bf16 v[110:113], v[142:145], v[166:169], v[110:113]
	v_mfma_f32_16x16x32_bf16 v[118:121], v[134:137], v[174:177], v[118:121]
	v_mfma_f32_16x16x32_bf16 v[126:129], v[142:145], v[174:177], v[126:129]
	v_mfma_f32_16x16x32_bf16 v[50:53], v[134:137], v[182:185], v[50:53]
	v_mfma_f32_16x16x32_bf16 v[62:65], v[142:145], v[182:185], v[62:65]
	v_mfma_f32_16x16x32_bf16 v[10:13], v[134:137], v[190:193], v[10:13]
	v_mfma_f32_16x16x32_bf16 v[14:17], v[142:145], v[190:193], v[14:17]
	v_mfma_f32_16x16x32_bf16 v[106:109], v[138:141], v[170:173], v[106:109]
	v_mfma_f32_16x16x32_bf16 v[110:113], v[146:149], v[170:173], v[110:113]
	v_mfma_f32_16x16x32_bf16 v[118:121], v[138:141], v[178:181], v[118:121]
	v_mfma_f32_16x16x32_bf16 v[126:129], v[146:149], v[178:181], v[126:129]
	v_mfma_f32_16x16x32_bf16 v[50:53], v[138:141], v[186:189], v[50:53]
	v_mfma_f32_16x16x32_bf16 v[62:65], v[146:149], v[186:189], v[62:65]
	v_mfma_f32_16x16x32_bf16 v[10:13], v[138:141], v[238:241], v[10:13]
	v_mfma_f32_16x16x32_bf16 v[14:17], v[146:149], v[238:241], v[14:17]
	s_setprio 0
	s_setprio 1
	v_mfma_f32_16x16x32_bf16 v[114:117], v[150:153], v[166:169], v[114:117]
	v_mfma_f32_16x16x32_bf16 v[122:125], v[158:161], v[166:169], v[122:125]
	v_mfma_f32_16x16x32_bf16 v[66:69], v[150:153], v[174:177], v[66:69]
	v_mfma_f32_16x16x32_bf16 v[78:81], v[158:161], v[174:177], v[78:81]
	v_mfma_f32_16x16x32_bf16 v[18:21], v[150:153], v[182:185], v[18:21]
	v_mfma_f32_16x16x32_bf16 v[22:25], v[158:161], v[182:185], v[22:25]
	v_mfma_f32_16x16x32_bf16 v[2:5], v[150:153], v[190:193], v[2:5]
	v_mfma_f32_16x16x32_bf16 v[6:9], v[158:161], v[190:193], v[6:9]
	v_mfma_f32_16x16x32_bf16 v[114:117], v[154:157], v[170:173], v[114:117]
	v_mfma_f32_16x16x32_bf16 v[122:125], v[162:165], v[170:173], v[122:125]
	v_mfma_f32_16x16x32_bf16 v[66:69], v[154:157], v[178:181], v[66:69]
	v_mfma_f32_16x16x32_bf16 v[78:81], v[162:165], v[178:181], v[78:81]
	s_barrier
	s_setprio 2
	v_mfma_f32_16x16x32_bf16 v[18:21], v[154:157], v[186:189], v[18:21]
	v_mfma_f32_16x16x32_bf16 v[22:25], v[162:165], v[186:189], v[22:25]
	v_mfma_f32_16x16x32_bf16 v[2:5], v[154:157], v[238:241], v[2:5]
	v_mfma_f32_16x16x32_bf16 v[6:9], v[162:165], v[238:241], v[6:9]
	s_setprio 0
	ds_read_b128 v[134:137], v235
	ds_read_b128 v[138:141], v235 offset:1024
	ds_read_b128 v[142:145], v235 offset:2048
	ds_read_b128 v[146:149], v235 offset:3072
	ds_read_b128 v[150:153], v236
	ds_read_b128 v[154:157], v236 offset:1024
	ds_read_b128 v[158:161], v236 offset:2048
	ds_read_b128 v[162:165], v236 offset:3072
	s_add_u32 s34, s34, 0x80000
	s_addc_u32 s35, s35, 0
	s_mov_b32 m0, s43
	v_lshl_add_u64 v[250:251], s[34:35], 0, v[194:195]
	ds_read_b128 v[166:169], v226 offset:32768
	ds_read_b128 v[170:173], v226 offset:33792
	ds_read_b128 v[174:177], v226 offset:34816
	ds_read_b128 v[178:181], v226 offset:35840
	ds_read_b128 v[182:185], v226 offset:36864
	ds_read_b128 v[186:189], v226 offset:37888
	ds_read_b128 v[190:193], v226 offset:38912
	ds_read_b128 v[238:241], v226 offset:39936
	global_load_lds_dwordx4 v[250:251], off
	v_lshl_add_u64 v[250:251], s[34:35], 0, v[204:205]
	s_mov_b32 m0, s44
	s_nop 0
	global_load_lds_dwordx4 v[250:251], off
	s_waitcnt vmcnt(8)
	s_waitcnt lgkmcnt(0)
	s_barrier
	s_setprio 1
	s_waitcnt lgkmcnt(0)
	v_mfma_f32_16x16x32_bf16 v[26:29], v[134:137], v[166:169], v[26:29]
	v_mfma_f32_16x16x32_bf16 v[30:33], v[142:145], v[166:169], v[30:33]
	v_mfma_f32_16x16x32_bf16 v[42:45], v[134:137], v[174:177], v[42:45]
	v_mfma_f32_16x16x32_bf16 v[46:49], v[142:145], v[174:177], v[46:49]
	v_mfma_f32_16x16x32_bf16 v[70:73], v[134:137], v[182:185], v[70:73]
	v_mfma_f32_16x16x32_bf16 v[74:77], v[142:145], v[182:185], v[74:77]
	v_mfma_f32_16x16x32_bf16 v[90:93], v[134:137], v[190:193], v[90:93]
	v_mfma_f32_16x16x32_bf16 v[94:97], v[142:145], v[190:193], v[94:97]
	v_mfma_f32_16x16x32_bf16 v[26:29], v[138:141], v[170:173], v[26:29]
	v_mfma_f32_16x16x32_bf16 v[30:33], v[146:149], v[170:173], v[30:33]
	v_mfma_f32_16x16x32_bf16 v[42:45], v[138:141], v[178:181], v[42:45]
	v_mfma_f32_16x16x32_bf16 v[46:49], v[146:149], v[178:181], v[46:49]
	v_mfma_f32_16x16x32_bf16 v[70:73], v[138:141], v[186:189], v[70:73]
	v_mfma_f32_16x16x32_bf16 v[74:77], v[146:149], v[186:189], v[74:77]
	v_mfma_f32_16x16x32_bf16 v[90:93], v[138:141], v[238:241], v[90:93]
	v_mfma_f32_16x16x32_bf16 v[94:97], v[146:149], v[238:241], v[94:97]
	s_setprio 0
	s_setprio 1
	v_mfma_f32_16x16x32_bf16 v[34:37], v[150:153], v[166:169], v[34:37]
	v_mfma_f32_16x16x32_bf16 v[38:41], v[158:161], v[166:169], v[38:41]
	v_mfma_f32_16x16x32_bf16 v[54:57], v[150:153], v[174:177], v[54:57]
	v_mfma_f32_16x16x32_bf16 v[58:61], v[158:161], v[174:177], v[58:61]
	v_mfma_f32_16x16x32_bf16 v[82:85], v[150:153], v[182:185], v[82:85]
	v_mfma_f32_16x16x32_bf16 v[86:89], v[158:161], v[182:185], v[86:89]
	v_mfma_f32_16x16x32_bf16 v[98:101], v[150:153], v[190:193], v[98:101]
	v_mfma_f32_16x16x32_bf16 v[102:105], v[158:161], v[190:193], v[102:105]
	v_mfma_f32_16x16x32_bf16 v[34:37], v[154:157], v[170:173], v[34:37]
	v_mfma_f32_16x16x32_bf16 v[38:41], v[162:165], v[170:173], v[38:41]
	v_mfma_f32_16x16x32_bf16 v[54:57], v[154:157], v[178:181], v[54:57]
	v_mfma_f32_16x16x32_bf16 v[58:61], v[162:165], v[178:181], v[58:61]
	s_barrier
	s_setprio 2
	v_mfma_f32_16x16x32_bf16 v[82:85], v[154:157], v[186:189], v[82:85]
	v_mfma_f32_16x16x32_bf16 v[86:89], v[162:165], v[186:189], v[86:89]
	v_mfma_f32_16x16x32_bf16 v[98:101], v[154:157], v[238:241], v[98:101]
	v_mfma_f32_16x16x32_bf16 v[102:105], v[162:165], v[238:241], v[102:105]
	s_setprio 0
	s_mov_b32 m0, s72
	v_lshl_add_u64 v[242:243], v[242:243], 0, s[6:7]
	s_add_u32 s30, s30, 0x80080
	ds_read_b128 v[166:169], v226 offset:49152
	ds_read_b128 v[170:173], v226 offset:50176
	ds_read_b128 v[174:177], v226 offset:51200
	ds_read_b128 v[178:181], v226 offset:52224
	ds_read_b128 v[182:185], v226 offset:53248
	ds_read_b128 v[186:189], v226 offset:54272
	ds_read_b128 v[190:193], v226 offset:55296
	ds_read_b128 v[238:241], v226 offset:56320
	global_load_lds_dwordx4 v[242:243], off
	v_lshl_add_u64 v[242:243], v[244:245], 0, s[6:7]
	s_mov_b32 m0, s73
	s_addc_u32 s31, s31, 0
	global_load_lds_dwordx4 v[242:243], off
	v_lshl_add_u64 v[242:243], s[30:31], 0, v[202:203]
	s_mov_b32 m0, s74
	s_nop 0
	global_load_lds_dwordx4 v[242:243], off
	v_lshl_add_u64 v[242:243], s[30:31], 0, v[206:207]
	s_mov_b32 m0, s75
	s_nop 0
	global_load_lds_dwordx4 v[242:243], off
	v_lshl_add_u64 v[242:243], v[246:247], 0, s[6:7]
	s_mov_b32 m0, s51
	s_nop 0
	global_load_lds_dwordx4 v[242:243], off
	v_lshl_add_u64 v[242:243], v[248:249], 0, s[6:7]
	s_mov_b32 m0, s53
	s_nop 0
	global_load_lds_dwordx4 v[242:243], off
	s_waitcnt vmcnt(8)
	s_waitcnt lgkmcnt(0)
	s_barrier
	s_setprio 1
	s_waitcnt lgkmcnt(0)
	v_mfma_f32_16x16x32_bf16 v[106:109], v[134:137], v[166:169], v[106:109]
	v_mfma_f32_16x16x32_bf16 v[110:113], v[142:145], v[166:169], v[110:113]
	v_mfma_f32_16x16x32_bf16 v[118:121], v[134:137], v[174:177], v[118:121]
	v_mfma_f32_16x16x32_bf16 v[126:129], v[142:145], v[174:177], v[126:129]
	v_mfma_f32_16x16x32_bf16 v[50:53], v[134:137], v[182:185], v[50:53]
	v_mfma_f32_16x16x32_bf16 v[62:65], v[142:145], v[182:185], v[62:65]
	v_mfma_f32_16x16x32_bf16 v[10:13], v[134:137], v[190:193], v[10:13]
	v_mfma_f32_16x16x32_bf16 v[14:17], v[142:145], v[190:193], v[14:17]
	v_mfma_f32_16x16x32_bf16 v[106:109], v[138:141], v[170:173], v[106:109]
	v_mfma_f32_16x16x32_bf16 v[110:113], v[146:149], v[170:173], v[110:113]
	v_mfma_f32_16x16x32_bf16 v[118:121], v[138:141], v[178:181], v[118:121]
	v_mfma_f32_16x16x32_bf16 v[126:129], v[146:149], v[178:181], v[126:129]
	v_mfma_f32_16x16x32_bf16 v[50:53], v[138:141], v[186:189], v[50:53]
	v_mfma_f32_16x16x32_bf16 v[62:65], v[146:149], v[186:189], v[62:65]
	v_mfma_f32_16x16x32_bf16 v[10:13], v[138:141], v[238:241], v[10:13]
	v_mfma_f32_16x16x32_bf16 v[14:17], v[146:149], v[238:241], v[14:17]
	s_setprio 0
	s_setprio 1
	v_mfma_f32_16x16x32_bf16 v[114:117], v[150:153], v[166:169], v[114:117]
	v_mfma_f32_16x16x32_bf16 v[122:125], v[158:161], v[166:169], v[122:125]
	v_mfma_f32_16x16x32_bf16 v[66:69], v[150:153], v[174:177], v[66:69]
	v_mfma_f32_16x16x32_bf16 v[78:81], v[158:161], v[174:177], v[78:81]
	v_mfma_f32_16x16x32_bf16 v[18:21], v[150:153], v[182:185], v[18:21]
	v_mfma_f32_16x16x32_bf16 v[22:25], v[158:161], v[182:185], v[22:25]
	v_mfma_f32_16x16x32_bf16 v[2:5], v[150:153], v[190:193], v[2:5]
	v_mfma_f32_16x16x32_bf16 v[6:9], v[158:161], v[190:193], v[6:9]
	v_mfma_f32_16x16x32_bf16 v[114:117], v[154:157], v[170:173], v[114:117]
	v_mfma_f32_16x16x32_bf16 v[122:125], v[162:165], v[170:173], v[122:125]
	v_mfma_f32_16x16x32_bf16 v[66:69], v[154:157], v[178:181], v[66:69]
	v_mfma_f32_16x16x32_bf16 v[78:81], v[162:165], v[178:181], v[78:81]
	s_barrier
	s_setprio 2
	v_mfma_f32_16x16x32_bf16 v[18:21], v[154:157], v[186:189], v[18:21]
	v_mfma_f32_16x16x32_bf16 v[22:25], v[162:165], v[186:189], v[22:25]
	v_mfma_f32_16x16x32_bf16 v[2:5], v[154:157], v[238:241], v[2:5]
	v_mfma_f32_16x16x32_bf16 v[6:9], v[162:165], v[238:241], v[6:9]
	s_setprio 0
	s_add_i32 s41, s41, 2
	s_add_u32 s2, s2, 0x100
	s_addc_u32 s3, s3, 0
	s_cmp_gt_u32 s41, 29
	s_cbranch_scc0 .LBB0_752
	s_and_b64 vcc, exec, s[8:9]
	s_cbranch_vccz .LBB0_755
	s_barrier

.LBB0_817:
	ds_read_b128 v[130:133], v223
	ds_read_b128 v[134:137], v223 offset:1024
	ds_read_b128 v[138:141], v223 offset:2048
	ds_read_b128 v[142:145], v223 offset:3072
	ds_read_b128 v[146:149], v224
	ds_read_b128 v[150:153], v224 offset:1024
	ds_read_b128 v[154:157], v224 offset:2048
	ds_read_b128 v[158:161], v224 offset:3072
	s_add_u32 s6, s4, 0xfff00080
	s_addc_u32 s7, s5, -1
	s_cmp_eq_u32 s14, 60
	s_cselect_b32 s9, s19, s7
	s_cselect_b32 s8, s18, s6
	s_cselect_b32 s7, s79, s1
	s_cselect_b32 s6, s78, s0
	v_lshl_add_u64 v[194:195], s[4:5], 0, v[170:171]
	s_add_i32 m0, s35, 0xc000
	ds_read_b128 v[174:177], v225
	ds_read_b128 v[178:181], v225 offset:1024
	ds_read_b128 v[182:185], v225 offset:2048
	ds_read_b128 v[186:189], v225 offset:3072
	ds_read_b128 v[190:193], v225 offset:4096
	ds_read_b128 v[202:205], v225 offset:5120
	ds_read_b128 v[206:209], v225 offset:6144
	ds_read_b128 v[210:213], v225 offset:7168
	global_load_lds_dwordx4 v[194:195], off
	v_lshl_add_u64 v[194:195], s[4:5], 0, v[172:173]
	s_add_i32 m0, s35, 0xe000
	s_nop 0
	global_load_lds_dwordx4 v[194:195], off
	s_waitcnt vmcnt(8)
	s_waitcnt lgkmcnt(0)
	s_barrier
	s_setprio 1
	s_waitcnt lgkmcnt(0)
	v_mfma_f32_16x16x32_bf16 v[14:17], v[130:133], v[174:177], v[14:17]
	v_mfma_f32_16x16x32_bf16 v[10:13], v[138:141], v[174:177], v[10:13]
	v_mfma_f32_16x16x32_bf16 v[34:37], v[130:133], v[182:185], v[34:37]
	v_mfma_f32_16x16x32_bf16 v[26:29], v[138:141], v[182:185], v[26:29]
	v_mfma_f32_16x16x32_bf16 v[46:49], v[130:133], v[190:193], v[46:49]
	v_mfma_f32_16x16x32_bf16 v[42:45], v[138:141], v[190:193], v[42:45]
	v_mfma_f32_16x16x32_bf16 v[62:65], v[130:133], v[206:209], v[62:65]
	v_mfma_f32_16x16x32_bf16 v[58:61], v[138:141], v[206:209], v[58:61]
	v_mfma_f32_16x16x32_bf16 v[14:17], v[134:137], v[178:181], v[14:17]
	v_mfma_f32_16x16x32_bf16 v[10:13], v[142:145], v[178:181], v[10:13]
	v_mfma_f32_16x16x32_bf16 v[34:37], v[134:137], v[186:189], v[34:37]
	v_mfma_f32_16x16x32_bf16 v[26:29], v[142:145], v[186:189], v[26:29]
	v_mfma_f32_16x16x32_bf16 v[46:49], v[134:137], v[202:205], v[46:49]
	v_mfma_f32_16x16x32_bf16 v[42:45], v[142:145], v[202:205], v[42:45]
	v_mfma_f32_16x16x32_bf16 v[62:65], v[134:137], v[210:213], v[62:65]
	v_mfma_f32_16x16x32_bf16 v[58:61], v[142:145], v[210:213], v[58:61]
	s_setprio 0
	s_setprio 1
	v_mfma_f32_16x16x32_bf16 v[6:9], v[146:149], v[174:177], v[6:9]
	v_mfma_f32_16x16x32_bf16 v[2:5], v[154:157], v[174:177], v[2:5]
	v_mfma_f32_16x16x32_bf16 v[22:25], v[146:149], v[182:185], v[22:25]
	v_mfma_f32_16x16x32_bf16 v[18:21], v[154:157], v[182:185], v[18:21]
	v_mfma_f32_16x16x32_bf16 v[38:41], v[146:149], v[190:193], v[38:41]
	v_mfma_f32_16x16x32_bf16 v[30:33], v[154:157], v[190:193], v[30:33]
	v_mfma_f32_16x16x32_bf16 v[54:57], v[146:149], v[206:209], v[54:57]
	v_mfma_f32_16x16x32_bf16 v[50:53], v[154:157], v[206:209], v[50:53]
	v_mfma_f32_16x16x32_bf16 v[6:9], v[150:153], v[178:181], v[6:9]
	v_mfma_f32_16x16x32_bf16 v[2:5], v[158:161], v[178:181], v[2:5]
	v_mfma_f32_16x16x32_bf16 v[22:25], v[150:153], v[186:189], v[22:25]
	v_mfma_f32_16x16x32_bf16 v[18:21], v[158:161], v[186:189], v[18:21]
	s_barrier
	s_setprio 2
	v_mfma_f32_16x16x32_bf16 v[38:41], v[150:153], v[202:205], v[38:41]
	v_mfma_f32_16x16x32_bf16 v[30:33], v[158:161], v[202:205], v[30:33]
	v_mfma_f32_16x16x32_bf16 v[54:57], v[150:153], v[210:213], v[54:57]
	v_mfma_f32_16x16x32_bf16 v[50:53], v[158:161], v[210:213], v[50:53]
	s_setprio 0
	s_add_i32 s15, s17, s33
	v_lshl_add_u64 v[194:195], s[6:7], 0, v[164:165]
	s_mov_b32 m0, s15
	ds_read_b128 v[174:177], v225 offset:16384
	ds_read_b128 v[178:181], v225 offset:17408
	ds_read_b128 v[182:185], v225 offset:18432
	ds_read_b128 v[186:189], v225 offset:19456
	ds_read_b128 v[190:193], v225 offset:20480
	ds_read_b128 v[202:205], v225 offset:21504
	ds_read_b128 v[206:209], v225 offset:22528
	ds_read_b128 v[210:213], v225 offset:23552
	global_load_lds_dwordx4 v[194:195], off
	s_add_i32 m0, s15, 0x2000
	s_add_u32 s44, s6, 0x100000
	v_lshl_add_u64 v[214:215], s[6:7], 0, v[168:169]
	s_addc_u32 s45, s7, 0
	s_add_i32 s15, s55, s33
	global_load_lds_dwordx4 v[214:215], off
	v_lshl_add_u64 v[216:217], s[44:45], 0, v[164:165]
	s_mov_b32 m0, s15
	v_lshl_add_u64 v[218:219], s[8:9], 0, v[166:167]
	global_load_lds_dwordx4 v[216:217], off
	v_lshl_add_u64 v[216:217], s[44:45], 0, v[168:169]
	s_add_i32 m0, s15, 0x2000
	s_nop 0
	global_load_lds_dwordx4 v[216:217], off
	v_lshl_add_u64 v[216:217], s[8:9], 0, v[162:163]
	s_mov_b32 m0, s35
	s_nop 0
	global_load_lds_dwordx4 v[216:217], off
	s_mov_b32 m0, s80
	s_nop 0
	global_load_lds_dwordx4 v[218:219], off
	s_waitcnt vmcnt(8)
	s_waitcnt lgkmcnt(0)
	s_barrier
	s_setprio 1
	s_waitcnt lgkmcnt(0)
	v_mfma_f32_16x16x32_bf16 v[78:81], v[130:133], v[174:177], v[78:81]
	v_mfma_f32_16x16x32_bf16 v[74:77], v[138:141], v[174:177], v[74:77]
	v_mfma_f32_16x16x32_bf16 v[94:97], v[130:133], v[182:185], v[94:97]
	v_mfma_f32_16x16x32_bf16 v[90:93], v[138:141], v[182:185], v[90:93]
	v_mfma_f32_16x16x32_bf16 v[110:113], v[130:133], v[190:193], v[110:113]
	v_mfma_f32_16x16x32_bf16 v[106:109], v[138:141], v[190:193], v[106:109]
	v_mfma_f32_16x16x32_bf16 v[118:121], v[130:133], v[206:209], v[118:121]
	v_mfma_f32_16x16x32_bf16 v[114:117], v[138:141], v[206:209], v[114:117]
	v_mfma_f32_16x16x32_bf16 v[78:81], v[134:137], v[178:181], v[78:81]
	v_mfma_f32_16x16x32_bf16 v[74:77], v[142:145], v[178:181], v[74:77]
	v_mfma_f32_16x16x32_bf16 v[94:97], v[134:137], v[186:189], v[94:97]
	v_mfma_f32_16x16x32_bf16 v[90:93], v[142:145], v[186:189], v[90:93]
	v_mfma_f32_16x16x32_bf16 v[110:113], v[134:137], v[202:205], v[110:113]
	v_mfma_f32_16x16x32_bf16 v[106:109], v[142:145], v[202:205], v[106:109]
	v_mfma_f32_16x16x32_bf16 v[118:121], v[134:137], v[210:213], v[118:121]
	v_mfma_f32_16x16x32_bf16 v[114:117], v[142:145], v[210:213], v[114:117]
	s_setprio 0
	s_setprio 1
	v_mfma_f32_16x16x32_bf16 v[70:73], v[146:149], v[174:177], v[70:73]
	v_mfma_f32_16x16x32_bf16 v[66:69], v[154:157], v[174:177], v[66:69]
	v_mfma_f32_16x16x32_bf16 v[86:89], v[146:149], v[182:185], v[86:89]
	v_mfma_f32_16x16x32_bf16 v[82:85], v[154:157], v[182:185], v[82:85]
	v_mfma_f32_16x16x32_bf16 v[102:105], v[146:149], v[190:193], v[102:105]
	v_mfma_f32_16x16x32_bf16 v[98:101], v[154:157], v[190:193], v[98:101]
	v_mfma_f32_16x16x32_bf16 v[122:125], v[146:149], v[206:209], v[122:125]
	v_mfma_f32_16x16x32_bf16 v[126:129], v[154:157], v[206:209], v[126:129]
	v_mfma_f32_16x16x32_bf16 v[70:73], v[150:153], v[178:181], v[70:73]
	v_mfma_f32_16x16x32_bf16 v[66:69], v[158:161], v[178:181], v[66:69]
	v_mfma_f32_16x16x32_bf16 v[86:89], v[150:153], v[186:189], v[86:89]
	v_mfma_f32_16x16x32_bf16 v[82:85], v[158:161], v[186:189], v[82:85]
	s_barrier
	s_setprio 2
	v_mfma_f32_16x16x32_bf16 v[102:105], v[150:153], v[202:205], v[102:105]
	v_mfma_f32_16x16x32_bf16 v[98:101], v[158:161], v[202:205], v[98:101]
	v_mfma_f32_16x16x32_bf16 v[122:125], v[150:153], v[210:213], v[122:125]
	v_mfma_f32_16x16x32_bf16 v[126:129], v[158:161], v[210:213], v[126:129]
	s_setprio 0
	s_add_i32 s56, 0, 0x18000
	s_add_i32 s57, 0, 0x1c000
	v_add_u32_e32 v142, s56, v222
	v_add_u32_e32 v158, s57, v222
	ds_read_b128 v[130:133], v142
	ds_read_b128 v[134:137], v142 offset:1024
	ds_read_b128 v[138:141], v142 offset:2048
	ds_read_b128 v[142:145], v142 offset:3072
	ds_read_b128 v[146:149], v158
	ds_read_b128 v[150:153], v158 offset:1024
	ds_read_b128 v[154:157], v158 offset:2048
	ds_read_b128 v[158:161], v158 offset:3072
	s_add_u32 s8, s8, 0x100000
	s_addc_u32 s9, s9, 0
	s_mov_b32 m0, s59
	v_lshl_add_u64 v[238:239], s[8:9], 0, v[162:163]
	ds_read_b128 v[174:177], v225 offset:32768
	ds_read_b128 v[178:181], v225 offset:33792
	ds_read_b128 v[182:185], v225 offset:34816
	ds_read_b128 v[186:189], v225 offset:35840
	ds_read_b128 v[190:193], v225 offset:36864
	ds_read_b128 v[202:205], v225 offset:37888
	ds_read_b128 v[206:209], v225 offset:38912
	ds_read_b128 v[210:213], v225 offset:39936
	global_load_lds_dwordx4 v[238:239], off
	v_lshl_add_u64 v[238:239], s[8:9], 0, v[166:167]
	s_mov_b32 m0, s60
	s_nop 0
	global_load_lds_dwordx4 v[238:239], off
	s_waitcnt vmcnt(8)
	s_waitcnt lgkmcnt(0)
	s_barrier
	s_setprio 1
	s_waitcnt lgkmcnt(0)
	v_mfma_f32_16x16x32_bf16 v[14:17], v[130:133], v[174:177], v[14:17]
	v_mfma_f32_16x16x32_bf16 v[10:13], v[138:141], v[174:177], v[10:13]
	v_mfma_f32_16x16x32_bf16 v[34:37], v[130:133], v[182:185], v[34:37]
	v_mfma_f32_16x16x32_bf16 v[26:29], v[138:141], v[182:185], v[26:29]
	v_mfma_f32_16x16x32_bf16 v[46:49], v[130:133], v[190:193], v[46:49]
	v_mfma_f32_16x16x32_bf16 v[42:45], v[138:141], v[190:193], v[42:45]
	v_mfma_f32_16x16x32_bf16 v[62:65], v[130:133], v[206:209], v[62:65]
	v_mfma_f32_16x16x32_bf16 v[58:61], v[138:141], v[206:209], v[58:61]
	v_mfma_f32_16x16x32_bf16 v[14:17], v[134:137], v[178:181], v[14:17]
	v_mfma_f32_16x16x32_bf16 v[10:13], v[142:145], v[178:181], v[10:13]
	v_mfma_f32_16x16x32_bf16 v[34:37], v[134:137], v[186:189], v[34:37]
	v_mfma_f32_16x16x32_bf16 v[26:29], v[142:145], v[186:189], v[26:29]
	v_mfma_f32_16x16x32_bf16 v[46:49], v[134:137], v[202:205], v[46:49]
	v_mfma_f32_16x16x32_bf16 v[42:45], v[142:145], v[202:205], v[42:45]
	v_mfma_f32_16x16x32_bf16 v[62:65], v[134:137], v[210:213], v[62:65]
	v_mfma_f32_16x16x32_bf16 v[58:61], v[142:145], v[210:213], v[58:61]
	s_setprio 0
	s_setprio 1
	v_mfma_f32_16x16x32_bf16 v[6:9], v[146:149], v[174:177], v[6:9]
	v_mfma_f32_16x16x32_bf16 v[2:5], v[154:157], v[174:177], v[2:5]
	v_mfma_f32_16x16x32_bf16 v[22:25], v[146:149], v[182:185], v[22:25]
	v_mfma_f32_16x16x32_bf16 v[18:21], v[154:157], v[182:185], v[18:21]
	v_mfma_f32_16x16x32_bf16 v[38:41], v[146:149], v[190:193], v[38:41]
	v_mfma_f32_16x16x32_bf16 v[30:33], v[154:157], v[190:193], v[30:33]
	v_mfma_f32_16x16x32_bf16 v[54:57], v[146:149], v[206:209], v[54:57]
	v_mfma_f32_16x16x32_bf16 v[50:53], v[154:157], v[206:209], v[50:53]
	v_mfma_f32_16x16x32_bf16 v[6:9], v[150:153], v[178:181], v[6:9]
	v_mfma_f32_16x16x32_bf16 v[2:5], v[158:161], v[178:181], v[2:5]
	v_mfma_f32_16x16x32_bf16 v[22:25], v[150:153], v[186:189], v[22:25]
	v_mfma_f32_16x16x32_bf16 v[18:21], v[158:161], v[186:189], v[18:21]
	s_barrier
	s_setprio 2
	v_mfma_f32_16x16x32_bf16 v[38:41], v[150:153], v[202:205], v[38:41]
	v_mfma_f32_16x16x32_bf16 v[30:33], v[158:161], v[202:205], v[30:33]
	v_mfma_f32_16x16x32_bf16 v[54:57], v[150:153], v[210:213], v[54:57]
	v_mfma_f32_16x16x32_bf16 v[50:53], v[158:161], v[210:213], v[50:53]
	s_setprio 0
	s_add_i32 s8, s56, s33
	v_lshl_add_u64 v[194:195], v[194:195], 0, s[26:27]
	s_mov_b32 m0, s8
	ds_read_b128 v[174:177], v225 offset:49152
	ds_read_b128 v[178:181], v225 offset:50176
	ds_read_b128 v[182:185], v225 offset:51200
	ds_read_b128 v[186:189], v225 offset:52224
	ds_read_b128 v[190:193], v225 offset:53248
	ds_read_b128 v[202:205], v225 offset:54272
	ds_read_b128 v[206:209], v225 offset:55296
	ds_read_b128 v[210:213], v225 offset:56320
	global_load_lds_dwordx4 v[194:195], off
	s_add_i32 m0, s8, 0x2000
	s_add_u32 s6, s6, 0x100080
	v_lshl_add_u64 v[194:195], v[214:215], 0, s[26:27]
	s_addc_u32 s7, s7, 0
	s_add_i32 s8, s57, s33
	global_load_lds_dwordx4 v[194:195], off
	v_lshl_add_u64 v[194:195], s[6:7], 0, v[164:165]
	s_mov_b32 m0, s8
	s_nop 0
	global_load_lds_dwordx4 v[194:195], off
	v_lshl_add_u64 v[194:195], s[6:7], 0, v[168:169]
	s_add_i32 m0, s8, 0x2000
	s_nop 0
	global_load_lds_dwordx4 v[194:195], off
	v_lshl_add_u64 v[194:195], v[216:217], 0, s[26:27]
	s_mov_b32 m0, s65
	s_nop 0
	global_load_lds_dwordx4 v[194:195], off
	v_lshl_add_u64 v[194:195], v[218:219], 0, s[26:27]
	s_mov_b32 m0, s66
	s_nop 0
	global_load_lds_dwordx4 v[194:195], off
	s_waitcnt vmcnt(8)
	s_waitcnt lgkmcnt(0)
	s_barrier
	s_setprio 1
	s_waitcnt lgkmcnt(0)
	v_mfma_f32_16x16x32_bf16 v[78:81], v[130:133], v[174:177], v[78:81]
	v_mfma_f32_16x16x32_bf16 v[74:77], v[138:141], v[174:177], v[74:77]
	v_mfma_f32_16x16x32_bf16 v[94:97], v[130:133], v[182:185], v[94:97]
	v_mfma_f32_16x16x32_bf16 v[90:93], v[138:141], v[182:185], v[90:93]
	v_mfma_f32_16x16x32_bf16 v[110:113], v[130:133], v[190:193], v[110:113]
	v_mfma_f32_16x16x32_bf16 v[106:109], v[138:141], v[190:193], v[106:109]
	v_mfma_f32_16x16x32_bf16 v[118:121], v[130:133], v[206:209], v[118:121]
	v_mfma_f32_16x16x32_bf16 v[114:117], v[138:141], v[206:209], v[114:117]
	v_mfma_f32_16x16x32_bf16 v[78:81], v[134:137], v[178:181], v[78:81]
	v_mfma_f32_16x16x32_bf16 v[74:77], v[142:145], v[178:181], v[74:77]
	v_mfma_f32_16x16x32_bf16 v[94:97], v[134:137], v[186:189], v[94:97]
	v_mfma_f32_16x16x32_bf16 v[90:93], v[142:145], v[186:189], v[90:93]
	v_mfma_f32_16x16x32_bf16 v[110:113], v[134:137], v[202:205], v[110:113]
	v_mfma_f32_16x16x32_bf16 v[106:109], v[142:145], v[202:205], v[106:109]
	v_mfma_f32_16x16x32_bf16 v[118:121], v[134:137], v[210:213], v[118:121]
	v_mfma_f32_16x16x32_bf16 v[114:117], v[142:145], v[210:213], v[114:117]
	s_setprio 0
	s_setprio 1
	v_mfma_f32_16x16x32_bf16 v[70:73], v[146:149], v[174:177], v[70:73]
	v_mfma_f32_16x16x32_bf16 v[66:69], v[154:157], v[174:177], v[66:69]
	v_mfma_f32_16x16x32_bf16 v[86:89], v[146:149], v[182:185], v[86:89]
	v_mfma_f32_16x16x32_bf16 v[82:85], v[154:157], v[182:185], v[82:85]
	v_mfma_f32_16x16x32_bf16 v[102:105], v[146:149], v[190:193], v[102:105]
	v_mfma_f32_16x16x32_bf16 v[98:101], v[154:157], v[190:193], v[98:101]
	v_mfma_f32_16x16x32_bf16 v[122:125], v[146:149], v[206:209], v[122:125]
	v_mfma_f32_16x16x32_bf16 v[126:129], v[154:157], v[206:209], v[126:129]
	v_mfma_f32_16x16x32_bf16 v[70:73], v[150:153], v[178:181], v[70:73]
	v_mfma_f32_16x16x32_bf16 v[66:69], v[158:161], v[178:181], v[66:69]
	v_mfma_f32_16x16x32_bf16 v[86:89], v[150:153], v[186:189], v[86:89]
	v_mfma_f32_16x16x32_bf16 v[82:85], v[158:161], v[186:189], v[82:85]
	s_barrier
	s_setprio 2
	v_mfma_f32_16x16x32_bf16 v[102:105], v[150:153], v[202:205], v[102:105]
	v_mfma_f32_16x16x32_bf16 v[98:101], v[158:161], v[202:205], v[98:101]
	v_mfma_f32_16x16x32_bf16 v[122:125], v[150:153], v[210:213], v[122:125]
	v_mfma_f32_16x16x32_bf16 v[126:129], v[158:161], v[210:213], v[126:129]
	s_setprio 0
	s_add_i32 s14, s14, 2
	s_add_u32 s4, s4, 0x100
	s_addc_u32 s5, s5, 0
	s_add_u32 s0, s0, 0x100
	s_addc_u32 s1, s1, 0
	s_cmp_gt_u32 s14, 61
	s_cbranch_scc0 .LBB0_817
	s_and_b64 vcc, exec, s[28:29]
	s_cbranch_vccz .LBB0_820
	s_barrier

.LBB0_961:
	ds_read_b128 v[158:161], v185
	ds_read_b128 v[154:157], v185 offset:1024
	ds_read_b128 v[150:153], v185 offset:2048
	ds_read_b128 v[146:149], v185 offset:3072
	ds_read_b128 v[142:145], v186
	ds_read_b128 v[138:141], v186 offset:1024
	ds_read_b128 v[134:137], v186 offset:2048
	ds_read_b128 v[130:133], v186 offset:3072
	s_add_u32 s30, s28, 0xfff80080
	s_addc_u32 s31, s29, -1
	s_cmp_eq_u32 s45, 28
	s_cselect_b32 s35, s1, s31
	s_cselect_b32 s34, s15, s30
	s_cselect_b32 s31, s19, s44
	s_cselect_b32 s30, s42, s43
	v_lshl_add_u64 v[220:221], s[28:29], 0, v[170:171]
	s_add_i32 m0, s27, 0xc000
	ds_read_b128 v[174:177], v187
	ds_read_b128 v[178:181], v187 offset:1024
	ds_read_b128 v[188:191], v187 offset:2048
	ds_read_b128 v[192:195], v187 offset:3072
	ds_read_b128 v[202:205], v187 offset:4096
	ds_read_b128 v[206:209], v187 offset:5120
	ds_read_b128 v[210:213], v187 offset:6144
	ds_read_b128 v[214:217], v187 offset:7168
	global_load_lds_dwordx4 v[220:221], off
	v_lshl_add_u64 v[220:221], s[28:29], 0, v[172:173]
	s_add_i32 m0, s27, 0xe000
	s_nop 0
	global_load_lds_dwordx4 v[220:221], off
	s_waitcnt vmcnt(8)
	s_waitcnt lgkmcnt(0)
	s_barrier
	s_setprio 1
	s_waitcnt lgkmcnt(0)
	v_mfma_i32_16x16x64_i8 v[126:129], v[158:161], v[174:177], v[126:129]
	s_nop 0
	v_mfma_i32_16x16x64_i8 v[126:129], v[154:157], v[178:181], v[126:129]
	v_mfma_i32_16x16x64_i8 v[122:125], v[150:153], v[174:177], v[122:125]
	s_nop 0
	v_mfma_i32_16x16x64_i8 v[122:125], v[146:149], v[178:181], v[122:125]
	v_mfma_i32_16x16x64_i8 v[110:113], v[158:161], v[188:191], v[110:113]
	s_nop 0
	v_mfma_i32_16x16x64_i8 v[110:113], v[154:157], v[192:195], v[110:113]
	v_mfma_i32_16x16x64_i8 v[106:109], v[150:153], v[188:191], v[106:109]
	s_nop 0
	v_mfma_i32_16x16x64_i8 v[106:109], v[146:149], v[192:195], v[106:109]
	v_mfma_i32_16x16x64_i8 v[94:97], v[158:161], v[202:205], v[94:97]
	s_nop 0
	v_mfma_i32_16x16x64_i8 v[94:97], v[154:157], v[206:209], v[94:97]
	v_mfma_i32_16x16x64_i8 v[90:93], v[150:153], v[202:205], v[90:93]
	s_nop 0
	v_mfma_i32_16x16x64_i8 v[90:93], v[146:149], v[206:209], v[90:93]
	v_mfma_i32_16x16x64_i8 v[78:81], v[158:161], v[210:213], v[78:81]
	s_nop 0
	v_mfma_i32_16x16x64_i8 v[78:81], v[154:157], v[214:217], v[78:81]
	v_mfma_i32_16x16x64_i8 v[74:77], v[150:153], v[210:213], v[74:77]
	s_nop 0
	v_mfma_i32_16x16x64_i8 v[74:77], v[146:149], v[214:217], v[74:77]
	s_setprio 0
	s_setprio 1
	v_mfma_i32_16x16x64_i8 v[118:121], v[142:145], v[174:177], v[118:121]
	s_nop 0
	v_mfma_i32_16x16x64_i8 v[118:121], v[138:141], v[178:181], v[118:121]
	v_mfma_i32_16x16x64_i8 v[114:117], v[134:137], v[174:177], v[114:117]
	s_nop 0
	v_mfma_i32_16x16x64_i8 v[114:117], v[130:133], v[178:181], v[114:117]
	v_mfma_i32_16x16x64_i8 v[102:105], v[142:145], v[188:191], v[102:105]
	s_nop 0
	v_mfma_i32_16x16x64_i8 v[102:105], v[138:141], v[192:195], v[102:105]
	v_mfma_i32_16x16x64_i8 v[98:101], v[134:137], v[188:191], v[98:101]
	s_nop 0
	v_mfma_i32_16x16x64_i8 v[98:101], v[130:133], v[192:195], v[98:101]
	v_mfma_i32_16x16x64_i8 v[86:89], v[142:145], v[202:205], v[86:89]
	s_nop 0
	v_mfma_i32_16x16x64_i8 v[86:89], v[138:141], v[206:209], v[86:89]
	v_mfma_i32_16x16x64_i8 v[82:85], v[134:137], v[202:205], v[82:85]
	s_nop 0
	v_mfma_i32_16x16x64_i8 v[82:85], v[130:133], v[206:209], v[82:85]
	s_barrier
	s_setprio 2
	v_mfma_i32_16x16x64_i8 v[70:73], v[142:145], v[210:213], v[70:73]
	s_nop 0
	v_mfma_i32_16x16x64_i8 v[70:73], v[138:141], v[214:217], v[70:73]
	v_mfma_i32_16x16x64_i8 v[66:69], v[134:137], v[210:213], v[66:69]
	s_nop 0
	v_mfma_i32_16x16x64_i8 v[66:69], v[130:133], v[214:217], v[66:69]
	s_setprio 0
	s_add_i32 s46, s17, s9
	v_lshl_add_u64 v[174:175], s[30:31], 0, v[166:167]
	s_mov_b32 m0, s46
	ds_read_b128 v[188:191], v187 offset:16384
	ds_read_b128 v[192:195], v187 offset:17408
	ds_read_b128 v[202:205], v187 offset:18432
	ds_read_b128 v[206:209], v187 offset:19456
	ds_read_b128 v[210:213], v187 offset:20480
	ds_read_b128 v[214:217], v187 offset:21504
	ds_read_b128 v[220:223], v187 offset:22528
	ds_read_b128 v[224:227], v187 offset:23552
	global_load_lds_dwordx4 v[174:175], off
	s_add_i32 m0, s46, 0x2000
	s_add_u32 s46, s30, 0x80000
	v_lshl_add_u64 v[176:177], s[30:31], 0, v[162:163]
	s_addc_u32 s47, s31, 0
	s_add_i32 s48, s55, s9
	global_load_lds_dwordx4 v[176:177], off
	v_lshl_add_u64 v[178:179], s[46:47], 0, v[166:167]
	s_mov_b32 m0, s48
	v_lshl_add_u64 v[180:181], s[34:35], 0, v[164:165]
	global_load_lds_dwordx4 v[178:179], off
	v_lshl_add_u64 v[178:179], s[46:47], 0, v[162:163]
	s_add_i32 m0, s48, 0x2000
	s_nop 0
	global_load_lds_dwordx4 v[178:179], off
	v_lshl_add_u64 v[178:179], s[34:35], 0, v[168:169]
	s_mov_b32 m0, s27
	s_nop 0
	global_load_lds_dwordx4 v[178:179], off
	s_mov_b32 m0, s33
	s_nop 0
	global_load_lds_dwordx4 v[180:181], off
	s_waitcnt vmcnt(8)
	s_waitcnt lgkmcnt(0)
	s_barrier
	s_setprio 1
	s_waitcnt lgkmcnt(0)
	v_mfma_i32_16x16x64_i8 v[62:65], v[158:161], v[188:191], v[62:65]
	s_nop 0
	v_mfma_i32_16x16x64_i8 v[62:65], v[154:157], v[192:195], v[62:65]
	v_mfma_i32_16x16x64_i8 v[58:61], v[150:153], v[188:191], v[58:61]
	s_nop 0
	v_mfma_i32_16x16x64_i8 v[58:61], v[146:149], v[192:195], v[58:61]
	v_mfma_i32_16x16x64_i8 v[46:49], v[158:161], v[202:205], v[46:49]
	s_nop 0
	v_mfma_i32_16x16x64_i8 v[46:49], v[154:157], v[206:209], v[46:49]
	v_mfma_i32_16x16x64_i8 v[42:45], v[150:153], v[202:205], v[42:45]
	s_nop 0
	v_mfma_i32_16x16x64_i8 v[42:45], v[146:149], v[206:209], v[42:45]
	v_mfma_i32_16x16x64_i8 v[30:33], v[158:161], v[210:213], v[30:33]
	s_nop 0
	v_mfma_i32_16x16x64_i8 v[30:33], v[154:157], v[214:217], v[30:33]
	v_mfma_i32_16x16x64_i8 v[26:29], v[150:153], v[210:213], v[26:29]
	s_nop 0
	v_mfma_i32_16x16x64_i8 v[26:29], v[146:149], v[214:217], v[26:29]
	v_mfma_i32_16x16x64_i8 v[14:17], v[158:161], v[220:223], v[14:17]
	s_nop 0
	v_mfma_i32_16x16x64_i8 v[14:17], v[154:157], v[224:227], v[14:17]
	v_mfma_i32_16x16x64_i8 v[10:13], v[150:153], v[220:223], v[10:13]
	s_nop 0
	v_mfma_i32_16x16x64_i8 v[10:13], v[146:149], v[224:227], v[10:13]
	s_setprio 0
	s_setprio 1
	v_mfma_i32_16x16x64_i8 v[54:57], v[142:145], v[188:191], v[54:57]
	s_nop 0
	v_mfma_i32_16x16x64_i8 v[54:57], v[138:141], v[192:195], v[54:57]
	v_mfma_i32_16x16x64_i8 v[50:53], v[134:137], v[188:191], v[50:53]
	s_nop 0
	v_mfma_i32_16x16x64_i8 v[50:53], v[130:133], v[192:195], v[50:53]
	v_mfma_i32_16x16x64_i8 v[38:41], v[142:145], v[202:205], v[38:41]
	s_nop 0
	v_mfma_i32_16x16x64_i8 v[38:41], v[138:141], v[206:209], v[38:41]
	v_mfma_i32_16x16x64_i8 v[34:37], v[134:137], v[202:205], v[34:37]
	s_nop 0
	v_mfma_i32_16x16x64_i8 v[34:37], v[130:133], v[206:209], v[34:37]
	v_mfma_i32_16x16x64_i8 v[22:25], v[142:145], v[210:213], v[22:25]
	s_nop 0
	v_mfma_i32_16x16x64_i8 v[22:25], v[138:141], v[214:217], v[22:25]
	v_mfma_i32_16x16x64_i8 v[18:21], v[134:137], v[210:213], v[18:21]
	s_nop 0
	v_mfma_i32_16x16x64_i8 v[18:21], v[130:133], v[214:217], v[18:21]
	s_barrier
	s_setprio 2
	v_mfma_i32_16x16x64_i8 v[6:9], v[142:145], v[220:223], v[6:9]
	s_nop 0
	v_mfma_i32_16x16x64_i8 v[6:9], v[138:141], v[224:227], v[6:9]
	v_mfma_i32_16x16x64_i8 v[2:5], v[134:137], v[220:223], v[2:5]
	s_nop 0
	v_mfma_i32_16x16x64_i8 v[2:5], v[130:133], v[224:227], v[2:5]
	s_setprio 0
	v_add_u32_e32 v142, s56, v183
	v_add_u32_e32 v158, s57, v183
	ds_read_b128 v[130:133], v142
	ds_read_b128 v[134:137], v142 offset:1024
	ds_read_b128 v[138:141], v142 offset:2048
	ds_read_b128 v[142:145], v142 offset:3072
	ds_read_b128 v[146:149], v158
	ds_read_b128 v[150:153], v158 offset:1024
	ds_read_b128 v[154:157], v158 offset:2048
	ds_read_b128 v[158:161], v158 offset:3072
	s_add_u32 s34, s34, 0x80000
	s_addc_u32 s35, s35, 0
	s_mov_b32 m0, s36
	v_lshl_add_u64 v[232:233], s[34:35], 0, v[168:169]
	ds_read_b128 v[188:191], v187 offset:32768
	ds_read_b128 v[192:195], v187 offset:33792
	ds_read_b128 v[202:205], v187 offset:34816
	ds_read_b128 v[206:209], v187 offset:35840
	ds_read_b128 v[210:213], v187 offset:36864
	ds_read_b128 v[214:217], v187 offset:37888
	ds_read_b128 v[220:223], v187 offset:38912
	ds_read_b128 v[224:227], v187 offset:39936
	global_load_lds_dwordx4 v[232:233], off
	v_lshl_add_u64 v[232:233], s[34:35], 0, v[164:165]
	s_mov_b32 m0, s37
	s_nop 0
	global_load_lds_dwordx4 v[232:233], off
	s_waitcnt vmcnt(8)
	s_waitcnt lgkmcnt(0)
	s_barrier
	s_setprio 1
	s_waitcnt lgkmcnt(0)
	v_mfma_i32_16x16x64_i8 v[126:129], v[130:133], v[188:191], v[126:129]
	s_nop 0
	v_mfma_i32_16x16x64_i8 v[126:129], v[134:137], v[192:195], v[126:129]
	v_mfma_i32_16x16x64_i8 v[122:125], v[138:141], v[188:191], v[122:125]
	s_nop 0
	v_mfma_i32_16x16x64_i8 v[122:125], v[142:145], v[192:195], v[122:125]
	v_mfma_i32_16x16x64_i8 v[110:113], v[130:133], v[202:205], v[110:113]
	s_nop 0
	v_mfma_i32_16x16x64_i8 v[110:113], v[134:137], v[206:209], v[110:113]
	v_mfma_i32_16x16x64_i8 v[106:109], v[138:141], v[202:205], v[106:109]
	s_nop 0
	v_mfma_i32_16x16x64_i8 v[106:109], v[142:145], v[206:209], v[106:109]
	v_mfma_i32_16x16x64_i8 v[94:97], v[130:133], v[210:213], v[94:97]
	s_nop 0
	v_mfma_i32_16x16x64_i8 v[94:97], v[134:137], v[214:217], v[94:97]
	v_mfma_i32_16x16x64_i8 v[90:93], v[138:141], v[210:213], v[90:93]
	s_nop 0
	v_mfma_i32_16x16x64_i8 v[90:93], v[142:145], v[214:217], v[90:93]
	v_mfma_i32_16x16x64_i8 v[78:81], v[130:133], v[220:223], v[78:81]
	s_nop 0
	v_mfma_i32_16x16x64_i8 v[78:81], v[134:137], v[224:227], v[78:81]
	v_mfma_i32_16x16x64_i8 v[74:77], v[138:141], v[220:223], v[74:77]
	s_nop 0
	v_mfma_i32_16x16x64_i8 v[74:77], v[142:145], v[224:227], v[74:77]
	s_setprio 0
	s_setprio 1
	v_mfma_i32_16x16x64_i8 v[118:121], v[146:149], v[188:191], v[118:121]
	s_nop 0
	v_mfma_i32_16x16x64_i8 v[118:121], v[150:153], v[192:195], v[118:121]
	v_mfma_i32_16x16x64_i8 v[114:117], v[154:157], v[188:191], v[114:117]
	s_nop 0
	v_mfma_i32_16x16x64_i8 v[114:117], v[158:161], v[192:195], v[114:117]
	v_mfma_i32_16x16x64_i8 v[102:105], v[146:149], v[202:205], v[102:105]
	s_nop 0
	v_mfma_i32_16x16x64_i8 v[102:105], v[150:153], v[206:209], v[102:105]
	v_mfma_i32_16x16x64_i8 v[98:101], v[154:157], v[202:205], v[98:101]
	s_nop 0
	v_mfma_i32_16x16x64_i8 v[98:101], v[158:161], v[206:209], v[98:101]
	v_mfma_i32_16x16x64_i8 v[86:89], v[146:149], v[210:213], v[86:89]
	s_nop 0
	v_mfma_i32_16x16x64_i8 v[86:89], v[150:153], v[214:217], v[86:89]
	v_mfma_i32_16x16x64_i8 v[82:85], v[154:157], v[210:213], v[82:85]
	s_nop 0
	v_mfma_i32_16x16x64_i8 v[82:85], v[158:161], v[214:217], v[82:85]
	s_barrier
	s_setprio 2
	v_mfma_i32_16x16x64_i8 v[70:73], v[146:149], v[220:223], v[70:73]
	s_nop 0
	v_mfma_i32_16x16x64_i8 v[70:73], v[150:153], v[224:227], v[70:73]
	v_mfma_i32_16x16x64_i8 v[66:69], v[154:157], v[220:223], v[66:69]
	s_nop 0
	v_mfma_i32_16x16x64_i8 v[66:69], v[158:161], v[224:227], v[66:69]
	s_setprio 0
	s_add_i32 s34, s56, s9
	v_lshl_add_u64 v[174:175], v[174:175], 0, s[4:5]
	s_mov_b32 m0, s34
	ds_read_b128 v[188:191], v187 offset:49152
	ds_read_b128 v[192:195], v187 offset:50176
	ds_read_b128 v[202:205], v187 offset:51200
	ds_read_b128 v[206:209], v187 offset:52224
	ds_read_b128 v[210:213], v187 offset:53248
	ds_read_b128 v[214:217], v187 offset:54272
	ds_read_b128 v[220:223], v187 offset:55296
	ds_read_b128 v[224:227], v187 offset:56320
	global_load_lds_dwordx4 v[174:175], off
	s_add_i32 m0, s34, 0x2000
	s_add_u32 s30, s30, 0x80080
	v_lshl_add_u64 v[174:175], v[176:177], 0, s[4:5]
	s_addc_u32 s31, s31, 0
	s_add_i32 s34, s57, s9
	global_load_lds_dwordx4 v[174:175], off
	v_lshl_add_u64 v[174:175], s[30:31], 0, v[166:167]
	s_mov_b32 m0, s34
	s_nop 0
	global_load_lds_dwordx4 v[174:175], off
	v_lshl_add_u64 v[174:175], s[30:31], 0, v[162:163]
	s_add_i32 m0, s34, 0x2000
	s_nop 0
	global_load_lds_dwordx4 v[174:175], off
	v_lshl_add_u64 v[174:175], v[178:179], 0, s[4:5]
	s_mov_b32 m0, s39
	s_nop 0
	global_load_lds_dwordx4 v[174:175], off
	v_lshl_add_u64 v[174:175], v[180:181], 0, s[4:5]
	s_mov_b32 m0, s40
	s_nop 0
	global_load_lds_dwordx4 v[174:175], off
	s_waitcnt vmcnt(8)
	s_waitcnt lgkmcnt(0)
	s_barrier
	s_setprio 1
	s_waitcnt lgkmcnt(0)
	v_mfma_i32_16x16x64_i8 v[62:65], v[130:133], v[188:191], v[62:65]
	s_nop 0
	v_mfma_i32_16x16x64_i8 v[62:65], v[134:137], v[192:195], v[62:65]
	v_mfma_i32_16x16x64_i8 v[58:61], v[138:141], v[188:191], v[58:61]
	s_nop 0
	v_mfma_i32_16x16x64_i8 v[58:61], v[142:145], v[192:195], v[58:61]
	v_mfma_i32_16x16x64_i8 v[46:49], v[130:133], v[202:205], v[46:49]
	s_nop 0
	v_mfma_i32_16x16x64_i8 v[46:49], v[134:137], v[206:209], v[46:49]
	v_mfma_i32_16x16x64_i8 v[42:45], v[138:141], v[202:205], v[42:45]
	s_nop 0
	v_mfma_i32_16x16x64_i8 v[42:45], v[142:145], v[206:209], v[42:45]
	v_mfma_i32_16x16x64_i8 v[30:33], v[130:133], v[210:213], v[30:33]
	s_nop 0
	v_mfma_i32_16x16x64_i8 v[30:33], v[134:137], v[214:217], v[30:33]
	v_mfma_i32_16x16x64_i8 v[26:29], v[138:141], v[210:213], v[26:29]
	s_nop 0
	v_mfma_i32_16x16x64_i8 v[26:29], v[142:145], v[214:217], v[26:29]
	v_mfma_i32_16x16x64_i8 v[14:17], v[130:133], v[220:223], v[14:17]
	s_nop 0
	v_mfma_i32_16x16x64_i8 v[14:17], v[134:137], v[224:227], v[14:17]
	v_mfma_i32_16x16x64_i8 v[10:13], v[138:141], v[220:223], v[10:13]
	s_nop 0
	v_mfma_i32_16x16x64_i8 v[10:13], v[142:145], v[224:227], v[10:13]
	s_setprio 0
	s_setprio 1
	v_mfma_i32_16x16x64_i8 v[54:57], v[146:149], v[188:191], v[54:57]
	s_nop 0
	v_mfma_i32_16x16x64_i8 v[54:57], v[150:153], v[192:195], v[54:57]
	v_mfma_i32_16x16x64_i8 v[50:53], v[154:157], v[188:191], v[50:53]
	s_nop 0
	v_mfma_i32_16x16x64_i8 v[50:53], v[158:161], v[192:195], v[50:53]
	v_mfma_i32_16x16x64_i8 v[38:41], v[146:149], v[202:205], v[38:41]
	s_nop 0
	v_mfma_i32_16x16x64_i8 v[38:41], v[150:153], v[206:209], v[38:41]
	v_mfma_i32_16x16x64_i8 v[34:37], v[154:157], v[202:205], v[34:37]
	s_nop 0
	v_mfma_i32_16x16x64_i8 v[34:37], v[158:161], v[206:209], v[34:37]
	v_mfma_i32_16x16x64_i8 v[22:25], v[146:149], v[210:213], v[22:25]
	s_nop 0
	v_mfma_i32_16x16x64_i8 v[22:25], v[150:153], v[214:217], v[22:25]
	v_mfma_i32_16x16x64_i8 v[18:21], v[154:157], v[210:213], v[18:21]
	s_nop 0
	v_mfma_i32_16x16x64_i8 v[18:21], v[158:161], v[214:217], v[18:21]
	s_barrier
	s_setprio 2
	v_mfma_i32_16x16x64_i8 v[6:9], v[146:149], v[220:223], v[6:9]
	s_nop 0
	v_mfma_i32_16x16x64_i8 v[6:9], v[150:153], v[224:227], v[6:9]
	v_mfma_i32_16x16x64_i8 v[2:5], v[154:157], v[220:223], v[2:5]
	s_nop 0
	v_mfma_i32_16x16x64_i8 v[2:5], v[158:161], v[224:227], v[2:5]
	s_setprio 0
	s_add_i32 s45, s45, 2
	s_add_u32 s28, s28, 0x100
	s_addc_u32 s29, s29, 0
	s_add_u32 s43, s43, 0x100
	s_addc_u32 s44, s44, 0
	s_cmp_gt_u32 s45, 29
	s_cbranch_scc0 .LBB0_961
	s_nop 15
	s_nop 15
	s_and_b64 vcc, exec, s[6:7]
	s_cbranch_vccz .LBB0_964
	s_barrier

.LBB0_1058:
	ds_read_b128 v[128:131], v194
	ds_read_b128 v[132:135], v194 offset:1024
	ds_read_b128 v[136:139], v194 offset:2048
	ds_read_b128 v[140:143], v194 offset:3072
	ds_read_b128 v[144:147], v195
	ds_read_b128 v[148:151], v195 offset:1024
	ds_read_b128 v[152:155], v195 offset:2048
	ds_read_b128 v[156:159], v195 offset:3072
	s_add_u32 s2, s0, 0x100
	s_addc_u32 s3, s1, 0
	s_cmpk_eq_i32 s39, 0xa8
	s_cselect_b32 s37, s31, s3
	s_cselect_b32 s36, s30, s2
	s_cselect_b32 s5, s7, s38
	s_cselect_b32 s4, s6, s29
	v_lshl_add_u64 v[188:189], s[0:1], 0, v[168:169]
	s_add_i32 m0, s27, 0xc000
	ds_read_b128 v[172:175], v196
	ds_read_b128 v[176:179], v196 offset:1024
	ds_read_b128 v[180:183], v196 offset:2048
	ds_read_b128 v[184:187], v196 offset:3072
	ds_read_b128 v[200:203], v196 offset:4096
	ds_read_b128 v[204:207], v196 offset:5120
	ds_read_b128 v[208:211], v196 offset:6144
	ds_read_b128 v[212:215], v196 offset:7168
	global_load_lds_dwordx4 v[188:189], off
	v_lshl_add_u64 v[188:189], s[0:1], 0, v[170:171]
	s_add_i32 m0, s27, 0xe000
	s_nop 0
	global_load_lds_dwordx4 v[188:189], off
	s_waitcnt vmcnt(8)
	s_waitcnt lgkmcnt(0)
	s_barrier
	s_setprio 1
	s_waitcnt lgkmcnt(0)
	v_mfma_f32_16x16x32_bf16 v[12:15], v[128:131], v[172:175], v[12:15]
	v_mfma_f32_16x16x32_bf16 v[8:11], v[136:139], v[172:175], v[8:11]
	v_mfma_f32_16x16x32_bf16 v[36:39], v[128:131], v[180:183], v[36:39]
	v_mfma_f32_16x16x32_bf16 v[32:35], v[136:139], v[180:183], v[32:35]
	v_mfma_f32_16x16x32_bf16 v[44:47], v[128:131], v[200:203], v[44:47]
	v_mfma_f32_16x16x32_bf16 v[40:43], v[136:139], v[200:203], v[40:43]
	v_mfma_f32_16x16x32_bf16 v[64:67], v[128:131], v[208:211], v[64:67]
	v_mfma_f32_16x16x32_bf16 v[56:59], v[136:139], v[208:211], v[56:59]
	v_mfma_f32_16x16x32_bf16 v[12:15], v[132:135], v[176:179], v[12:15]
	v_mfma_f32_16x16x32_bf16 v[8:11], v[140:143], v[176:179], v[8:11]
	v_mfma_f32_16x16x32_bf16 v[36:39], v[132:135], v[184:187], v[36:39]
	v_mfma_f32_16x16x32_bf16 v[32:35], v[140:143], v[184:187], v[32:35]
	v_mfma_f32_16x16x32_bf16 v[44:47], v[132:135], v[204:207], v[44:47]
	v_mfma_f32_16x16x32_bf16 v[40:43], v[140:143], v[204:207], v[40:43]
	v_mfma_f32_16x16x32_bf16 v[64:67], v[132:135], v[212:215], v[64:67]
	v_mfma_f32_16x16x32_bf16 v[56:59], v[140:143], v[212:215], v[56:59]
	s_setprio 0
	s_setprio 1
	v_mfma_f32_16x16x32_bf16 v[4:7], v[144:147], v[172:175], v[4:7]
	v_mfma_f32_16x16x32_bf16 v[0:3], v[152:155], v[172:175], v[0:3]
	v_mfma_f32_16x16x32_bf16 v[24:27], v[144:147], v[180:183], v[24:27]
	v_mfma_f32_16x16x32_bf16 v[16:19], v[152:155], v[180:183], v[16:19]
	v_mfma_f32_16x16x32_bf16 v[28:31], v[144:147], v[200:203], v[28:31]
	v_mfma_f32_16x16x32_bf16 v[20:23], v[152:155], v[200:203], v[20:23]
	v_mfma_f32_16x16x32_bf16 v[52:55], v[144:147], v[208:211], v[52:55]
	v_mfma_f32_16x16x32_bf16 v[48:51], v[152:155], v[208:211], v[48:51]
	v_mfma_f32_16x16x32_bf16 v[4:7], v[148:151], v[176:179], v[4:7]
	v_mfma_f32_16x16x32_bf16 v[0:3], v[156:159], v[176:179], v[0:3]
	v_mfma_f32_16x16x32_bf16 v[24:27], v[148:151], v[184:187], v[24:27]
	v_mfma_f32_16x16x32_bf16 v[16:19], v[156:159], v[184:187], v[16:19]
	s_barrier
	s_setprio 2
	v_mfma_f32_16x16x32_bf16 v[28:31], v[148:151], v[204:207], v[28:31]
	v_mfma_f32_16x16x32_bf16 v[20:23], v[156:159], v[204:207], v[20:23]
	v_mfma_f32_16x16x32_bf16 v[52:55], v[148:151], v[212:215], v[52:55]
	v_mfma_f32_16x16x32_bf16 v[48:51], v[156:159], v[212:215], v[48:51]
	s_setprio 0
	s_add_i32 s0, s17, s25
	v_lshl_add_u64 v[188:189], s[4:5], 0, v[162:163]
	s_mov_b32 m0, s0
	ds_read_b128 v[172:175], v196 offset:16384
	ds_read_b128 v[176:179], v196 offset:17408
	ds_read_b128 v[180:183], v196 offset:18432
	ds_read_b128 v[184:187], v196 offset:19456
	ds_read_b128 v[200:203], v196 offset:20480
	ds_read_b128 v[204:207], v196 offset:21504
	ds_read_b128 v[208:211], v196 offset:22528
	ds_read_b128 v[212:215], v196 offset:23552
	global_load_lds_dwordx4 v[188:189], off
	s_add_i32 m0, s0, 0x2000
	s_add_u32 s0, s4, 0x2b0000
	v_lshl_add_u64 v[216:217], s[4:5], 0, v[166:167]
	s_addc_u32 s1, s5, 0
	s_add_i32 s40, s55, s25
	global_load_lds_dwordx4 v[216:217], off
	v_lshl_add_u64 v[220:221], s[0:1], 0, v[162:163]
	s_mov_b32 m0, s40
	v_lshl_add_u64 v[222:223], s[36:37], 0, v[164:165]
	global_load_lds_dwordx4 v[220:221], off
	v_lshl_add_u64 v[220:221], s[0:1], 0, v[166:167]
	s_add_i32 m0, s40, 0x2000
	s_nop 0
	global_load_lds_dwordx4 v[220:221], off
	v_lshl_add_u64 v[220:221], s[36:37], 0, v[160:161]
	s_mov_b32 m0, s27
	s_nop 0
	global_load_lds_dwordx4 v[220:221], off
	s_mov_b32 m0, s33
	s_nop 0
	global_load_lds_dwordx4 v[222:223], off
	s_waitcnt vmcnt(8)
	s_waitcnt lgkmcnt(0)
	s_barrier
	s_setprio 1
	s_waitcnt lgkmcnt(0)
	v_mfma_f32_16x16x32_bf16 v[76:79], v[128:131], v[172:175], v[76:79]
	v_mfma_f32_16x16x32_bf16 v[72:75], v[136:139], v[172:175], v[72:75]
	v_mfma_f32_16x16x32_bf16 v[92:95], v[128:131], v[180:183], v[92:95]
	v_mfma_f32_16x16x32_bf16 v[88:91], v[136:139], v[180:183], v[88:91]
	v_mfma_f32_16x16x32_bf16 v[108:111], v[128:131], v[200:203], v[108:111]
	v_mfma_f32_16x16x32_bf16 v[104:107], v[136:139], v[200:203], v[104:107]
	v_mfma_f32_16x16x32_bf16 v[124:127], v[128:131], v[208:211], v[124:127]
	v_mfma_f32_16x16x32_bf16 v[120:123], v[136:139], v[208:211], v[120:123]
	v_mfma_f32_16x16x32_bf16 v[76:79], v[132:135], v[176:179], v[76:79]
	v_mfma_f32_16x16x32_bf16 v[72:75], v[140:143], v[176:179], v[72:75]
	v_mfma_f32_16x16x32_bf16 v[92:95], v[132:135], v[184:187], v[92:95]
	v_mfma_f32_16x16x32_bf16 v[88:91], v[140:143], v[184:187], v[88:91]
	v_mfma_f32_16x16x32_bf16 v[108:111], v[132:135], v[204:207], v[108:111]
	v_mfma_f32_16x16x32_bf16 v[104:107], v[140:143], v[204:207], v[104:107]
	v_mfma_f32_16x16x32_bf16 v[124:127], v[132:135], v[212:215], v[124:127]
	v_mfma_f32_16x16x32_bf16 v[120:123], v[140:143], v[212:215], v[120:123]
	s_setprio 0
	s_setprio 1
	v_mfma_f32_16x16x32_bf16 v[68:71], v[144:147], v[172:175], v[68:71]
	v_mfma_f32_16x16x32_bf16 v[60:63], v[152:155], v[172:175], v[60:63]
	v_mfma_f32_16x16x32_bf16 v[84:87], v[144:147], v[180:183], v[84:87]
	v_mfma_f32_16x16x32_bf16 v[80:83], v[152:155], v[180:183], v[80:83]
	v_mfma_f32_16x16x32_bf16 v[100:103], v[144:147], v[200:203], v[100:103]
	v_mfma_f32_16x16x32_bf16 v[96:99], v[152:155], v[200:203], v[96:99]
	v_mfma_f32_16x16x32_bf16 v[116:119], v[144:147], v[208:211], v[116:119]
	v_mfma_f32_16x16x32_bf16 v[112:115], v[152:155], v[208:211], v[112:115]
	v_mfma_f32_16x16x32_bf16 v[68:71], v[148:151], v[176:179], v[68:71]
	v_mfma_f32_16x16x32_bf16 v[60:63], v[156:159], v[176:179], v[60:63]
	v_mfma_f32_16x16x32_bf16 v[84:87], v[148:151], v[184:187], v[84:87]
	v_mfma_f32_16x16x32_bf16 v[80:83], v[156:159], v[184:187], v[80:83]
	s_barrier
	s_setprio 2
	v_mfma_f32_16x16x32_bf16 v[100:103], v[148:151], v[204:207], v[100:103]
	v_mfma_f32_16x16x32_bf16 v[96:99], v[156:159], v[204:207], v[96:99]
	v_mfma_f32_16x16x32_bf16 v[116:119], v[148:151], v[212:215], v[116:119]
	v_mfma_f32_16x16x32_bf16 v[112:115], v[156:159], v[212:215], v[112:115]
	s_setprio 0
	v_add_u32_e32 v140, s56, v193
	v_add_u32_e32 v156, s57, v193
	ds_read_b128 v[128:131], v140
	ds_read_b128 v[132:135], v140 offset:1024
	ds_read_b128 v[136:139], v140 offset:2048
	ds_read_b128 v[140:143], v140 offset:3072
	ds_read_b128 v[144:147], v156
	ds_read_b128 v[148:151], v156 offset:1024
	ds_read_b128 v[152:155], v156 offset:2048
	ds_read_b128 v[156:159], v156 offset:3072
	s_add_u32 s0, s36, 0x2b0000
	s_addc_u32 s1, s37, 0
	s_mov_b32 m0, s46
	v_lshl_add_u64 v[224:225], s[0:1], 0, v[160:161]
	ds_read_b128 v[172:175], v196 offset:32768
	ds_read_b128 v[176:179], v196 offset:33792
	ds_read_b128 v[180:183], v196 offset:34816
	ds_read_b128 v[184:187], v196 offset:35840
	ds_read_b128 v[200:203], v196 offset:36864
	ds_read_b128 v[204:207], v196 offset:37888
	ds_read_b128 v[208:211], v196 offset:38912
	ds_read_b128 v[212:215], v196 offset:39936
	global_load_lds_dwordx4 v[224:225], off
	v_lshl_add_u64 v[224:225], s[0:1], 0, v[164:165]
	s_mov_b32 m0, s47
	s_nop 0
	global_load_lds_dwordx4 v[224:225], off
	s_waitcnt vmcnt(8)
	s_waitcnt lgkmcnt(0)
	s_barrier
	s_setprio 1
	s_waitcnt lgkmcnt(0)
	v_mfma_f32_16x16x32_bf16 v[12:15], v[128:131], v[172:175], v[12:15]
	v_mfma_f32_16x16x32_bf16 v[8:11], v[136:139], v[172:175], v[8:11]
	v_mfma_f32_16x16x32_bf16 v[36:39], v[128:131], v[180:183], v[36:39]
	v_mfma_f32_16x16x32_bf16 v[32:35], v[136:139], v[180:183], v[32:35]
	v_mfma_f32_16x16x32_bf16 v[44:47], v[128:131], v[200:203], v[44:47]
	v_mfma_f32_16x16x32_bf16 v[40:43], v[136:139], v[200:203], v[40:43]
	v_mfma_f32_16x16x32_bf16 v[64:67], v[128:131], v[208:211], v[64:67]
	v_mfma_f32_16x16x32_bf16 v[56:59], v[136:139], v[208:211], v[56:59]
	v_mfma_f32_16x16x32_bf16 v[12:15], v[132:135], v[176:179], v[12:15]
	v_mfma_f32_16x16x32_bf16 v[8:11], v[140:143], v[176:179], v[8:11]
	v_mfma_f32_16x16x32_bf16 v[36:39], v[132:135], v[184:187], v[36:39]
	v_mfma_f32_16x16x32_bf16 v[32:35], v[140:143], v[184:187], v[32:35]
	v_mfma_f32_16x16x32_bf16 v[44:47], v[132:135], v[204:207], v[44:47]
	v_mfma_f32_16x16x32_bf16 v[40:43], v[140:143], v[204:207], v[40:43]
	v_mfma_f32_16x16x32_bf16 v[64:67], v[132:135], v[212:215], v[64:67]
	v_mfma_f32_16x16x32_bf16 v[56:59], v[140:143], v[212:215], v[56:59]
	s_setprio 0
	s_setprio 1
	v_mfma_f32_16x16x32_bf16 v[4:7], v[144:147], v[172:175], v[4:7]
	v_mfma_f32_16x16x32_bf16 v[0:3], v[152:155], v[172:175], v[0:3]
	v_mfma_f32_16x16x32_bf16 v[24:27], v[144:147], v[180:183], v[24:27]
	v_mfma_f32_16x16x32_bf16 v[16:19], v[152:155], v[180:183], v[16:19]
	v_mfma_f32_16x16x32_bf16 v[28:31], v[144:147], v[200:203], v[28:31]
	v_mfma_f32_16x16x32_bf16 v[20:23], v[152:155], v[200:203], v[20:23]
	v_mfma_f32_16x16x32_bf16 v[52:55], v[144:147], v[208:211], v[52:55]
	v_mfma_f32_16x16x32_bf16 v[48:51], v[152:155], v[208:211], v[48:51]
	v_mfma_f32_16x16x32_bf16 v[4:7], v[148:151], v[176:179], v[4:7]
	v_mfma_f32_16x16x32_bf16 v[0:3], v[156:159], v[176:179], v[0:3]
	v_mfma_f32_16x16x32_bf16 v[24:27], v[148:151], v[184:187], v[24:27]
	v_mfma_f32_16x16x32_bf16 v[16:19], v[156:159], v[184:187], v[16:19]
	s_barrier
	s_setprio 2
	v_mfma_f32_16x16x32_bf16 v[28:31], v[148:151], v[204:207], v[28:31]
	v_mfma_f32_16x16x32_bf16 v[20:23], v[156:159], v[204:207], v[20:23]
	v_mfma_f32_16x16x32_bf16 v[52:55], v[148:151], v[212:215], v[52:55]
	v_mfma_f32_16x16x32_bf16 v[48:51], v[156:159], v[212:215], v[48:51]
	s_setprio 0
	s_add_i32 s0, s56, s25
	v_lshl_add_u64 v[188:189], v[188:189], 0, s[18:19]
	s_mov_b32 m0, s0
	ds_read_b128 v[172:175], v196 offset:49152
	ds_read_b128 v[176:179], v196 offset:50176
	ds_read_b128 v[180:183], v196 offset:51200
	ds_read_b128 v[184:187], v196 offset:52224
	ds_read_b128 v[200:203], v196 offset:53248
	ds_read_b128 v[204:207], v196 offset:54272
	ds_read_b128 v[208:211], v196 offset:55296
	ds_read_b128 v[212:215], v196 offset:56320
	global_load_lds_dwordx4 v[188:189], off
	s_add_i32 m0, s0, 0x2000
	s_add_u32 s0, s4, 0x2b0080
	v_lshl_add_u64 v[188:189], v[216:217], 0, s[18:19]
	s_addc_u32 s1, s5, 0
	s_add_i32 s4, s57, s25
	global_load_lds_dwordx4 v[188:189], off
	v_lshl_add_u64 v[188:189], s[0:1], 0, v[162:163]
	s_mov_b32 m0, s4
	s_nop 0
	global_load_lds_dwordx4 v[188:189], off
	v_lshl_add_u64 v[188:189], s[0:1], 0, v[166:167]
	s_add_i32 m0, s4, 0x2000
	s_nop 0
	global_load_lds_dwordx4 v[188:189], off
	v_lshl_add_u64 v[188:189], v[220:221], 0, s[18:19]
	s_mov_b32 m0, s52
	s_nop 0
	global_load_lds_dwordx4 v[188:189], off
	v_lshl_add_u64 v[188:189], v[222:223], 0, s[18:19]
	s_mov_b32 m0, s53
	s_nop 0
	global_load_lds_dwordx4 v[188:189], off
	s_waitcnt vmcnt(8)
	s_waitcnt lgkmcnt(0)
	s_barrier
	s_setprio 1
	s_waitcnt lgkmcnt(0)
	v_mfma_f32_16x16x32_bf16 v[76:79], v[128:131], v[172:175], v[76:79]
	v_mfma_f32_16x16x32_bf16 v[72:75], v[136:139], v[172:175], v[72:75]
	v_mfma_f32_16x16x32_bf16 v[92:95], v[128:131], v[180:183], v[92:95]
	v_mfma_f32_16x16x32_bf16 v[88:91], v[136:139], v[180:183], v[88:91]
	v_mfma_f32_16x16x32_bf16 v[108:111], v[128:131], v[200:203], v[108:111]
	v_mfma_f32_16x16x32_bf16 v[104:107], v[136:139], v[200:203], v[104:107]
	v_mfma_f32_16x16x32_bf16 v[124:127], v[128:131], v[208:211], v[124:127]
	v_mfma_f32_16x16x32_bf16 v[120:123], v[136:139], v[208:211], v[120:123]
	v_mfma_f32_16x16x32_bf16 v[76:79], v[132:135], v[176:179], v[76:79]
	v_mfma_f32_16x16x32_bf16 v[72:75], v[140:143], v[176:179], v[72:75]
	v_mfma_f32_16x16x32_bf16 v[92:95], v[132:135], v[184:187], v[92:95]
	v_mfma_f32_16x16x32_bf16 v[88:91], v[140:143], v[184:187], v[88:91]
	v_mfma_f32_16x16x32_bf16 v[108:111], v[132:135], v[204:207], v[108:111]
	v_mfma_f32_16x16x32_bf16 v[104:107], v[140:143], v[204:207], v[104:107]
	v_mfma_f32_16x16x32_bf16 v[124:127], v[132:135], v[212:215], v[124:127]
	v_mfma_f32_16x16x32_bf16 v[120:123], v[140:143], v[212:215], v[120:123]
	s_setprio 0
	s_setprio 1
	v_mfma_f32_16x16x32_bf16 v[68:71], v[144:147], v[172:175], v[68:71]
	v_mfma_f32_16x16x32_bf16 v[60:63], v[152:155], v[172:175], v[60:63]
	v_mfma_f32_16x16x32_bf16 v[84:87], v[144:147], v[180:183], v[84:87]
	v_mfma_f32_16x16x32_bf16 v[80:83], v[152:155], v[180:183], v[80:83]
	v_mfma_f32_16x16x32_bf16 v[100:103], v[144:147], v[200:203], v[100:103]
	v_mfma_f32_16x16x32_bf16 v[96:99], v[152:155], v[200:203], v[96:99]
	v_mfma_f32_16x16x32_bf16 v[116:119], v[144:147], v[208:211], v[116:119]
	v_mfma_f32_16x16x32_bf16 v[112:115], v[152:155], v[208:211], v[112:115]
	v_mfma_f32_16x16x32_bf16 v[68:71], v[148:151], v[176:179], v[68:71]
	v_mfma_f32_16x16x32_bf16 v[60:63], v[156:159], v[176:179], v[60:63]
	v_mfma_f32_16x16x32_bf16 v[84:87], v[148:151], v[184:187], v[84:87]
	v_mfma_f32_16x16x32_bf16 v[80:83], v[156:159], v[184:187], v[80:83]
	s_barrier
	s_setprio 2
	v_mfma_f32_16x16x32_bf16 v[100:103], v[148:151], v[204:207], v[100:103]
	v_mfma_f32_16x16x32_bf16 v[96:99], v[156:159], v[204:207], v[96:99]
	v_mfma_f32_16x16x32_bf16 v[116:119], v[148:151], v[212:215], v[116:119]
	v_mfma_f32_16x16x32_bf16 v[112:115], v[156:159], v[212:215], v[112:115]
	s_setprio 0
	s_add_i32 s39, s39, 2
	s_add_u32 s29, s29, 0x100
	s_addc_u32 s38, s38, 0
	s_cmpk_gt_u32 s39, 0xa9
	s_mov_b64 s[0:1], s[2:3]
	s_cbranch_scc0 .LBB0_1058
	s_and_b64 vcc, exec, s[20:21]
	s_cbranch_vccz .LBB0_1061
	s_barrier
